# GEMM loops: deleted the back-to-back s_setprio 0 / s_setprio 1 pair in the middle of each 32-MFMA segment (48 sites)
# speedup vs baseline: 1.0022x; 1.0022x over previous
.LBB0_153:
	ds_read_b128 v[146:149], v153
	ds_read_b128 v[156:159], v153 offset:1024
	ds_read_b128 v[160:163], v153 offset:2048
	ds_read_b128 v[164:167], v153 offset:3072
	ds_read_b128 v[168:171], v154
	ds_read_b128 v[172:175], v154 offset:1024
	ds_read_b128 v[176:179], v154 offset:2048
	ds_read_b128 v[180:183], v154 offset:3072
	s_add_u32 s42, s40, 0xfff80080
	s_addc_u32 s43, s41, -1
	s_cmp_eq_u32 s60, 28
	s_cselect_b32 s45, s2, s43
	s_cselect_b32 s44, s3, s42
	s_cselect_b32 s43, s29, s59
	s_cselect_b32 s42, s31, s58
	v_lshl_add_u64 v[218:219], s[40:41], 0, v[138:139]
	s_add_i32 m0, s39, 0xc000
	ds_read_b128 v[184:187], v155
	ds_read_b128 v[188:191], v155 offset:1024
	ds_read_b128 v[192:195], v155 offset:2048
	ds_read_b128 v[196:199], v155 offset:3072
	ds_read_b128 v[200:203], v155 offset:4096
	ds_read_b128 v[204:207], v155 offset:5120
	ds_read_b128 v[210:213], v155 offset:6144
	ds_read_b128 v[214:217], v155 offset:7168
	global_load_lds_dwordx4 v[218:219], off
	v_lshl_add_u64 v[218:219], s[40:41], 0, v[140:141]
	s_add_i32 m0, s39, 0xe000
	s_nop 0
	global_load_lds_dwordx4 v[218:219], off
	s_waitcnt vmcnt(8)
	s_waitcnt lgkmcnt(0)
	s_barrier
	s_setprio 1
	s_waitcnt lgkmcnt(0)
	v_mfma_f32_16x16x32_bf16 v[124:127], v[146:149], v[184:187], v[124:127]
	v_mfma_f32_16x16x32_bf16 v[120:123], v[160:163], v[184:187], v[120:123]
	v_mfma_f32_16x16x32_bf16 v[116:119], v[146:149], v[192:195], v[116:119]
	v_mfma_f32_16x16x32_bf16 v[108:111], v[160:163], v[192:195], v[108:111]
	v_mfma_f32_16x16x32_bf16 v[100:103], v[146:149], v[200:203], v[100:103]
	v_mfma_f32_16x16x32_bf16 v[92:95], v[160:163], v[200:203], v[92:95]
	v_mfma_f32_16x16x32_bf16 v[84:87], v[146:149], v[210:213], v[84:87]
	v_mfma_f32_16x16x32_bf16 v[76:79], v[160:163], v[210:213], v[76:79]
	v_mfma_f32_16x16x32_bf16 v[124:127], v[156:159], v[188:191], v[124:127]
	v_mfma_f32_16x16x32_bf16 v[120:123], v[164:167], v[188:191], v[120:123]
	v_mfma_f32_16x16x32_bf16 v[116:119], v[156:159], v[196:199], v[116:119]
	v_mfma_f32_16x16x32_bf16 v[108:111], v[164:167], v[196:199], v[108:111]
	v_mfma_f32_16x16x32_bf16 v[100:103], v[156:159], v[204:207], v[100:103]
	v_mfma_f32_16x16x32_bf16 v[92:95], v[164:167], v[204:207], v[92:95]
	v_mfma_f32_16x16x32_bf16 v[84:87], v[156:159], v[214:217], v[84:87]
	v_mfma_f32_16x16x32_bf16 v[76:79], v[164:167], v[214:217], v[76:79]
	v_mfma_f32_16x16x32_bf16 v[112:115], v[168:171], v[184:187], v[112:115]
	v_mfma_f32_16x16x32_bf16 v[104:107], v[176:179], v[184:187], v[104:107]
	v_mfma_f32_16x16x32_bf16 v[96:99], v[168:171], v[192:195], v[96:99]
	v_mfma_f32_16x16x32_bf16 v[88:91], v[176:179], v[192:195], v[88:91]
	v_mfma_f32_16x16x32_bf16 v[80:83], v[168:171], v[200:203], v[80:83]
	v_mfma_f32_16x16x32_bf16 v[72:75], v[176:179], v[200:203], v[72:75]
	v_mfma_f32_16x16x32_bf16 v[68:71], v[168:171], v[210:213], v[68:71]
	v_mfma_f32_16x16x32_bf16 v[64:67], v[176:179], v[210:213], v[64:67]
	v_mfma_f32_16x16x32_bf16 v[112:115], v[172:175], v[188:191], v[112:115]
	v_mfma_f32_16x16x32_bf16 v[104:107], v[180:183], v[188:191], v[104:107]
	v_mfma_f32_16x16x32_bf16 v[96:99], v[172:175], v[196:199], v[96:99]
	v_mfma_f32_16x16x32_bf16 v[88:91], v[180:183], v[196:199], v[88:91]
	v_mfma_f32_16x16x32_bf16 v[80:83], v[172:175], v[204:207], v[80:83]
	v_mfma_f32_16x16x32_bf16 v[72:75], v[180:183], v[204:207], v[72:75]
	v_mfma_f32_16x16x32_bf16 v[68:71], v[172:175], v[214:217], v[68:71]
	v_mfma_f32_16x16x32_bf16 v[64:67], v[180:183], v[214:217], v[64:67]
	s_setprio 0
	s_barrier
	s_add_i32 s61, s54, s93
	v_lshl_add_u64 v[218:219], s[42:43], 0, v[132:133]
	s_mov_b32 m0, s61
	ds_read_b128 v[184:187], v155 offset:16384
	ds_read_b128 v[188:191], v155 offset:17408
	ds_read_b128 v[192:195], v155 offset:18432
	ds_read_b128 v[196:199], v155 offset:19456
	ds_read_b128 v[200:203], v155 offset:20480
	ds_read_b128 v[204:207], v155 offset:21504
	ds_read_b128 v[210:213], v155 offset:22528
	ds_read_b128 v[214:217], v155 offset:23552
	global_load_lds_dwordx4 v[218:219], off
	s_add_i32 m0, s61, 0x2000
	s_add_u32 s62, s42, 0x80000
	v_lshl_add_u64 v[220:221], s[42:43], 0, v[128:129]
	s_addc_u32 s63, s43, 0
	s_add_i32 s61, s55, s93
	global_load_lds_dwordx4 v[220:221], off
	v_lshl_add_u64 v[222:223], s[62:63], 0, v[132:133]
	s_mov_b32 m0, s61
	v_lshl_add_u64 v[224:225], s[44:45], 0, v[130:131]
	global_load_lds_dwordx4 v[222:223], off
	v_lshl_add_u64 v[222:223], s[62:63], 0, v[128:129]
	s_add_i32 m0, s61, 0x2000
	s_nop 0
	global_load_lds_dwordx4 v[222:223], off
	v_lshl_add_u64 v[222:223], s[44:45], 0, v[134:135]
	s_mov_b32 m0, s39
	s_nop 0
	global_load_lds_dwordx4 v[222:223], off
	s_mov_b32 m0, s47
	s_nop 0
	global_load_lds_dwordx4 v[224:225], off
	s_waitcnt vmcnt(8)
	s_waitcnt lgkmcnt(0)
	s_barrier
	s_setprio 1
	s_waitcnt lgkmcnt(0)
	v_mfma_f32_16x16x32_bf16 v[60:63], v[146:149], v[184:187], v[60:63]
	v_mfma_f32_16x16x32_bf16 v[56:59], v[160:163], v[184:187], v[56:59]
	v_mfma_f32_16x16x32_bf16 v[52:55], v[146:149], v[192:195], v[52:55]
	v_mfma_f32_16x16x32_bf16 v[44:47], v[160:163], v[192:195], v[44:47]
	v_mfma_f32_16x16x32_bf16 v[36:39], v[146:149], v[200:203], v[36:39]
	v_mfma_f32_16x16x32_bf16 v[28:31], v[160:163], v[200:203], v[28:31]
	v_mfma_f32_16x16x32_bf16 v[20:23], v[146:149], v[210:213], v[20:23]
	v_mfma_f32_16x16x32_bf16 v[12:15], v[160:163], v[210:213], v[12:15]
	v_mfma_f32_16x16x32_bf16 v[60:63], v[156:159], v[188:191], v[60:63]
	v_mfma_f32_16x16x32_bf16 v[56:59], v[164:167], v[188:191], v[56:59]
	v_mfma_f32_16x16x32_bf16 v[52:55], v[156:159], v[196:199], v[52:55]
	v_mfma_f32_16x16x32_bf16 v[44:47], v[164:167], v[196:199], v[44:47]
	v_mfma_f32_16x16x32_bf16 v[36:39], v[156:159], v[204:207], v[36:39]
	v_mfma_f32_16x16x32_bf16 v[28:31], v[164:167], v[204:207], v[28:31]
	v_mfma_f32_16x16x32_bf16 v[20:23], v[156:159], v[214:217], v[20:23]
	v_mfma_f32_16x16x32_bf16 v[12:15], v[164:167], v[214:217], v[12:15]
	v_mfma_f32_16x16x32_bf16 v[48:51], v[168:171], v[184:187], v[48:51]
	v_mfma_f32_16x16x32_bf16 v[40:43], v[176:179], v[184:187], v[40:43]
	v_mfma_f32_16x16x32_bf16 v[32:35], v[168:171], v[192:195], v[32:35]
	v_mfma_f32_16x16x32_bf16 v[24:27], v[176:179], v[192:195], v[24:27]
	v_mfma_f32_16x16x32_bf16 v[16:19], v[168:171], v[200:203], v[16:19]
	v_mfma_f32_16x16x32_bf16 v[8:11], v[176:179], v[200:203], v[8:11]
	v_mfma_f32_16x16x32_bf16 v[4:7], v[168:171], v[210:213], v[4:7]
	v_mfma_f32_16x16x32_bf16 v[0:3], v[176:179], v[210:213], v[0:3]
	v_mfma_f32_16x16x32_bf16 v[48:51], v[172:175], v[188:191], v[48:51]
	v_mfma_f32_16x16x32_bf16 v[40:43], v[180:183], v[188:191], v[40:43]
	v_mfma_f32_16x16x32_bf16 v[32:35], v[172:175], v[196:199], v[32:35]
	v_mfma_f32_16x16x32_bf16 v[24:27], v[180:183], v[196:199], v[24:27]
	v_mfma_f32_16x16x32_bf16 v[16:19], v[172:175], v[204:207], v[16:19]
	v_mfma_f32_16x16x32_bf16 v[8:11], v[180:183], v[204:207], v[8:11]
	v_mfma_f32_16x16x32_bf16 v[4:7], v[172:175], v[214:217], v[4:7]
	v_mfma_f32_16x16x32_bf16 v[0:3], v[180:183], v[214:217], v[0:3]
	s_setprio 0
	s_barrier
	s_add_i32 s61, 0, 0x18000
	s_add_i32 s62, 0, 0x1c000
	v_add_u32_e32 v164, s61, v151
	v_add_u32_e32 v180, s62, v151
	ds_read_b128 v[146:149], v164
	ds_read_b128 v[156:159], v164 offset:1024
	ds_read_b128 v[160:163], v164 offset:2048
	ds_read_b128 v[164:167], v164 offset:3072
	ds_read_b128 v[168:171], v180
	ds_read_b128 v[172:175], v180 offset:1024
	ds_read_b128 v[176:179], v180 offset:2048
	ds_read_b128 v[180:183], v180 offset:3072
	s_add_u32 s44, s44, 0x80000
	s_addc_u32 s45, s45, 0
	s_mov_b32 m0, s48
	v_lshl_add_u64 v[226:227], s[44:45], 0, v[134:135]
	ds_read_b128 v[184:187], v155 offset:32768
	ds_read_b128 v[188:191], v155 offset:33792
	ds_read_b128 v[192:195], v155 offset:34816
	ds_read_b128 v[196:199], v155 offset:35840
	ds_read_b128 v[200:203], v155 offset:36864
	ds_read_b128 v[204:207], v155 offset:37888
	ds_read_b128 v[210:213], v155 offset:38912
	ds_read_b128 v[214:217], v155 offset:39936
	global_load_lds_dwordx4 v[226:227], off
	v_lshl_add_u64 v[226:227], s[44:45], 0, v[130:131]
	s_mov_b32 m0, s49
	s_nop 0
	global_load_lds_dwordx4 v[226:227], off
	s_waitcnt vmcnt(8)
	s_waitcnt lgkmcnt(0)
	s_barrier
	s_setprio 1
	s_waitcnt lgkmcnt(0)
	v_mfma_f32_16x16x32_bf16 v[124:127], v[146:149], v[184:187], v[124:127]
	v_mfma_f32_16x16x32_bf16 v[120:123], v[160:163], v[184:187], v[120:123]
	v_mfma_f32_16x16x32_bf16 v[116:119], v[146:149], v[192:195], v[116:119]
	v_mfma_f32_16x16x32_bf16 v[108:111], v[160:163], v[192:195], v[108:111]
	v_mfma_f32_16x16x32_bf16 v[100:103], v[146:149], v[200:203], v[100:103]
	v_mfma_f32_16x16x32_bf16 v[92:95], v[160:163], v[200:203], v[92:95]
	v_mfma_f32_16x16x32_bf16 v[84:87], v[146:149], v[210:213], v[84:87]
	v_mfma_f32_16x16x32_bf16 v[76:79], v[160:163], v[210:213], v[76:79]
	v_mfma_f32_16x16x32_bf16 v[124:127], v[156:159], v[188:191], v[124:127]
	v_mfma_f32_16x16x32_bf16 v[120:123], v[164:167], v[188:191], v[120:123]
	v_mfma_f32_16x16x32_bf16 v[116:119], v[156:159], v[196:199], v[116:119]
	v_mfma_f32_16x16x32_bf16 v[108:111], v[164:167], v[196:199], v[108:111]
	v_mfma_f32_16x16x32_bf16 v[100:103], v[156:159], v[204:207], v[100:103]
	v_mfma_f32_16x16x32_bf16 v[92:95], v[164:167], v[204:207], v[92:95]
	v_mfma_f32_16x16x32_bf16 v[84:87], v[156:159], v[214:217], v[84:87]
	v_mfma_f32_16x16x32_bf16 v[76:79], v[164:167], v[214:217], v[76:79]
	v_mfma_f32_16x16x32_bf16 v[112:115], v[168:171], v[184:187], v[112:115]
	v_mfma_f32_16x16x32_bf16 v[104:107], v[176:179], v[184:187], v[104:107]
	v_mfma_f32_16x16x32_bf16 v[96:99], v[168:171], v[192:195], v[96:99]
	v_mfma_f32_16x16x32_bf16 v[88:91], v[176:179], v[192:195], v[88:91]
	v_mfma_f32_16x16x32_bf16 v[80:83], v[168:171], v[200:203], v[80:83]
	v_mfma_f32_16x16x32_bf16 v[72:75], v[176:179], v[200:203], v[72:75]
	v_mfma_f32_16x16x32_bf16 v[68:71], v[168:171], v[210:213], v[68:71]
	v_mfma_f32_16x16x32_bf16 v[64:67], v[176:179], v[210:213], v[64:67]
	v_mfma_f32_16x16x32_bf16 v[112:115], v[172:175], v[188:191], v[112:115]
	v_mfma_f32_16x16x32_bf16 v[104:107], v[180:183], v[188:191], v[104:107]
	v_mfma_f32_16x16x32_bf16 v[96:99], v[172:175], v[196:199], v[96:99]
	v_mfma_f32_16x16x32_bf16 v[88:91], v[180:183], v[196:199], v[88:91]
	v_mfma_f32_16x16x32_bf16 v[80:83], v[172:175], v[204:207], v[80:83]
	v_mfma_f32_16x16x32_bf16 v[72:75], v[180:183], v[204:207], v[72:75]
	v_mfma_f32_16x16x32_bf16 v[68:71], v[172:175], v[214:217], v[68:71]
	v_mfma_f32_16x16x32_bf16 v[64:67], v[180:183], v[214:217], v[64:67]
	s_setprio 0
	s_barrier
	s_add_i32 s44, s61, s93
	v_lshl_add_u64 v[218:219], v[218:219], 0, s[6:7]
	s_mov_b32 m0, s44
	ds_read_b128 v[184:187], v155 offset:49152
	ds_read_b128 v[188:191], v155 offset:50176
	ds_read_b128 v[192:195], v155 offset:51200
	ds_read_b128 v[196:199], v155 offset:52224
	ds_read_b128 v[200:203], v155 offset:53248
	ds_read_b128 v[204:207], v155 offset:54272
	ds_read_b128 v[210:213], v155 offset:55296
	ds_read_b128 v[214:217], v155 offset:56320
	global_load_lds_dwordx4 v[218:219], off
	s_add_i32 m0, s44, 0x2000
	s_add_u32 s42, s42, 0x80080
	v_lshl_add_u64 v[218:219], v[220:221], 0, s[6:7]
	s_addc_u32 s43, s43, 0
	s_add_i32 s44, s62, s93
	global_load_lds_dwordx4 v[218:219], off
	v_lshl_add_u64 v[218:219], s[42:43], 0, v[132:133]
	s_mov_b32 m0, s44
	s_nop 0
	global_load_lds_dwordx4 v[218:219], off
	v_lshl_add_u64 v[218:219], s[42:43], 0, v[128:129]
	s_add_i32 m0, s44, 0x2000
	s_nop 0
	global_load_lds_dwordx4 v[218:219], off
	v_lshl_add_u64 v[218:219], v[222:223], 0, s[6:7]
	s_mov_b32 m0, s51
	s_nop 0
	global_load_lds_dwordx4 v[218:219], off
	v_lshl_add_u64 v[218:219], v[224:225], 0, s[6:7]
	s_mov_b32 m0, s52
	s_nop 0
	global_load_lds_dwordx4 v[218:219], off
	s_waitcnt vmcnt(8)
	s_waitcnt lgkmcnt(0)
	s_barrier
	s_setprio 1
	s_waitcnt lgkmcnt(0)
	v_mfma_f32_16x16x32_bf16 v[60:63], v[146:149], v[184:187], v[60:63]
	v_mfma_f32_16x16x32_bf16 v[56:59], v[160:163], v[184:187], v[56:59]
	v_mfma_f32_16x16x32_bf16 v[52:55], v[146:149], v[192:195], v[52:55]
	v_mfma_f32_16x16x32_bf16 v[44:47], v[160:163], v[192:195], v[44:47]
	v_mfma_f32_16x16x32_bf16 v[36:39], v[146:149], v[200:203], v[36:39]
	v_mfma_f32_16x16x32_bf16 v[28:31], v[160:163], v[200:203], v[28:31]
	v_mfma_f32_16x16x32_bf16 v[20:23], v[146:149], v[210:213], v[20:23]
	v_mfma_f32_16x16x32_bf16 v[12:15], v[160:163], v[210:213], v[12:15]
	v_mfma_f32_16x16x32_bf16 v[60:63], v[156:159], v[188:191], v[60:63]
	v_mfma_f32_16x16x32_bf16 v[56:59], v[164:167], v[188:191], v[56:59]
	v_mfma_f32_16x16x32_bf16 v[52:55], v[156:159], v[196:199], v[52:55]
	v_mfma_f32_16x16x32_bf16 v[44:47], v[164:167], v[196:199], v[44:47]
	v_mfma_f32_16x16x32_bf16 v[36:39], v[156:159], v[204:207], v[36:39]
	v_mfma_f32_16x16x32_bf16 v[28:31], v[164:167], v[204:207], v[28:31]
	v_mfma_f32_16x16x32_bf16 v[20:23], v[156:159], v[214:217], v[20:23]
	v_mfma_f32_16x16x32_bf16 v[12:15], v[164:167], v[214:217], v[12:15]
	v_mfma_f32_16x16x32_bf16 v[48:51], v[168:171], v[184:187], v[48:51]
	v_mfma_f32_16x16x32_bf16 v[40:43], v[176:179], v[184:187], v[40:43]
	v_mfma_f32_16x16x32_bf16 v[32:35], v[168:171], v[192:195], v[32:35]
	v_mfma_f32_16x16x32_bf16 v[24:27], v[176:179], v[192:195], v[24:27]
	v_mfma_f32_16x16x32_bf16 v[16:19], v[168:171], v[200:203], v[16:19]
	v_mfma_f32_16x16x32_bf16 v[8:11], v[176:179], v[200:203], v[8:11]
	v_mfma_f32_16x16x32_bf16 v[4:7], v[168:171], v[210:213], v[4:7]
	v_mfma_f32_16x16x32_bf16 v[0:3], v[176:179], v[210:213], v[0:3]
	v_mfma_f32_16x16x32_bf16 v[48:51], v[172:175], v[188:191], v[48:51]
	v_mfma_f32_16x16x32_bf16 v[40:43], v[180:183], v[188:191], v[40:43]
	v_mfma_f32_16x16x32_bf16 v[32:35], v[172:175], v[196:199], v[32:35]
	v_mfma_f32_16x16x32_bf16 v[24:27], v[180:183], v[196:199], v[24:27]
	v_mfma_f32_16x16x32_bf16 v[16:19], v[172:175], v[204:207], v[16:19]
	v_mfma_f32_16x16x32_bf16 v[8:11], v[180:183], v[204:207], v[8:11]
	v_mfma_f32_16x16x32_bf16 v[4:7], v[172:175], v[214:217], v[4:7]
	v_mfma_f32_16x16x32_bf16 v[0:3], v[180:183], v[214:217], v[0:3]
	s_setprio 0
	s_barrier
	s_add_i32 s60, s60, 2
	s_add_u32 s40, s40, 0x100
	s_addc_u32 s41, s41, 0
	s_add_u32 s58, s58, 0x100
	s_addc_u32 s59, s59, 0
	s_cmp_gt_u32 s60, 29
	s_cbranch_scc0 .LBB0_153
	s_and_b64 vcc, exec, s[14:15]
	s_cbranch_vccnz .LBB0_158
	s_cmp_gt_i32 s57, 37
	s_mov_b64 s[2:3], -1
	s_cbranch_scc1 .LBB0_159

.LBB0_376:
	ds_read_b128 v[32:35], v165
	ds_read_b128 v[36:39], v165 offset:1024
	ds_read_b128 v[48:51], v165 offset:2048
	ds_read_b128 v[52:55], v165 offset:3072
	ds_read_b128 v[156:159], v166
	ds_read_b128 v[168:171], v166 offset:1024
	ds_read_b128 v[172:175], v166 offset:2048
	ds_read_b128 v[176:179], v166 offset:3072
	s_add_u32 s46, s44, 0xfff80080
	s_addc_u32 s47, s45, -1
	s_cmp_eq_u32 s72, 60
	s_cselect_b32 s49, s2, s47
	s_cselect_b32 s48, s3, s46
	s_cselect_b32 s47, s33, s71
	s_cselect_b32 s46, s37, s39
	v_lshl_add_u64 v[160:161], s[44:45], 0, v[152:153]
	s_add_i32 m0, s61, 0xc000
	ds_read_b128 v[180:183], v167
	ds_read_b128 v[184:187], v167 offset:1024
	ds_read_b128 v[188:191], v167 offset:2048
	ds_read_b128 v[192:195], v167 offset:3072
	ds_read_b128 v[196:199], v167 offset:4096
	ds_read_b128 v[200:203], v167 offset:5120
	ds_read_b128 v[204:207], v167 offset:6144
	ds_read_b128 v[210:213], v167 offset:7168
	global_load_lds_dwordx4 v[160:161], off
	v_lshl_add_u64 v[160:161], s[44:45], 0, v[154:155]
	s_add_i32 m0, s61, 0xe000
	s_nop 0
	global_load_lds_dwordx4 v[160:161], off
	s_waitcnt vmcnt(8)
	s_waitcnt lgkmcnt(0)
	s_barrier
	s_setprio 1
	s_waitcnt lgkmcnt(0)
	v_mfma_f32_16x16x32_bf16 v[140:143], v[32:35], v[180:183], v[140:143]
	v_mfma_f32_16x16x32_bf16 v[136:139], v[48:51], v[180:183], v[136:139]
	v_mfma_f32_16x16x32_bf16 v[124:127], v[32:35], v[188:191], v[124:127]
	v_mfma_f32_16x16x32_bf16 v[120:123], v[48:51], v[188:191], v[120:123]
	v_mfma_f32_16x16x32_bf16 v[108:111], v[32:35], v[196:199], v[108:111]
	v_mfma_f32_16x16x32_bf16 v[104:107], v[48:51], v[196:199], v[104:107]
	v_mfma_f32_16x16x32_bf16 v[92:95], v[32:35], v[204:207], v[92:95]
	v_mfma_f32_16x16x32_bf16 v[88:91], v[48:51], v[204:207], v[88:91]
	v_mfma_f32_16x16x32_bf16 v[140:143], v[36:39], v[184:187], v[140:143]
	v_mfma_f32_16x16x32_bf16 v[136:139], v[52:55], v[184:187], v[136:139]
	v_mfma_f32_16x16x32_bf16 v[124:127], v[36:39], v[192:195], v[124:127]
	v_mfma_f32_16x16x32_bf16 v[120:123], v[52:55], v[192:195], v[120:123]
	v_mfma_f32_16x16x32_bf16 v[108:111], v[36:39], v[200:203], v[108:111]
	v_mfma_f32_16x16x32_bf16 v[104:107], v[52:55], v[200:203], v[104:107]
	v_mfma_f32_16x16x32_bf16 v[92:95], v[36:39], v[210:213], v[92:95]
	v_mfma_f32_16x16x32_bf16 v[88:91], v[52:55], v[210:213], v[88:91]
	v_mfma_f32_16x16x32_bf16 v[132:135], v[156:159], v[180:183], v[132:135]
	v_mfma_f32_16x16x32_bf16 v[128:131], v[172:175], v[180:183], v[128:131]
	v_mfma_f32_16x16x32_bf16 v[116:119], v[156:159], v[188:191], v[116:119]
	v_mfma_f32_16x16x32_bf16 v[112:115], v[172:175], v[188:191], v[112:115]
	v_mfma_f32_16x16x32_bf16 v[100:103], v[156:159], v[196:199], v[100:103]
	v_mfma_f32_16x16x32_bf16 v[96:99], v[172:175], v[196:199], v[96:99]
	v_mfma_f32_16x16x32_bf16 v[84:87], v[156:159], v[204:207], v[84:87]
	v_mfma_f32_16x16x32_bf16 v[80:83], v[172:175], v[204:207], v[80:83]
	v_mfma_f32_16x16x32_bf16 v[132:135], v[168:171], v[184:187], v[132:135]
	v_mfma_f32_16x16x32_bf16 v[128:131], v[176:179], v[184:187], v[128:131]
	v_mfma_f32_16x16x32_bf16 v[116:119], v[168:171], v[192:195], v[116:119]
	v_mfma_f32_16x16x32_bf16 v[112:115], v[176:179], v[192:195], v[112:115]
	v_mfma_f32_16x16x32_bf16 v[100:103], v[168:171], v[200:203], v[100:103]
	v_mfma_f32_16x16x32_bf16 v[96:99], v[176:179], v[200:203], v[96:99]
	v_mfma_f32_16x16x32_bf16 v[84:87], v[168:171], v[210:213], v[84:87]
	v_mfma_f32_16x16x32_bf16 v[80:83], v[176:179], v[210:213], v[80:83]
	s_setprio 0
	s_barrier
	s_add_i32 s73, s68, s93
	v_lshl_add_u64 v[160:161], s[46:47], 0, v[146:147]
	s_mov_b32 m0, s73
	ds_read_b128 v[180:183], v167 offset:16384
	ds_read_b128 v[184:187], v167 offset:17408
	ds_read_b128 v[188:191], v167 offset:18432
	ds_read_b128 v[192:195], v167 offset:19456
	ds_read_b128 v[196:199], v167 offset:20480
	ds_read_b128 v[200:203], v167 offset:21504
	ds_read_b128 v[204:207], v167 offset:22528
	ds_read_b128 v[210:213], v167 offset:23552
	global_load_lds_dwordx4 v[160:161], off
	s_add_i32 m0, s73, 0x2000
	s_add_u32 s74, s46, 0x100000
	v_lshl_add_u64 v[214:215], s[46:47], 0, v[150:151]
	s_addc_u32 s75, s47, 0
	s_add_i32 s73, s69, s93
	global_load_lds_dwordx4 v[214:215], off
	v_lshl_add_u64 v[216:217], s[74:75], 0, v[146:147]
	s_mov_b32 m0, s73
	v_lshl_add_u64 v[218:219], s[48:49], 0, v[148:149]
	global_load_lds_dwordx4 v[216:217], off
	v_lshl_add_u64 v[216:217], s[74:75], 0, v[150:151]
	s_add_i32 m0, s73, 0x2000
	s_nop 0
	global_load_lds_dwordx4 v[216:217], off
	v_lshl_add_u64 v[216:217], s[48:49], 0, v[144:145]
	s_mov_b32 m0, s61
	s_nop 0
	global_load_lds_dwordx4 v[216:217], off
	s_mov_b32 m0, s62
	s_nop 0
	global_load_lds_dwordx4 v[218:219], off
	s_waitcnt vmcnt(8)
	s_waitcnt lgkmcnt(0)
	s_barrier
	s_setprio 1
	s_waitcnt lgkmcnt(0)
	v_mfma_f32_16x16x32_bf16 v[76:79], v[32:35], v[180:183], v[76:79]
	v_mfma_f32_16x16x32_bf16 v[72:75], v[48:51], v[180:183], v[72:75]
	v_mfma_f32_16x16x32_bf16 v[60:63], v[32:35], v[188:191], v[60:63]
	v_mfma_f32_16x16x32_bf16 v[56:59], v[48:51], v[188:191], v[56:59]
	v_mfma_f32_16x16x32_bf16 v[28:31], v[32:35], v[196:199], v[28:31]
	v_mfma_f32_16x16x32_bf16 v[24:27], v[48:51], v[196:199], v[24:27]
	v_mfma_f32_16x16x32_bf16 v[12:15], v[32:35], v[204:207], v[12:15]
	v_mfma_f32_16x16x32_bf16 v[8:11], v[48:51], v[204:207], v[8:11]
	v_mfma_f32_16x16x32_bf16 v[76:79], v[36:39], v[184:187], v[76:79]
	v_mfma_f32_16x16x32_bf16 v[72:75], v[52:55], v[184:187], v[72:75]
	v_mfma_f32_16x16x32_bf16 v[60:63], v[36:39], v[192:195], v[60:63]
	v_mfma_f32_16x16x32_bf16 v[56:59], v[52:55], v[192:195], v[56:59]
	v_mfma_f32_16x16x32_bf16 v[28:31], v[36:39], v[200:203], v[28:31]
	v_mfma_f32_16x16x32_bf16 v[24:27], v[52:55], v[200:203], v[24:27]
	v_mfma_f32_16x16x32_bf16 v[12:15], v[36:39], v[210:213], v[12:15]
	v_mfma_f32_16x16x32_bf16 v[8:11], v[52:55], v[210:213], v[8:11]
	v_mfma_f32_16x16x32_bf16 v[44:47], v[156:159], v[188:191], v[44:47]
	v_mfma_f32_16x16x32_bf16 v[40:43], v[172:175], v[188:191], v[40:43]
	v_mfma_f32_16x16x32_bf16 v[20:23], v[156:159], v[196:199], v[20:23]
	v_mfma_f32_16x16x32_bf16 v[16:19], v[172:175], v[196:199], v[16:19]
	v_mfma_f32_16x16x32_bf16 v[4:7], v[156:159], v[204:207], v[4:7]
	v_mfma_f32_16x16x32_bf16 v[0:3], v[172:175], v[204:207], v[0:3]
	v_mfma_f32_16x16x32_bf16 v[32:35], v[156:159], v[180:183], v[68:71]
	v_mfma_f32_16x16x32_bf16 v[36:39], v[172:175], v[180:183], v[64:67]
	v_mfma_f32_16x16x32_bf16 v[44:47], v[168:171], v[192:195], v[44:47]
	v_mfma_f32_16x16x32_bf16 v[40:43], v[176:179], v[192:195], v[40:43]
	v_mfma_f32_16x16x32_bf16 v[20:23], v[168:171], v[200:203], v[20:23]
	v_mfma_f32_16x16x32_bf16 v[16:19], v[176:179], v[200:203], v[16:19]
	v_mfma_f32_16x16x32_bf16 v[4:7], v[168:171], v[210:213], v[4:7]
	v_mfma_f32_16x16x32_bf16 v[0:3], v[176:179], v[210:213], v[0:3]
	v_mfma_f32_16x16x32_bf16 v[32:35], v[168:171], v[184:187], v[32:35]
	v_mfma_f32_16x16x32_bf16 v[36:39], v[176:179], v[184:187], v[36:39]
	s_setprio 0
	s_barrier
	s_add_i32 s73, 0, 0x18000
	s_add_i32 s74, 0, 0x1c000
	v_add_u32_e32 v68, s73, v163
	v_add_u32_e32 v176, s74, v163
	ds_read_b128 v[48:51], v68
	ds_read_b128 v[52:55], v68 offset:1024
	ds_read_b128 v[64:67], v68 offset:2048
	ds_read_b128 v[68:71], v68 offset:3072
	ds_read_b128 v[156:159], v176
	ds_read_b128 v[168:171], v176 offset:1024
	ds_read_b128 v[172:175], v176 offset:2048
	ds_read_b128 v[176:179], v176 offset:3072
	s_add_u32 s48, s48, 0x80000
	s_addc_u32 s49, s49, 0
	s_mov_b32 m0, s63
	v_lshl_add_u64 v[220:221], s[48:49], 0, v[144:145]
	ds_read_b128 v[180:183], v167 offset:32768
	ds_read_b128 v[184:187], v167 offset:33792
	ds_read_b128 v[188:191], v167 offset:34816
	ds_read_b128 v[192:195], v167 offset:35840
	ds_read_b128 v[196:199], v167 offset:36864
	ds_read_b128 v[200:203], v167 offset:37888
	ds_read_b128 v[204:207], v167 offset:38912
	ds_read_b128 v[210:213], v167 offset:39936
	global_load_lds_dwordx4 v[220:221], off
	v_lshl_add_u64 v[220:221], s[48:49], 0, v[148:149]
	s_mov_b32 m0, s64
	s_nop 0
	global_load_lds_dwordx4 v[220:221], off
	s_waitcnt vmcnt(8)
	s_waitcnt lgkmcnt(0)
	s_barrier
	s_setprio 1
	s_waitcnt lgkmcnt(0)
	v_mfma_f32_16x16x32_bf16 v[140:143], v[48:51], v[180:183], v[140:143]
	v_mfma_f32_16x16x32_bf16 v[136:139], v[64:67], v[180:183], v[136:139]
	v_mfma_f32_16x16x32_bf16 v[124:127], v[48:51], v[188:191], v[124:127]
	v_mfma_f32_16x16x32_bf16 v[120:123], v[64:67], v[188:191], v[120:123]
	v_mfma_f32_16x16x32_bf16 v[108:111], v[48:51], v[196:199], v[108:111]
	v_mfma_f32_16x16x32_bf16 v[104:107], v[64:67], v[196:199], v[104:107]
	v_mfma_f32_16x16x32_bf16 v[92:95], v[48:51], v[204:207], v[92:95]
	v_mfma_f32_16x16x32_bf16 v[88:91], v[64:67], v[204:207], v[88:91]
	v_mfma_f32_16x16x32_bf16 v[140:143], v[52:55], v[184:187], v[140:143]
	v_mfma_f32_16x16x32_bf16 v[136:139], v[68:71], v[184:187], v[136:139]
	v_mfma_f32_16x16x32_bf16 v[124:127], v[52:55], v[192:195], v[124:127]
	v_mfma_f32_16x16x32_bf16 v[120:123], v[68:71], v[192:195], v[120:123]
	v_mfma_f32_16x16x32_bf16 v[108:111], v[52:55], v[200:203], v[108:111]
	v_mfma_f32_16x16x32_bf16 v[104:107], v[68:71], v[200:203], v[104:107]
	v_mfma_f32_16x16x32_bf16 v[92:95], v[52:55], v[210:213], v[92:95]
	v_mfma_f32_16x16x32_bf16 v[88:91], v[68:71], v[210:213], v[88:91]
	v_mfma_f32_16x16x32_bf16 v[132:135], v[156:159], v[180:183], v[132:135]
	v_mfma_f32_16x16x32_bf16 v[128:131], v[172:175], v[180:183], v[128:131]
	v_mfma_f32_16x16x32_bf16 v[116:119], v[156:159], v[188:191], v[116:119]
	v_mfma_f32_16x16x32_bf16 v[112:115], v[172:175], v[188:191], v[112:115]
	v_mfma_f32_16x16x32_bf16 v[100:103], v[156:159], v[196:199], v[100:103]
	v_mfma_f32_16x16x32_bf16 v[96:99], v[172:175], v[196:199], v[96:99]
	v_mfma_f32_16x16x32_bf16 v[84:87], v[156:159], v[204:207], v[84:87]
	v_mfma_f32_16x16x32_bf16 v[80:83], v[172:175], v[204:207], v[80:83]
	v_mfma_f32_16x16x32_bf16 v[132:135], v[168:171], v[184:187], v[132:135]
	v_mfma_f32_16x16x32_bf16 v[128:131], v[176:179], v[184:187], v[128:131]
	v_mfma_f32_16x16x32_bf16 v[116:119], v[168:171], v[192:195], v[116:119]
	v_mfma_f32_16x16x32_bf16 v[112:115], v[176:179], v[192:195], v[112:115]
	v_mfma_f32_16x16x32_bf16 v[100:103], v[168:171], v[200:203], v[100:103]
	v_mfma_f32_16x16x32_bf16 v[96:99], v[176:179], v[200:203], v[96:99]
	v_mfma_f32_16x16x32_bf16 v[84:87], v[168:171], v[210:213], v[84:87]
	v_mfma_f32_16x16x32_bf16 v[80:83], v[176:179], v[210:213], v[80:83]
	s_setprio 0
	s_barrier
	s_add_i32 s48, s73, s93
	v_lshl_add_u64 v[160:161], v[160:161], 0, s[28:29]
	s_mov_b32 m0, s48
	ds_read_b128 v[180:183], v167 offset:49152
	ds_read_b128 v[184:187], v167 offset:50176
	ds_read_b128 v[188:191], v167 offset:51200
	ds_read_b128 v[192:195], v167 offset:52224
	ds_read_b128 v[196:199], v167 offset:53248
	ds_read_b128 v[200:203], v167 offset:54272
	ds_read_b128 v[204:207], v167 offset:55296
	ds_read_b128 v[210:213], v167 offset:56320
	global_load_lds_dwordx4 v[160:161], off
	s_add_i32 m0, s48, 0x2000
	s_add_u32 s46, s46, 0x100080
	v_lshl_add_u64 v[160:161], v[214:215], 0, s[28:29]
	s_addc_u32 s47, s47, 0
	s_add_i32 s48, s74, s93
	global_load_lds_dwordx4 v[160:161], off
	v_lshl_add_u64 v[160:161], s[46:47], 0, v[146:147]
	s_mov_b32 m0, s48
	s_nop 0
	global_load_lds_dwordx4 v[160:161], off
	v_lshl_add_u64 v[160:161], s[46:47], 0, v[150:151]
	s_add_i32 m0, s48, 0x2000
	s_nop 0
	global_load_lds_dwordx4 v[160:161], off
	v_lshl_add_u64 v[160:161], v[216:217], 0, s[28:29]
	s_mov_b32 m0, s65
	s_nop 0
	global_load_lds_dwordx4 v[160:161], off
	v_lshl_add_u64 v[160:161], v[218:219], 0, s[28:29]
	s_mov_b32 m0, s66
	s_nop 0
	global_load_lds_dwordx4 v[160:161], off
	s_waitcnt vmcnt(8)
	s_waitcnt lgkmcnt(0)
	s_barrier
	s_setprio 1
	s_waitcnt lgkmcnt(0)
	v_mfma_f32_16x16x32_bf16 v[76:79], v[48:51], v[180:183], v[76:79]
	v_mfma_f32_16x16x32_bf16 v[72:75], v[64:67], v[180:183], v[72:75]
	v_mfma_f32_16x16x32_bf16 v[60:63], v[48:51], v[188:191], v[60:63]
	v_mfma_f32_16x16x32_bf16 v[56:59], v[64:67], v[188:191], v[56:59]
	v_mfma_f32_16x16x32_bf16 v[28:31], v[48:51], v[196:199], v[28:31]
	v_mfma_f32_16x16x32_bf16 v[24:27], v[64:67], v[196:199], v[24:27]
	v_mfma_f32_16x16x32_bf16 v[12:15], v[48:51], v[204:207], v[12:15]
	v_mfma_f32_16x16x32_bf16 v[8:11], v[64:67], v[204:207], v[8:11]
	v_mfma_f32_16x16x32_bf16 v[76:79], v[52:55], v[184:187], v[76:79]
	v_mfma_f32_16x16x32_bf16 v[72:75], v[68:71], v[184:187], v[72:75]
	v_mfma_f32_16x16x32_bf16 v[60:63], v[52:55], v[192:195], v[60:63]
	v_mfma_f32_16x16x32_bf16 v[56:59], v[68:71], v[192:195], v[56:59]
	v_mfma_f32_16x16x32_bf16 v[28:31], v[52:55], v[200:203], v[28:31]
	v_mfma_f32_16x16x32_bf16 v[24:27], v[68:71], v[200:203], v[24:27]
	v_mfma_f32_16x16x32_bf16 v[12:15], v[52:55], v[210:213], v[12:15]
	v_mfma_f32_16x16x32_bf16 v[8:11], v[68:71], v[210:213], v[8:11]
	v_mfma_f32_16x16x32_bf16 v[32:35], v[156:159], v[180:183], v[32:35]
	v_mfma_f32_16x16x32_bf16 v[68:71], v[168:171], v[184:187], v[32:35]
	v_mfma_f32_16x16x32_bf16 v[32:35], v[172:175], v[180:183], v[36:39]
	v_mfma_f32_16x16x32_bf16 v[64:67], v[176:179], v[184:187], v[32:35]
	v_mfma_f32_16x16x32_bf16 v[32:35], v[156:159], v[188:191], v[44:47]
	v_mfma_f32_16x16x32_bf16 v[44:47], v[168:171], v[192:195], v[32:35]
	v_mfma_f32_16x16x32_bf16 v[32:35], v[172:175], v[188:191], v[40:43]
	v_mfma_f32_16x16x32_bf16 v[20:23], v[156:159], v[196:199], v[20:23]
	v_mfma_f32_16x16x32_bf16 v[16:19], v[172:175], v[196:199], v[16:19]
	v_mfma_f32_16x16x32_bf16 v[4:7], v[156:159], v[204:207], v[4:7]
	v_mfma_f32_16x16x32_bf16 v[0:3], v[172:175], v[204:207], v[0:3]
	v_mfma_f32_16x16x32_bf16 v[40:43], v[176:179], v[192:195], v[32:35]
	v_mfma_f32_16x16x32_bf16 v[20:23], v[168:171], v[200:203], v[20:23]
	v_mfma_f32_16x16x32_bf16 v[16:19], v[176:179], v[200:203], v[16:19]
	v_mfma_f32_16x16x32_bf16 v[4:7], v[168:171], v[210:213], v[4:7]
	v_mfma_f32_16x16x32_bf16 v[0:3], v[176:179], v[210:213], v[0:3]
	s_setprio 0
	s_barrier
	s_add_i32 s72, s72, 2
	s_add_u32 s44, s44, 0x100
	s_addc_u32 s45, s45, 0
	s_add_u32 s39, s39, 0x100
	s_addc_u32 s71, s71, 0
	s_cmp_gt_u32 s72, 61
	s_cbranch_scc0 .LBB0_376
	v_readlane_b32 s72, v235, 62
	s_and_b64 vcc, exec, s[30:31]
	v_readlane_b32 s73, v235, 63
	v_readlane_b32 s74, v234, 0
	v_readlane_b32 s75, v234, 1
	s_cbranch_vccz .LBB0_379
	s_barrier

.LBB0_399:
	s_ashr_i32 s39, s38, 31
	s_lshl_b64 s[2:3], s[38:39], 17
	s_add_u32 s40, s6, s2
	s_addc_u32 s41, s7, s3
	ds_read_b128 v[0:3], v90
	ds_read_b128 v[4:7], v90 offset:1024
	ds_read_b128 v[8:11], v90 offset:2048
	ds_read_b128 v[12:15], v90 offset:3072
	s_and_b64 s[2:3], s[34:35], exec
	s_cselect_b32 s49, s41, s45
	s_cselect_b32 s48, s40, s44
	s_ashr_i32 s37, s36, 31
	s_lshl_b64 s[2:3], s[36:37], 17
	s_add_u32 s42, s20, s2
	s_addc_u32 s43, s21, s3
	s_and_b64 s[2:3], s[34:35], exec
	s_cselect_b32 s47, s43, s51
	s_cselect_b32 s46, s42, s50
	s_add_u32 s2, s44, 0x10080
	s_addc_u32 s3, s45, 0
	s_mov_b32 m0, s59
	v_lshl_add_u64 v[48:49], s[2:3], 0, v[64:65]
	ds_read_b128 v[16:19], v91
	ds_read_b128 v[20:23], v91 offset:1024
	ds_read_b128 v[24:27], v91 offset:2048
	ds_read_b128 v[28:31], v91 offset:3072
	ds_read_b128 v[32:35], v91 offset:4096
	ds_read_b128 v[36:39], v91 offset:5120
	ds_read_b128 v[40:43], v91 offset:6144
	ds_read_b128 v[44:47], v91 offset:7168
	global_load_lds_dwordx4 v[48:49], off
	v_lshl_add_u64 v[48:49], s[2:3], 0, v[68:69]
	s_mov_b32 m0, s68
	s_nop 0
	global_load_lds_dwordx4 v[48:49], off
	s_waitcnt vmcnt(8)
	s_waitcnt lgkmcnt(0)
	s_barrier
	s_setprio 1
	s_waitcnt lgkmcnt(0)
	v_mfma_f32_16x16x32_bf16 v[48:51], v[0:3], v[16:19], 0
	v_mfma_f32_16x16x32_bf16 v[16:19], v[8:11], v[16:19], 0
	v_mfma_f32_16x16x32_bf16 v[48:51], v[4:7], v[20:23], v[48:51]
	v_mfma_f32_16x16x32_bf16 v[16:19], v[12:15], v[20:23], v[16:19]
	v_mfma_f32_16x16x32_bf16 v[20:23], v[0:3], v[24:27], 0
	v_mfma_f32_16x16x32_bf16 v[24:27], v[8:11], v[24:27], 0
	v_mfma_f32_16x16x32_bf16 v[20:23], v[4:7], v[28:31], v[20:23]
	v_mfma_f32_16x16x32_bf16 v[24:27], v[12:15], v[28:31], v[24:27]
	v_mfma_f32_16x16x32_bf16 v[28:31], v[0:3], v[32:35], 0
	v_mfma_f32_16x16x32_bf16 v[32:35], v[8:11], v[32:35], 0
	v_mfma_f32_16x16x32_bf16 v[28:31], v[4:7], v[36:39], v[28:31]
	v_mfma_f32_16x16x32_bf16 v[32:35], v[12:15], v[36:39], v[32:35]
	v_mfma_f32_16x16x32_bf16 v[36:39], v[0:3], v[40:43], 0
	v_mfma_f32_16x16x32_bf16 v[40:43], v[8:11], v[40:43], 0
	v_mfma_f32_16x16x32_bf16 v[36:39], v[4:7], v[44:47], v[36:39]
	v_mfma_f32_16x16x32_bf16 v[40:43], v[12:15], v[44:47], v[40:43]
	s_setprio 0
	s_barrier
	v_lshl_add_u64 v[142:143], s[50:51], 0, v[66:67]
	s_mov_b32 m0, s69
	v_lshl_add_u64 v[110:111], v[142:143], 0, s[26:27]
	v_lshl_add_u64 v[144:145], s[50:51], 0, v[70:71]
	s_add_u32 s2, s50, 0x10100
	ds_read_b128 v[44:47], v91 offset:16384
	ds_read_b128 v[52:55], v91 offset:17408
	ds_read_b128 v[56:59], v91 offset:18432
	ds_read_b128 v[60:63], v91 offset:19456
	ds_read_b128 v[94:97], v91 offset:20480
	ds_read_b128 v[98:101], v91 offset:21504
	ds_read_b128 v[102:105], v91 offset:22528
	ds_read_b128 v[106:109], v91 offset:23552
	global_load_lds_dwordx4 v[110:111], off
	v_lshl_add_u64 v[110:111], v[144:145], 0, s[26:27]
	s_mov_b32 m0, s70
	s_addc_u32 s3, s51, 0
	global_load_lds_dwordx4 v[110:111], off
	v_lshl_add_u64 v[110:111], s[2:3], 0, v[66:67]
	s_mov_b32 m0, s33
	v_lshl_add_u64 v[146:147], s[44:45], 0, v[64:65]
	global_load_lds_dwordx4 v[110:111], off
	v_lshl_add_u64 v[110:111], s[2:3], 0, v[70:71]
	s_mov_b32 m0, s60
	v_lshl_add_u64 v[148:149], s[44:45], 0, v[68:69]
	global_load_lds_dwordx4 v[110:111], off
	v_lshl_add_u64 v[110:111], v[146:147], 0, s[26:27]
	s_mov_b32 m0, s31
	s_nop 0
	global_load_lds_dwordx4 v[110:111], off
	v_lshl_add_u64 v[110:111], v[148:149], 0, s[26:27]
	s_mov_b32 m0, s61
	s_nop 0
	global_load_lds_dwordx4 v[110:111], off
	s_waitcnt vmcnt(8)
	s_waitcnt lgkmcnt(0)
	s_barrier
	s_setprio 1
	s_waitcnt lgkmcnt(0)
	v_mfma_f32_16x16x32_bf16 v[110:113], v[0:3], v[44:47], 0
	v_mfma_f32_16x16x32_bf16 v[44:47], v[8:11], v[44:47], 0
	v_mfma_f32_16x16x32_bf16 v[110:113], v[4:7], v[52:55], v[110:113]
	v_mfma_f32_16x16x32_bf16 v[44:47], v[12:15], v[52:55], v[44:47]
	v_mfma_f32_16x16x32_bf16 v[52:55], v[0:3], v[56:59], 0
	v_mfma_f32_16x16x32_bf16 v[56:59], v[8:11], v[56:59], 0
	v_mfma_f32_16x16x32_bf16 v[52:55], v[4:7], v[60:63], v[52:55]
	v_mfma_f32_16x16x32_bf16 v[56:59], v[12:15], v[60:63], v[56:59]
	v_mfma_f32_16x16x32_bf16 v[60:63], v[0:3], v[94:97], 0
	v_mfma_f32_16x16x32_bf16 v[0:3], v[0:3], v[102:105], 0
	v_mfma_f32_16x16x32_bf16 v[60:63], v[4:7], v[98:101], v[60:63]
	v_mfma_f32_16x16x32_bf16 v[0:3], v[4:7], v[106:109], v[0:3]
	v_mfma_f32_16x16x32_bf16 v[4:7], v[8:11], v[102:105], 0
	v_mfma_f32_16x16x32_bf16 v[94:97], v[8:11], v[94:97], 0
	v_mfma_f32_16x16x32_bf16 v[4:7], v[12:15], v[106:109], v[4:7]
	v_mfma_f32_16x16x32_bf16 v[94:97], v[12:15], v[98:101], v[94:97]
	s_setprio 0
	s_barrier
	ds_read_b128 v[8:11], v92
	ds_read_b128 v[12:15], v92 offset:1024
	ds_read_b128 v[98:101], v92 offset:2048
	ds_read_b128 v[102:105], v92 offset:3072
	s_add_u32 s2, s44, 0x10100
	s_addc_u32 s3, s45, 0
	s_mov_b32 m0, s62
	v_lshl_add_u64 v[150:151], s[2:3], 0, v[64:65]
	ds_read_b128 v[106:109], v91 offset:32768
	ds_read_b128 v[114:117], v91 offset:33792
	ds_read_b128 v[118:121], v91 offset:34816
	ds_read_b128 v[122:125], v91 offset:35840
	ds_read_b128 v[126:129], v91 offset:36864
	ds_read_b128 v[130:133], v91 offset:37888
	ds_read_b128 v[134:137], v91 offset:38912
	ds_read_b128 v[138:141], v91 offset:39936
	global_load_lds_dwordx4 v[150:151], off
	v_lshl_add_u64 v[150:151], s[2:3], 0, v[68:69]
	s_mov_b32 m0, s63
	s_nop 0
	global_load_lds_dwordx4 v[150:151], off
	s_waitcnt vmcnt(8)
	s_waitcnt lgkmcnt(0)
	s_barrier
	s_setprio 1
	s_waitcnt lgkmcnt(0)
	v_mfma_f32_16x16x32_bf16 v[48:51], v[8:11], v[106:109], v[48:51]
	v_mfma_f32_16x16x32_bf16 v[16:19], v[98:101], v[106:109], v[16:19]
	v_mfma_f32_16x16x32_bf16 v[20:23], v[8:11], v[118:121], v[20:23]
	v_mfma_f32_16x16x32_bf16 v[24:27], v[98:101], v[118:121], v[24:27]
	v_mfma_f32_16x16x32_bf16 v[28:31], v[8:11], v[126:129], v[28:31]
	v_mfma_f32_16x16x32_bf16 v[32:35], v[98:101], v[126:129], v[32:35]
	v_mfma_f32_16x16x32_bf16 v[36:39], v[8:11], v[134:137], v[36:39]
	v_mfma_f32_16x16x32_bf16 v[40:43], v[98:101], v[134:137], v[40:43]
	v_mfma_f32_16x16x32_bf16 v[48:51], v[12:15], v[114:117], v[48:51]
	v_mfma_f32_16x16x32_bf16 v[16:19], v[102:105], v[114:117], v[16:19]
	v_mfma_f32_16x16x32_bf16 v[20:23], v[12:15], v[122:125], v[20:23]
	v_mfma_f32_16x16x32_bf16 v[24:27], v[102:105], v[122:125], v[24:27]
	v_mfma_f32_16x16x32_bf16 v[28:31], v[12:15], v[130:133], v[28:31]
	v_mfma_f32_16x16x32_bf16 v[32:35], v[102:105], v[130:133], v[32:35]
	v_mfma_f32_16x16x32_bf16 v[36:39], v[12:15], v[138:141], v[36:39]
	v_mfma_f32_16x16x32_bf16 v[40:43], v[102:105], v[138:141], v[40:43]
	s_setprio 0
	s_barrier
	s_mov_b32 m0, s71
	v_lshl_add_u64 v[142:143], v[142:143], 0, s[28:29]
	s_add_u32 s2, s50, 0x10180
	ds_read_b128 v[106:109], v91 offset:49152
	ds_read_b128 v[114:117], v91 offset:50176
	ds_read_b128 v[118:121], v91 offset:51200
	ds_read_b128 v[122:125], v91 offset:52224
	ds_read_b128 v[126:129], v91 offset:53248
	ds_read_b128 v[130:133], v91 offset:54272
	ds_read_b128 v[134:137], v91 offset:55296
	ds_read_b128 v[138:141], v91 offset:56320
	global_load_lds_dwordx4 v[142:143], off
	v_lshl_add_u64 v[142:143], v[144:145], 0, s[28:29]
	s_mov_b32 m0, s72
	s_addc_u32 s3, s51, 0
	global_load_lds_dwordx4 v[142:143], off
	v_lshl_add_u64 v[142:143], s[2:3], 0, v[66:67]
	s_mov_b32 m0, s66
	s_nop 0
	global_load_lds_dwordx4 v[142:143], off
	v_lshl_add_u64 v[142:143], s[2:3], 0, v[70:71]
	s_mov_b32 m0, s67
	s_nop 0
	global_load_lds_dwordx4 v[142:143], off
	v_lshl_add_u64 v[142:143], v[146:147], 0, s[28:29]
	s_mov_b32 m0, s64
	s_nop 0
	global_load_lds_dwordx4 v[142:143], off
	v_lshl_add_u64 v[142:143], v[148:149], 0, s[28:29]
	s_mov_b32 m0, s65
	s_nop 0
	global_load_lds_dwordx4 v[142:143], off
	s_waitcnt vmcnt(8)
	s_waitcnt lgkmcnt(0)
	s_barrier
	s_setprio 1
	s_waitcnt lgkmcnt(0)
	v_mfma_f32_16x16x32_bf16 v[44:47], v[98:101], v[106:109], v[44:47]
	v_mfma_f32_16x16x32_bf16 v[52:55], v[8:11], v[118:121], v[52:55]
	v_mfma_f32_16x16x32_bf16 v[56:59], v[98:101], v[118:121], v[56:59]
	v_mfma_f32_16x16x32_bf16 v[60:63], v[8:11], v[126:129], v[60:63]
	v_mfma_f32_16x16x32_bf16 v[0:3], v[8:11], v[134:137], v[0:3]
	v_mfma_f32_16x16x32_bf16 v[4:7], v[98:101], v[134:137], v[4:7]
	v_mfma_f32_16x16x32_bf16 v[110:113], v[8:11], v[106:109], v[110:113]
	v_mfma_f32_16x16x32_bf16 v[44:47], v[102:105], v[114:117], v[44:47]
	v_mfma_f32_16x16x32_bf16 v[52:55], v[12:15], v[122:125], v[52:55]
	v_mfma_f32_16x16x32_bf16 v[56:59], v[102:105], v[122:125], v[56:59]
	v_mfma_f32_16x16x32_bf16 v[60:63], v[12:15], v[130:133], v[60:63]
	v_mfma_f32_16x16x32_bf16 v[94:97], v[98:101], v[126:129], v[94:97]
	v_mfma_f32_16x16x32_bf16 v[0:3], v[12:15], v[138:141], v[0:3]
	v_mfma_f32_16x16x32_bf16 v[4:7], v[102:105], v[138:141], v[4:7]
	v_mfma_f32_16x16x32_bf16 v[110:113], v[12:15], v[114:117], v[110:113]
	v_mfma_f32_16x16x32_bf16 v[94:97], v[102:105], v[130:133], v[94:97]
	s_setprio 0
	s_barrier
	ds_read_b128 v[8:11], v90
	ds_read_b128 v[12:15], v90 offset:1024
	ds_read_b128 v[98:101], v90 offset:2048
	ds_read_b128 v[102:105], v90 offset:3072
	s_add_u32 s2, s44, 0x10180
	s_addc_u32 s3, s45, 0
	s_mov_b32 m0, s59
	v_lshl_add_u64 v[142:143], s[2:3], 0, v[64:65]
	ds_read_b128 v[106:109], v91
	ds_read_b128 v[114:117], v91 offset:1024
	ds_read_b128 v[118:121], v91 offset:2048
	ds_read_b128 v[122:125], v91 offset:3072
	ds_read_b128 v[126:129], v91 offset:4096
	ds_read_b128 v[130:133], v91 offset:5120
	ds_read_b128 v[134:137], v91 offset:6144
	ds_read_b128 v[138:141], v91 offset:7168
	global_load_lds_dwordx4 v[142:143], off
	v_lshl_add_u64 v[142:143], s[2:3], 0, v[68:69]
	s_mov_b32 m0, s68
	s_nop 0
	global_load_lds_dwordx4 v[142:143], off
	s_waitcnt vmcnt(8)
	s_waitcnt lgkmcnt(0)
	s_barrier
	s_setprio 1
	s_waitcnt lgkmcnt(0)
	v_mfma_f32_16x16x32_bf16 v[36:39], v[8:11], v[134:137], v[36:39]
	v_mfma_f32_16x16x32_bf16 v[48:51], v[8:11], v[106:109], v[48:51]
	v_mfma_f32_16x16x32_bf16 v[16:19], v[98:101], v[106:109], v[16:19]
	v_mfma_f32_16x16x32_bf16 v[20:23], v[8:11], v[118:121], v[20:23]
	v_mfma_f32_16x16x32_bf16 v[24:27], v[98:101], v[118:121], v[24:27]
	v_mfma_f32_16x16x32_bf16 v[28:31], v[8:11], v[126:129], v[28:31]
	v_mfma_f32_16x16x32_bf16 v[32:35], v[98:101], v[126:129], v[32:35]
	v_mfma_f32_16x16x32_bf16 v[106:109], v[12:15], v[138:141], v[36:39]
	v_mfma_f32_16x16x32_bf16 v[36:39], v[98:101], v[134:137], v[40:43]
	v_mfma_f32_16x16x32_bf16 v[48:51], v[12:15], v[114:117], v[48:51]
	v_mfma_f32_16x16x32_bf16 v[16:19], v[102:105], v[114:117], v[16:19]
	v_mfma_f32_16x16x32_bf16 v[20:23], v[12:15], v[122:125], v[20:23]
	v_mfma_f32_16x16x32_bf16 v[24:27], v[102:105], v[122:125], v[24:27]
	v_mfma_f32_16x16x32_bf16 v[28:31], v[12:15], v[130:133], v[28:31]
	v_mfma_f32_16x16x32_bf16 v[32:35], v[102:105], v[130:133], v[32:35]
	v_mfma_f32_16x16x32_bf16 v[40:43], v[102:105], v[138:141], v[36:39]
	s_setprio 0
	s_barrier
	s_mov_b32 m0, s69
	v_lshl_add_u64 v[154:155], s[46:47], 0, v[66:67]
	s_add_u32 s2, s46, 0x10000
	ds_read_b128 v[36:39], v91 offset:16384
	ds_read_b128 v[114:117], v91 offset:17408
	ds_read_b128 v[118:121], v91 offset:18432
	ds_read_b128 v[122:125], v91 offset:19456
	ds_read_b128 v[126:129], v91 offset:20480
	ds_read_b128 v[130:133], v91 offset:21504
	ds_read_b128 v[134:137], v91 offset:22528
	ds_read_b128 v[138:141], v91 offset:23552
	global_load_lds_dwordx4 v[154:155], off
	v_lshl_add_u64 v[156:157], s[46:47], 0, v[70:71]
	s_mov_b32 m0, s70
	s_addc_u32 s3, s47, 0
	global_load_lds_dwordx4 v[156:157], off
	v_lshl_add_u64 v[142:143], s[2:3], 0, v[66:67]
	s_mov_b32 m0, s33
	v_lshl_add_u64 v[158:159], s[48:49], 0, v[64:65]
	global_load_lds_dwordx4 v[142:143], off
	v_lshl_add_u64 v[142:143], s[2:3], 0, v[70:71]
	s_mov_b32 m0, s60
	v_lshl_add_u64 v[160:161], s[48:49], 0, v[68:69]
	global_load_lds_dwordx4 v[142:143], off
	s_mov_b32 m0, s31
	s_nop 0
	global_load_lds_dwordx4 v[158:159], off
	s_mov_b32 m0, s61
	s_nop 0
	global_load_lds_dwordx4 v[160:161], off
	s_waitcnt vmcnt(8)
	s_waitcnt lgkmcnt(0)
	s_barrier
	s_setprio 1
	s_waitcnt lgkmcnt(0)
	v_mfma_f32_16x16x32_bf16 v[110:113], v[8:11], v[36:39], v[110:113]
	v_mfma_f32_16x16x32_bf16 v[36:39], v[98:101], v[36:39], v[44:47]
	v_mfma_f32_16x16x32_bf16 v[110:113], v[12:15], v[114:117], v[110:113]
	v_mfma_f32_16x16x32_bf16 v[114:117], v[102:105], v[114:117], v[36:39]
	v_mfma_f32_16x16x32_bf16 v[36:39], v[8:11], v[118:121], v[52:55]
	v_mfma_f32_16x16x32_bf16 v[142:145], v[12:15], v[122:125], v[36:39]
	v_mfma_f32_16x16x32_bf16 v[36:39], v[98:101], v[118:121], v[56:59]
	v_mfma_f32_16x16x32_bf16 v[118:121], v[102:105], v[122:125], v[36:39]
	v_mfma_f32_16x16x32_bf16 v[36:39], v[8:11], v[126:129], v[60:63]
	v_mfma_f32_16x16x32_bf16 v[0:3], v[8:11], v[134:137], v[0:3]
	v_mfma_f32_16x16x32_bf16 v[122:125], v[12:15], v[130:133], v[36:39]
	v_mfma_f32_16x16x32_bf16 v[36:39], v[98:101], v[126:129], v[94:97]
	v_mfma_f32_16x16x32_bf16 v[0:3], v[12:15], v[138:141], v[0:3]
	v_mfma_f32_16x16x32_bf16 v[4:7], v[98:101], v[134:137], v[4:7]
	v_mfma_f32_16x16x32_bf16 v[94:97], v[102:105], v[130:133], v[36:39]
	v_mfma_f32_16x16x32_bf16 v[98:101], v[102:105], v[138:141], v[4:7]
	s_setprio 0
	s_barrier
	s_nop 1
	ds_read_b128 v[4:7], v92
	ds_read_b128 v[102:105], v92 offset:1024
	ds_read_b128 v[126:129], v92 offset:2048
	ds_read_b128 v[130:133], v92 offset:3072
	s_add_u32 s2, s48, 0x10000
	s_addc_u32 s3, s49, 0
	s_mov_b32 m0, s62
	v_lshl_add_u64 v[52:53], s[2:3], 0, v[64:65]
	ds_read_b128 v[8:11], v91 offset:32768
	ds_read_b128 v[12:15], v91 offset:33792
	ds_read_b128 v[36:39], v91 offset:34816
	ds_read_b128 v[44:47], v91 offset:35840
	ds_read_b128 v[134:137], v91 offset:36864
	ds_read_b128 v[138:141], v91 offset:37888
	ds_read_b128 v[146:149], v91 offset:38912
	ds_read_b128 v[150:153], v91 offset:39936
	global_load_lds_dwordx4 v[52:53], off
	v_lshl_add_u64 v[52:53], s[2:3], 0, v[68:69]
	s_mov_b32 m0, s63
	s_nop 0
	global_load_lds_dwordx4 v[52:53], off
	s_waitcnt vmcnt(8)
	s_waitcnt lgkmcnt(0)
	s_barrier
	s_setprio 1
	s_waitcnt lgkmcnt(0)
	v_mfma_f32_16x16x32_bf16 v[48:51], v[4:7], v[8:11], v[48:51]
	v_mfma_f32_16x16x32_bf16 v[8:11], v[126:129], v[8:11], v[16:19]
	v_mfma_f32_16x16x32_bf16 v[56:59], v[130:133], v[12:15], v[8:11]
	v_mfma_f32_16x16x32_bf16 v[8:11], v[4:7], v[36:39], v[20:23]
	v_mfma_f32_16x16x32_bf16 v[52:55], v[102:105], v[44:47], v[8:11]
	v_mfma_f32_16x16x32_bf16 v[8:11], v[126:129], v[36:39], v[24:27]
	v_mfma_f32_16x16x32_bf16 v[60:63], v[102:105], v[12:15], v[48:51]
	v_mfma_f32_16x16x32_bf16 v[48:51], v[130:133], v[44:47], v[8:11]
	v_mfma_f32_16x16x32_bf16 v[8:11], v[4:7], v[134:137], v[28:31]
	v_mfma_f32_16x16x32_bf16 v[44:47], v[102:105], v[138:141], v[8:11]
	v_mfma_f32_16x16x32_bf16 v[8:11], v[126:129], v[134:137], v[32:35]
	v_mfma_f32_16x16x32_bf16 v[36:39], v[130:133], v[138:141], v[8:11]
	v_mfma_f32_16x16x32_bf16 v[8:11], v[4:7], v[146:149], v[106:109]
	v_mfma_f32_16x16x32_bf16 v[32:35], v[102:105], v[150:153], v[8:11]
	v_mfma_f32_16x16x32_bf16 v[8:11], v[126:129], v[146:149], v[40:43]
	v_mfma_f32_16x16x32_bf16 v[24:27], v[130:133], v[150:153], v[8:11]
	s_setprio 0
	s_barrier
	s_mov_b32 m0, s71
	v_lshl_add_u64 v[20:21], v[154:155], 0, s[22:23]
	s_add_u32 s2, s46, 0x10080
	ds_read_b128 v[8:11], v91 offset:49152
	ds_read_b128 v[12:15], v91 offset:50176
	ds_read_b128 v[16:19], v91 offset:51200
	ds_read_b128 v[106:109], v91 offset:52224
	ds_read_b128 v[134:137], v91 offset:53248
	ds_read_b128 v[138:141], v91 offset:54272
	ds_read_b128 v[146:149], v91 offset:55296
	ds_read_b128 v[150:153], v91 offset:56320
	global_load_lds_dwordx4 v[20:21], off
	v_lshl_add_u64 v[20:21], v[156:157], 0, s[22:23]
	s_mov_b32 m0, s72
	s_addc_u32 s3, s47, 0
	global_load_lds_dwordx4 v[20:21], off
	v_lshl_add_u64 v[20:21], s[2:3], 0, v[66:67]
	s_mov_b32 m0, s66
	s_nop 0
	global_load_lds_dwordx4 v[20:21], off
	v_lshl_add_u64 v[20:21], s[2:3], 0, v[70:71]
	s_mov_b32 m0, s67
	s_nop 0
	global_load_lds_dwordx4 v[20:21], off
	v_lshl_add_u64 v[20:21], v[158:159], 0, s[22:23]
	s_mov_b32 m0, s64
	s_nop 0
	global_load_lds_dwordx4 v[20:21], off
	v_lshl_add_u64 v[20:21], v[160:161], 0, s[22:23]
	s_mov_b32 m0, s65
	s_nop 0
	global_load_lds_dwordx4 v[20:21], off
	s_waitcnt vmcnt(8)
	s_waitcnt lgkmcnt(0)
	s_barrier
	s_setprio 1
	s_waitcnt lgkmcnt(0)
	v_mfma_f32_16x16x32_bf16 v[20:23], v[4:7], v[8:11], v[110:113]
	v_mfma_f32_16x16x32_bf16 v[8:11], v[126:129], v[8:11], v[114:117]
	v_mfma_f32_16x16x32_bf16 v[28:31], v[130:133], v[12:15], v[8:11]
	v_mfma_f32_16x16x32_bf16 v[8:11], v[4:7], v[16:19], v[142:145]
	v_mfma_f32_16x16x32_bf16 v[40:43], v[102:105], v[12:15], v[20:23]
	v_mfma_f32_16x16x32_bf16 v[20:23], v[102:105], v[106:109], v[8:11]
	v_mfma_f32_16x16x32_bf16 v[8:11], v[126:129], v[16:19], v[118:121]
	v_mfma_f32_16x16x32_bf16 v[16:19], v[130:133], v[106:109], v[8:11]
	v_mfma_f32_16x16x32_bf16 v[8:11], v[4:7], v[134:137], v[122:125]
	v_mfma_f32_16x16x32_bf16 v[0:3], v[4:7], v[146:149], v[0:3]
	v_mfma_f32_16x16x32_bf16 v[12:15], v[102:105], v[138:141], v[8:11]
	v_mfma_f32_16x16x32_bf16 v[8:11], v[126:129], v[134:137], v[94:97]
	v_mfma_f32_16x16x32_bf16 v[4:7], v[102:105], v[150:153], v[0:3]
	v_mfma_f32_16x16x32_bf16 v[0:3], v[126:129], v[146:149], v[98:101]
	v_mfma_f32_16x16x32_bf16 v[8:11], v[130:133], v[138:141], v[8:11]
	v_mfma_f32_16x16x32_bf16 v[0:3], v[130:133], v[150:153], v[0:3]
	s_setprio 0
	s_barrier
	s_and_b64 vcc, exec, s[4:5]
	s_cbranch_vccnz .LBB0_401
	s_barrier

.LBB0_424:
	ds_read_b128 v[32:35], v165
	ds_read_b128 v[36:39], v165 offset:1024
	ds_read_b128 v[48:51], v165 offset:2048
	ds_read_b128 v[52:55], v165 offset:3072
	ds_read_b128 v[156:159], v166
	ds_read_b128 v[168:171], v166 offset:1024
	ds_read_b128 v[172:175], v166 offset:2048
	ds_read_b128 v[176:179], v166 offset:3072
	s_add_u32 s40, s38, 0xfff80080
	s_addc_u32 s41, s39, -1
	s_cmp_eq_u32 s64, 60
	s_cselect_b32 s43, s2, s41
	s_cselect_b32 s42, s3, s40
	s_cselect_b32 s41, s29, s63
	s_cselect_b32 s40, s31, s33
	v_lshl_add_u64 v[160:161], s[38:39], 0, v[152:153]
	s_add_i32 m0, s47, 0xc000
	ds_read_b128 v[180:183], v167
	ds_read_b128 v[184:187], v167 offset:1024
	ds_read_b128 v[188:191], v167 offset:2048
	ds_read_b128 v[192:195], v167 offset:3072
	ds_read_b128 v[196:199], v167 offset:4096
	ds_read_b128 v[200:203], v167 offset:5120
	ds_read_b128 v[204:207], v167 offset:6144
	ds_read_b128 v[210:213], v167 offset:7168
	global_load_lds_dwordx4 v[160:161], off
	v_lshl_add_u64 v[160:161], s[38:39], 0, v[154:155]
	s_add_i32 m0, s47, 0xe000
	s_nop 0
	global_load_lds_dwordx4 v[160:161], off
	s_waitcnt vmcnt(8)
	s_waitcnt lgkmcnt(0)
	s_barrier
	s_setprio 1
	s_waitcnt lgkmcnt(0)
	v_mfma_f32_16x16x32_bf16 v[140:143], v[32:35], v[180:183], v[140:143]
	v_mfma_f32_16x16x32_bf16 v[136:139], v[48:51], v[180:183], v[136:139]
	v_mfma_f32_16x16x32_bf16 v[124:127], v[32:35], v[188:191], v[124:127]
	v_mfma_f32_16x16x32_bf16 v[120:123], v[48:51], v[188:191], v[120:123]
	v_mfma_f32_16x16x32_bf16 v[108:111], v[32:35], v[196:199], v[108:111]
	v_mfma_f32_16x16x32_bf16 v[104:107], v[48:51], v[196:199], v[104:107]
	v_mfma_f32_16x16x32_bf16 v[92:95], v[32:35], v[204:207], v[92:95]
	v_mfma_f32_16x16x32_bf16 v[88:91], v[48:51], v[204:207], v[88:91]
	v_mfma_f32_16x16x32_bf16 v[140:143], v[36:39], v[184:187], v[140:143]
	v_mfma_f32_16x16x32_bf16 v[136:139], v[52:55], v[184:187], v[136:139]
	v_mfma_f32_16x16x32_bf16 v[124:127], v[36:39], v[192:195], v[124:127]
	v_mfma_f32_16x16x32_bf16 v[120:123], v[52:55], v[192:195], v[120:123]
	v_mfma_f32_16x16x32_bf16 v[108:111], v[36:39], v[200:203], v[108:111]
	v_mfma_f32_16x16x32_bf16 v[104:107], v[52:55], v[200:203], v[104:107]
	v_mfma_f32_16x16x32_bf16 v[92:95], v[36:39], v[210:213], v[92:95]
	v_mfma_f32_16x16x32_bf16 v[88:91], v[52:55], v[210:213], v[88:91]
	v_mfma_f32_16x16x32_bf16 v[132:135], v[156:159], v[180:183], v[132:135]
	v_mfma_f32_16x16x32_bf16 v[128:131], v[172:175], v[180:183], v[128:131]
	v_mfma_f32_16x16x32_bf16 v[116:119], v[156:159], v[188:191], v[116:119]
	v_mfma_f32_16x16x32_bf16 v[112:115], v[172:175], v[188:191], v[112:115]
	v_mfma_f32_16x16x32_bf16 v[100:103], v[156:159], v[196:199], v[100:103]
	v_mfma_f32_16x16x32_bf16 v[96:99], v[172:175], v[196:199], v[96:99]
	v_mfma_f32_16x16x32_bf16 v[84:87], v[156:159], v[204:207], v[84:87]
	v_mfma_f32_16x16x32_bf16 v[80:83], v[172:175], v[204:207], v[80:83]
	v_mfma_f32_16x16x32_bf16 v[132:135], v[168:171], v[184:187], v[132:135]
	v_mfma_f32_16x16x32_bf16 v[128:131], v[176:179], v[184:187], v[128:131]
	v_mfma_f32_16x16x32_bf16 v[116:119], v[168:171], v[192:195], v[116:119]
	v_mfma_f32_16x16x32_bf16 v[112:115], v[176:179], v[192:195], v[112:115]
	v_mfma_f32_16x16x32_bf16 v[100:103], v[168:171], v[200:203], v[100:103]
	v_mfma_f32_16x16x32_bf16 v[96:99], v[176:179], v[200:203], v[96:99]
	v_mfma_f32_16x16x32_bf16 v[84:87], v[168:171], v[210:213], v[84:87]
	v_mfma_f32_16x16x32_bf16 v[80:83], v[176:179], v[210:213], v[80:83]
	s_setprio 0
	s_barrier
	s_add_i32 s65, s60, s93
	v_lshl_add_u64 v[160:161], s[40:41], 0, v[146:147]
	s_mov_b32 m0, s65
	ds_read_b128 v[180:183], v167 offset:16384
	ds_read_b128 v[184:187], v167 offset:17408
	ds_read_b128 v[188:191], v167 offset:18432
	ds_read_b128 v[192:195], v167 offset:19456
	ds_read_b128 v[196:199], v167 offset:20480
	ds_read_b128 v[200:203], v167 offset:21504
	ds_read_b128 v[204:207], v167 offset:22528
	ds_read_b128 v[210:213], v167 offset:23552
	global_load_lds_dwordx4 v[160:161], off
	s_add_i32 m0, s65, 0x2000
	s_add_u32 s66, s40, 0x100000
	v_lshl_add_u64 v[214:215], s[40:41], 0, v[150:151]
	s_addc_u32 s67, s41, 0
	s_add_i32 s65, s61, s93
	global_load_lds_dwordx4 v[214:215], off
	v_lshl_add_u64 v[216:217], s[66:67], 0, v[146:147]
	s_mov_b32 m0, s65
	v_lshl_add_u64 v[218:219], s[42:43], 0, v[148:149]
	global_load_lds_dwordx4 v[216:217], off
	v_lshl_add_u64 v[216:217], s[66:67], 0, v[150:151]
	s_add_i32 m0, s65, 0x2000
	s_nop 0
	global_load_lds_dwordx4 v[216:217], off
	v_lshl_add_u64 v[216:217], s[42:43], 0, v[144:145]
	s_mov_b32 m0, s47
	s_nop 0
	global_load_lds_dwordx4 v[216:217], off
	s_mov_b32 m0, s48
	s_nop 0
	global_load_lds_dwordx4 v[218:219], off
	s_waitcnt vmcnt(8)
	s_waitcnt lgkmcnt(0)
	s_barrier
	s_setprio 1
	s_waitcnt lgkmcnt(0)
	v_mfma_f32_16x16x32_bf16 v[76:79], v[32:35], v[180:183], v[76:79]
	v_mfma_f32_16x16x32_bf16 v[72:75], v[48:51], v[180:183], v[72:75]
	v_mfma_f32_16x16x32_bf16 v[60:63], v[32:35], v[188:191], v[60:63]
	v_mfma_f32_16x16x32_bf16 v[56:59], v[48:51], v[188:191], v[56:59]
	v_mfma_f32_16x16x32_bf16 v[28:31], v[32:35], v[196:199], v[28:31]
	v_mfma_f32_16x16x32_bf16 v[24:27], v[48:51], v[196:199], v[24:27]
	v_mfma_f32_16x16x32_bf16 v[12:15], v[32:35], v[204:207], v[12:15]
	v_mfma_f32_16x16x32_bf16 v[8:11], v[48:51], v[204:207], v[8:11]
	v_mfma_f32_16x16x32_bf16 v[76:79], v[36:39], v[184:187], v[76:79]
	v_mfma_f32_16x16x32_bf16 v[72:75], v[52:55], v[184:187], v[72:75]
	v_mfma_f32_16x16x32_bf16 v[60:63], v[36:39], v[192:195], v[60:63]
	v_mfma_f32_16x16x32_bf16 v[56:59], v[52:55], v[192:195], v[56:59]
	v_mfma_f32_16x16x32_bf16 v[28:31], v[36:39], v[200:203], v[28:31]
	v_mfma_f32_16x16x32_bf16 v[24:27], v[52:55], v[200:203], v[24:27]
	v_mfma_f32_16x16x32_bf16 v[12:15], v[36:39], v[210:213], v[12:15]
	v_mfma_f32_16x16x32_bf16 v[8:11], v[52:55], v[210:213], v[8:11]
	v_mfma_f32_16x16x32_bf16 v[44:47], v[156:159], v[188:191], v[44:47]
	v_mfma_f32_16x16x32_bf16 v[40:43], v[172:175], v[188:191], v[40:43]
	v_mfma_f32_16x16x32_bf16 v[20:23], v[156:159], v[196:199], v[20:23]
	v_mfma_f32_16x16x32_bf16 v[16:19], v[172:175], v[196:199], v[16:19]
	v_mfma_f32_16x16x32_bf16 v[4:7], v[156:159], v[204:207], v[4:7]
	v_mfma_f32_16x16x32_bf16 v[0:3], v[172:175], v[204:207], v[0:3]
	v_mfma_f32_16x16x32_bf16 v[32:35], v[156:159], v[180:183], v[68:71]
	v_mfma_f32_16x16x32_bf16 v[36:39], v[172:175], v[180:183], v[64:67]
	v_mfma_f32_16x16x32_bf16 v[44:47], v[168:171], v[192:195], v[44:47]
	v_mfma_f32_16x16x32_bf16 v[40:43], v[176:179], v[192:195], v[40:43]
	v_mfma_f32_16x16x32_bf16 v[20:23], v[168:171], v[200:203], v[20:23]
	v_mfma_f32_16x16x32_bf16 v[16:19], v[176:179], v[200:203], v[16:19]
	v_mfma_f32_16x16x32_bf16 v[4:7], v[168:171], v[210:213], v[4:7]
	v_mfma_f32_16x16x32_bf16 v[0:3], v[176:179], v[210:213], v[0:3]
	v_mfma_f32_16x16x32_bf16 v[32:35], v[168:171], v[184:187], v[32:35]
	v_mfma_f32_16x16x32_bf16 v[36:39], v[176:179], v[184:187], v[36:39]
	s_setprio 0
	s_barrier
	s_add_i32 s65, 0, 0x18000
	s_add_i32 s66, 0, 0x1c000
	v_add_u32_e32 v68, s65, v163
	v_add_u32_e32 v176, s66, v163
	ds_read_b128 v[48:51], v68
	ds_read_b128 v[52:55], v68 offset:1024
	ds_read_b128 v[64:67], v68 offset:2048
	ds_read_b128 v[68:71], v68 offset:3072
	ds_read_b128 v[156:159], v176
	ds_read_b128 v[168:171], v176 offset:1024
	ds_read_b128 v[172:175], v176 offset:2048
	ds_read_b128 v[176:179], v176 offset:3072
	s_add_u32 s42, s42, 0x80000
	s_addc_u32 s43, s43, 0
	s_mov_b32 m0, s49
	v_lshl_add_u64 v[220:221], s[42:43], 0, v[144:145]
	ds_read_b128 v[180:183], v167 offset:32768
	ds_read_b128 v[184:187], v167 offset:33792
	ds_read_b128 v[188:191], v167 offset:34816
	ds_read_b128 v[192:195], v167 offset:35840
	ds_read_b128 v[196:199], v167 offset:36864
	ds_read_b128 v[200:203], v167 offset:37888
	ds_read_b128 v[204:207], v167 offset:38912
	ds_read_b128 v[210:213], v167 offset:39936
	global_load_lds_dwordx4 v[220:221], off
	v_lshl_add_u64 v[220:221], s[42:43], 0, v[148:149]
	s_mov_b32 m0, s50
	s_nop 0
	global_load_lds_dwordx4 v[220:221], off
	s_waitcnt vmcnt(8)
	s_waitcnt lgkmcnt(0)
	s_barrier
	s_setprio 1
	s_waitcnt lgkmcnt(0)
	v_mfma_f32_16x16x32_bf16 v[140:143], v[48:51], v[180:183], v[140:143]
	v_mfma_f32_16x16x32_bf16 v[136:139], v[64:67], v[180:183], v[136:139]
	v_mfma_f32_16x16x32_bf16 v[124:127], v[48:51], v[188:191], v[124:127]
	v_mfma_f32_16x16x32_bf16 v[120:123], v[64:67], v[188:191], v[120:123]
	v_mfma_f32_16x16x32_bf16 v[108:111], v[48:51], v[196:199], v[108:111]
	v_mfma_f32_16x16x32_bf16 v[104:107], v[64:67], v[196:199], v[104:107]
	v_mfma_f32_16x16x32_bf16 v[92:95], v[48:51], v[204:207], v[92:95]
	v_mfma_f32_16x16x32_bf16 v[88:91], v[64:67], v[204:207], v[88:91]
	v_mfma_f32_16x16x32_bf16 v[140:143], v[52:55], v[184:187], v[140:143]
	v_mfma_f32_16x16x32_bf16 v[136:139], v[68:71], v[184:187], v[136:139]
	v_mfma_f32_16x16x32_bf16 v[124:127], v[52:55], v[192:195], v[124:127]
	v_mfma_f32_16x16x32_bf16 v[120:123], v[68:71], v[192:195], v[120:123]
	v_mfma_f32_16x16x32_bf16 v[108:111], v[52:55], v[200:203], v[108:111]
	v_mfma_f32_16x16x32_bf16 v[104:107], v[68:71], v[200:203], v[104:107]
	v_mfma_f32_16x16x32_bf16 v[92:95], v[52:55], v[210:213], v[92:95]
	v_mfma_f32_16x16x32_bf16 v[88:91], v[68:71], v[210:213], v[88:91]
	v_mfma_f32_16x16x32_bf16 v[132:135], v[156:159], v[180:183], v[132:135]
	v_mfma_f32_16x16x32_bf16 v[128:131], v[172:175], v[180:183], v[128:131]
	v_mfma_f32_16x16x32_bf16 v[116:119], v[156:159], v[188:191], v[116:119]
	v_mfma_f32_16x16x32_bf16 v[112:115], v[172:175], v[188:191], v[112:115]
	v_mfma_f32_16x16x32_bf16 v[100:103], v[156:159], v[196:199], v[100:103]
	v_mfma_f32_16x16x32_bf16 v[96:99], v[172:175], v[196:199], v[96:99]
	v_mfma_f32_16x16x32_bf16 v[84:87], v[156:159], v[204:207], v[84:87]
	v_mfma_f32_16x16x32_bf16 v[80:83], v[172:175], v[204:207], v[80:83]
	v_mfma_f32_16x16x32_bf16 v[132:135], v[168:171], v[184:187], v[132:135]
	v_mfma_f32_16x16x32_bf16 v[128:131], v[176:179], v[184:187], v[128:131]
	v_mfma_f32_16x16x32_bf16 v[116:119], v[168:171], v[192:195], v[116:119]
	v_mfma_f32_16x16x32_bf16 v[112:115], v[176:179], v[192:195], v[112:115]
	v_mfma_f32_16x16x32_bf16 v[100:103], v[168:171], v[200:203], v[100:103]
	v_mfma_f32_16x16x32_bf16 v[96:99], v[176:179], v[200:203], v[96:99]
	v_mfma_f32_16x16x32_bf16 v[84:87], v[168:171], v[210:213], v[84:87]
	v_mfma_f32_16x16x32_bf16 v[80:83], v[176:179], v[210:213], v[80:83]
	s_setprio 0
	s_barrier
	s_add_i32 s42, s65, s93
	v_lshl_add_u64 v[160:161], v[160:161], 0, s[22:23]
	s_mov_b32 m0, s42
	ds_read_b128 v[180:183], v167 offset:49152
	ds_read_b128 v[184:187], v167 offset:50176
	ds_read_b128 v[188:191], v167 offset:51200
	ds_read_b128 v[192:195], v167 offset:52224
	ds_read_b128 v[196:199], v167 offset:53248
	ds_read_b128 v[200:203], v167 offset:54272
	ds_read_b128 v[204:207], v167 offset:55296
	ds_read_b128 v[210:213], v167 offset:56320
	global_load_lds_dwordx4 v[160:161], off
	s_add_i32 m0, s42, 0x2000
	s_add_u32 s40, s40, 0x100080
	v_lshl_add_u64 v[160:161], v[214:215], 0, s[22:23]
	s_addc_u32 s41, s41, 0
	s_add_i32 s42, s66, s93
	global_load_lds_dwordx4 v[160:161], off
	v_lshl_add_u64 v[160:161], s[40:41], 0, v[146:147]
	s_mov_b32 m0, s42
	s_nop 0
	global_load_lds_dwordx4 v[160:161], off
	v_lshl_add_u64 v[160:161], s[40:41], 0, v[150:151]
	s_add_i32 m0, s42, 0x2000
	s_nop 0
	global_load_lds_dwordx4 v[160:161], off
	v_lshl_add_u64 v[160:161], v[216:217], 0, s[22:23]
	s_mov_b32 m0, s51
	s_nop 0
	global_load_lds_dwordx4 v[160:161], off
	v_lshl_add_u64 v[160:161], v[218:219], 0, s[22:23]
	s_mov_b32 m0, s58
	s_nop 0
	global_load_lds_dwordx4 v[160:161], off
	s_waitcnt vmcnt(8)
	s_waitcnt lgkmcnt(0)
	s_barrier
	s_setprio 1
	s_waitcnt lgkmcnt(0)
	v_mfma_f32_16x16x32_bf16 v[76:79], v[48:51], v[180:183], v[76:79]
	v_mfma_f32_16x16x32_bf16 v[72:75], v[64:67], v[180:183], v[72:75]
	v_mfma_f32_16x16x32_bf16 v[60:63], v[48:51], v[188:191], v[60:63]
	v_mfma_f32_16x16x32_bf16 v[56:59], v[64:67], v[188:191], v[56:59]
	v_mfma_f32_16x16x32_bf16 v[28:31], v[48:51], v[196:199], v[28:31]
	v_mfma_f32_16x16x32_bf16 v[24:27], v[64:67], v[196:199], v[24:27]
	v_mfma_f32_16x16x32_bf16 v[12:15], v[48:51], v[204:207], v[12:15]
	v_mfma_f32_16x16x32_bf16 v[8:11], v[64:67], v[204:207], v[8:11]
	v_mfma_f32_16x16x32_bf16 v[76:79], v[52:55], v[184:187], v[76:79]
	v_mfma_f32_16x16x32_bf16 v[72:75], v[68:71], v[184:187], v[72:75]
	v_mfma_f32_16x16x32_bf16 v[60:63], v[52:55], v[192:195], v[60:63]
	v_mfma_f32_16x16x32_bf16 v[56:59], v[68:71], v[192:195], v[56:59]
	v_mfma_f32_16x16x32_bf16 v[28:31], v[52:55], v[200:203], v[28:31]
	v_mfma_f32_16x16x32_bf16 v[24:27], v[68:71], v[200:203], v[24:27]
	v_mfma_f32_16x16x32_bf16 v[12:15], v[52:55], v[210:213], v[12:15]
	v_mfma_f32_16x16x32_bf16 v[8:11], v[68:71], v[210:213], v[8:11]
	v_mfma_f32_16x16x32_bf16 v[32:35], v[156:159], v[180:183], v[32:35]
	v_mfma_f32_16x16x32_bf16 v[68:71], v[168:171], v[184:187], v[32:35]
	v_mfma_f32_16x16x32_bf16 v[32:35], v[172:175], v[180:183], v[36:39]
	v_mfma_f32_16x16x32_bf16 v[64:67], v[176:179], v[184:187], v[32:35]
	v_mfma_f32_16x16x32_bf16 v[32:35], v[156:159], v[188:191], v[44:47]
	v_mfma_f32_16x16x32_bf16 v[44:47], v[168:171], v[192:195], v[32:35]
	v_mfma_f32_16x16x32_bf16 v[32:35], v[172:175], v[188:191], v[40:43]
	v_mfma_f32_16x16x32_bf16 v[20:23], v[156:159], v[196:199], v[20:23]
	v_mfma_f32_16x16x32_bf16 v[16:19], v[172:175], v[196:199], v[16:19]
	v_mfma_f32_16x16x32_bf16 v[4:7], v[156:159], v[204:207], v[4:7]
	v_mfma_f32_16x16x32_bf16 v[0:3], v[172:175], v[204:207], v[0:3]
	v_mfma_f32_16x16x32_bf16 v[40:43], v[176:179], v[192:195], v[32:35]
	v_mfma_f32_16x16x32_bf16 v[20:23], v[168:171], v[200:203], v[20:23]
	v_mfma_f32_16x16x32_bf16 v[16:19], v[176:179], v[200:203], v[16:19]
	v_mfma_f32_16x16x32_bf16 v[4:7], v[168:171], v[210:213], v[4:7]
	v_mfma_f32_16x16x32_bf16 v[0:3], v[176:179], v[210:213], v[0:3]
	s_setprio 0
	s_barrier
	s_add_i32 s64, s64, 2
	s_add_u32 s38, s38, 0x100
	s_addc_u32 s39, s39, 0
	s_add_u32 s33, s33, 0x100
	s_addc_u32 s63, s63, 0
	s_cmp_gt_u32 s64, 61
	s_cbranch_scc0 .LBB0_424
	s_and_b64 vcc, exec, s[24:25]
	s_cbranch_vccz .LBB0_427
	s_barrier

.LBB0_562:
	s_ashr_i32 s31, s30, 31
	s_lshl_b64 s[2:3], s[30:31], 17
	s_add_u32 s34, s4, s2
	s_addc_u32 s35, s5, s3
	ds_read_b128 v[0:3], v75
	ds_read_b128 v[4:7], v75 offset:1024
	ds_read_b128 v[8:11], v75 offset:2048
	ds_read_b128 v[12:15], v75 offset:3072
	s_and_b64 s[2:3], s[26:27], exec
	s_cselect_b32 s43, s35, s39
	s_cselect_b32 s42, s34, s38
	s_ashr_i32 s29, s28, 31
	s_lshl_b64 s[2:3], s[28:29], 17
	s_add_u32 s36, s8, s2
	s_addc_u32 s37, s9, s3
	s_and_b64 s[2:3], s[26:27], exec
	s_cselect_b32 s41, s37, s45
	s_cselect_b32 s40, s36, s44
	s_add_u32 s2, s38, 0x10080
	s_addc_u32 s3, s39, 0
	s_mov_b32 m0, s57
	v_lshl_add_u64 v[48:49], s[2:3], 0, v[64:65]
	ds_read_b128 v[16:19], v76
	ds_read_b128 v[20:23], v76 offset:1024
	ds_read_b128 v[24:27], v76 offset:2048
	ds_read_b128 v[28:31], v76 offset:3072
	ds_read_b128 v[32:35], v76 offset:4096
	ds_read_b128 v[36:39], v76 offset:5120
	ds_read_b128 v[40:43], v76 offset:6144
	ds_read_b128 v[44:47], v76 offset:7168
	global_load_lds_dwordx4 v[48:49], off
	v_lshl_add_u64 v[48:49], s[2:3], 0, v[68:69]
	s_mov_b32 m0, s59
	s_nop 0
	global_load_lds_dwordx4 v[48:49], off
	s_waitcnt vmcnt(8)
	s_waitcnt lgkmcnt(0)
	s_barrier
	s_setprio 1
	s_waitcnt lgkmcnt(0)
	v_mfma_f32_16x16x32_bf16 v[48:51], v[0:3], v[16:19], 0
	v_mfma_f32_16x16x32_bf16 v[16:19], v[8:11], v[16:19], 0
	v_mfma_f32_16x16x32_bf16 v[48:51], v[4:7], v[20:23], v[48:51]
	v_mfma_f32_16x16x32_bf16 v[16:19], v[12:15], v[20:23], v[16:19]
	v_mfma_f32_16x16x32_bf16 v[20:23], v[0:3], v[24:27], 0
	v_mfma_f32_16x16x32_bf16 v[24:27], v[8:11], v[24:27], 0
	v_mfma_f32_16x16x32_bf16 v[20:23], v[4:7], v[28:31], v[20:23]
	v_mfma_f32_16x16x32_bf16 v[24:27], v[12:15], v[28:31], v[24:27]
	v_mfma_f32_16x16x32_bf16 v[28:31], v[0:3], v[32:35], 0
	v_mfma_f32_16x16x32_bf16 v[32:35], v[8:11], v[32:35], 0
	v_mfma_f32_16x16x32_bf16 v[28:31], v[4:7], v[36:39], v[28:31]
	v_mfma_f32_16x16x32_bf16 v[32:35], v[12:15], v[36:39], v[32:35]
	v_mfma_f32_16x16x32_bf16 v[36:39], v[0:3], v[40:43], 0
	v_mfma_f32_16x16x32_bf16 v[40:43], v[8:11], v[40:43], 0
	v_mfma_f32_16x16x32_bf16 v[36:39], v[4:7], v[44:47], v[36:39]
	v_mfma_f32_16x16x32_bf16 v[40:43], v[12:15], v[44:47], v[40:43]
	s_setprio 0
	s_barrier
	v_lshl_add_u64 v[126:127], s[44:45], 0, v[66:67]
	s_mov_b32 m0, s60
	v_lshl_add_u64 v[94:95], v[126:127], 0, s[22:23]
	v_lshl_add_u64 v[128:129], s[44:45], 0, v[70:71]
	s_add_u32 s2, s44, 0x10100
	ds_read_b128 v[44:47], v76 offset:16384
	ds_read_b128 v[52:55], v76 offset:17408
	ds_read_b128 v[56:59], v76 offset:18432
	ds_read_b128 v[60:63], v76 offset:19456
	ds_read_b128 v[78:81], v76 offset:20480
	ds_read_b128 v[82:85], v76 offset:21504
	ds_read_b128 v[86:89], v76 offset:22528
	ds_read_b128 v[90:93], v76 offset:23552
	global_load_lds_dwordx4 v[94:95], off
	v_lshl_add_u64 v[94:95], v[128:129], 0, s[22:23]
	s_mov_b32 m0, s61
	s_addc_u32 s3, s45, 0
	global_load_lds_dwordx4 v[94:95], off
	v_lshl_add_u64 v[94:95], s[2:3], 0, v[66:67]
	s_mov_b32 m0, s33
	v_lshl_add_u64 v[130:131], s[38:39], 0, v[64:65]
	global_load_lds_dwordx4 v[94:95], off
	v_lshl_add_u64 v[94:95], s[2:3], 0, v[70:71]
	s_mov_b32 m0, s46
	v_lshl_add_u64 v[132:133], s[38:39], 0, v[68:69]
	global_load_lds_dwordx4 v[94:95], off
	v_lshl_add_u64 v[94:95], v[130:131], 0, s[22:23]
	s_mov_b32 m0, s11
	s_nop 0
	global_load_lds_dwordx4 v[94:95], off
	v_lshl_add_u64 v[94:95], v[132:133], 0, s[22:23]
	s_mov_b32 m0, s47
	s_nop 0
	global_load_lds_dwordx4 v[94:95], off
	s_waitcnt vmcnt(8)
	s_waitcnt lgkmcnt(0)
	s_barrier
	s_setprio 1
	s_waitcnt lgkmcnt(0)
	v_mfma_f32_16x16x32_bf16 v[94:97], v[0:3], v[44:47], 0
	v_mfma_f32_16x16x32_bf16 v[44:47], v[8:11], v[44:47], 0
	v_mfma_f32_16x16x32_bf16 v[94:97], v[4:7], v[52:55], v[94:97]
	v_mfma_f32_16x16x32_bf16 v[44:47], v[12:15], v[52:55], v[44:47]
	v_mfma_f32_16x16x32_bf16 v[52:55], v[0:3], v[56:59], 0
	v_mfma_f32_16x16x32_bf16 v[56:59], v[8:11], v[56:59], 0
	v_mfma_f32_16x16x32_bf16 v[52:55], v[4:7], v[60:63], v[52:55]
	v_mfma_f32_16x16x32_bf16 v[56:59], v[12:15], v[60:63], v[56:59]
	v_mfma_f32_16x16x32_bf16 v[60:63], v[0:3], v[78:81], 0
	v_mfma_f32_16x16x32_bf16 v[0:3], v[0:3], v[86:89], 0
	v_mfma_f32_16x16x32_bf16 v[60:63], v[4:7], v[82:85], v[60:63]
	v_mfma_f32_16x16x32_bf16 v[0:3], v[4:7], v[90:93], v[0:3]
	v_mfma_f32_16x16x32_bf16 v[4:7], v[8:11], v[86:89], 0
	v_mfma_f32_16x16x32_bf16 v[78:81], v[8:11], v[78:81], 0
	v_mfma_f32_16x16x32_bf16 v[4:7], v[12:15], v[90:93], v[4:7]
	v_mfma_f32_16x16x32_bf16 v[78:81], v[12:15], v[82:85], v[78:81]
	s_setprio 0
	s_barrier
	ds_read_b128 v[8:11], v77
	ds_read_b128 v[12:15], v77 offset:1024
	ds_read_b128 v[82:85], v77 offset:2048
	ds_read_b128 v[86:89], v77 offset:3072
	s_add_u32 s2, s38, 0x10100
	s_addc_u32 s3, s39, 0
	s_mov_b32 m0, s48
	v_lshl_add_u64 v[134:135], s[2:3], 0, v[64:65]
	ds_read_b128 v[90:93], v76 offset:32768
	ds_read_b128 v[98:101], v76 offset:33792
	ds_read_b128 v[102:105], v76 offset:34816
	ds_read_b128 v[106:109], v76 offset:35840
	ds_read_b128 v[110:113], v76 offset:36864
	ds_read_b128 v[114:117], v76 offset:37888
	ds_read_b128 v[118:121], v76 offset:38912
	ds_read_b128 v[122:125], v76 offset:39936
	global_load_lds_dwordx4 v[134:135], off
	v_lshl_add_u64 v[134:135], s[2:3], 0, v[68:69]
	s_mov_b32 m0, s49
	s_nop 0
	global_load_lds_dwordx4 v[134:135], off
	s_waitcnt vmcnt(8)
	s_waitcnt lgkmcnt(0)
	s_barrier
	s_setprio 1
	s_waitcnt lgkmcnt(0)
	v_mfma_f32_16x16x32_bf16 v[48:51], v[8:11], v[90:93], v[48:51]
	v_mfma_f32_16x16x32_bf16 v[16:19], v[82:85], v[90:93], v[16:19]
	v_mfma_f32_16x16x32_bf16 v[20:23], v[8:11], v[102:105], v[20:23]
	v_mfma_f32_16x16x32_bf16 v[24:27], v[82:85], v[102:105], v[24:27]
	v_mfma_f32_16x16x32_bf16 v[28:31], v[8:11], v[110:113], v[28:31]
	v_mfma_f32_16x16x32_bf16 v[32:35], v[82:85], v[110:113], v[32:35]
	v_mfma_f32_16x16x32_bf16 v[36:39], v[8:11], v[118:121], v[36:39]
	v_mfma_f32_16x16x32_bf16 v[40:43], v[82:85], v[118:121], v[40:43]
	v_mfma_f32_16x16x32_bf16 v[48:51], v[12:15], v[98:101], v[48:51]
	v_mfma_f32_16x16x32_bf16 v[16:19], v[86:89], v[98:101], v[16:19]
	v_mfma_f32_16x16x32_bf16 v[20:23], v[12:15], v[106:109], v[20:23]
	v_mfma_f32_16x16x32_bf16 v[24:27], v[86:89], v[106:109], v[24:27]
	v_mfma_f32_16x16x32_bf16 v[28:31], v[12:15], v[114:117], v[28:31]
	v_mfma_f32_16x16x32_bf16 v[32:35], v[86:89], v[114:117], v[32:35]
	v_mfma_f32_16x16x32_bf16 v[36:39], v[12:15], v[122:125], v[36:39]
	v_mfma_f32_16x16x32_bf16 v[40:43], v[86:89], v[122:125], v[40:43]
	s_setprio 0
	s_barrier
	s_mov_b32 m0, s62
	v_lshl_add_u64 v[126:127], v[126:127], 0, s[24:25]
	s_add_u32 s2, s44, 0x10180
	ds_read_b128 v[90:93], v76 offset:49152
	ds_read_b128 v[98:101], v76 offset:50176
	ds_read_b128 v[102:105], v76 offset:51200
	ds_read_b128 v[106:109], v76 offset:52224
	ds_read_b128 v[110:113], v76 offset:53248
	ds_read_b128 v[114:117], v76 offset:54272
	ds_read_b128 v[118:121], v76 offset:55296
	ds_read_b128 v[122:125], v76 offset:56320
	global_load_lds_dwordx4 v[126:127], off
	v_lshl_add_u64 v[126:127], v[128:129], 0, s[24:25]
	s_mov_b32 m0, s63
	s_addc_u32 s3, s45, 0
	global_load_lds_dwordx4 v[126:127], off
	v_lshl_add_u64 v[126:127], s[2:3], 0, v[66:67]
	s_mov_b32 m0, s54
	s_nop 0
	global_load_lds_dwordx4 v[126:127], off
	v_lshl_add_u64 v[126:127], s[2:3], 0, v[70:71]
	s_mov_b32 m0, s55
	s_nop 0
	global_load_lds_dwordx4 v[126:127], off
	v_lshl_add_u64 v[126:127], v[130:131], 0, s[24:25]
	s_mov_b32 m0, s50
	s_nop 0
	global_load_lds_dwordx4 v[126:127], off
	v_lshl_add_u64 v[126:127], v[132:133], 0, s[24:25]
	s_mov_b32 m0, s51
	s_nop 0
	global_load_lds_dwordx4 v[126:127], off
	s_waitcnt vmcnt(8)
	s_waitcnt lgkmcnt(0)
	s_barrier
	s_setprio 1
	s_waitcnt lgkmcnt(0)
	v_mfma_f32_16x16x32_bf16 v[44:47], v[82:85], v[90:93], v[44:47]
	v_mfma_f32_16x16x32_bf16 v[52:55], v[8:11], v[102:105], v[52:55]
	v_mfma_f32_16x16x32_bf16 v[56:59], v[82:85], v[102:105], v[56:59]
	v_mfma_f32_16x16x32_bf16 v[60:63], v[8:11], v[110:113], v[60:63]
	v_mfma_f32_16x16x32_bf16 v[0:3], v[8:11], v[118:121], v[0:3]
	v_mfma_f32_16x16x32_bf16 v[4:7], v[82:85], v[118:121], v[4:7]
	v_mfma_f32_16x16x32_bf16 v[94:97], v[8:11], v[90:93], v[94:97]
	v_mfma_f32_16x16x32_bf16 v[44:47], v[86:89], v[98:101], v[44:47]
	v_mfma_f32_16x16x32_bf16 v[52:55], v[12:15], v[106:109], v[52:55]
	v_mfma_f32_16x16x32_bf16 v[56:59], v[86:89], v[106:109], v[56:59]
	v_mfma_f32_16x16x32_bf16 v[60:63], v[12:15], v[114:117], v[60:63]
	v_mfma_f32_16x16x32_bf16 v[78:81], v[82:85], v[110:113], v[78:81]
	v_mfma_f32_16x16x32_bf16 v[0:3], v[12:15], v[122:125], v[0:3]
	v_mfma_f32_16x16x32_bf16 v[4:7], v[86:89], v[122:125], v[4:7]
	v_mfma_f32_16x16x32_bf16 v[94:97], v[12:15], v[98:101], v[94:97]
	v_mfma_f32_16x16x32_bf16 v[78:81], v[86:89], v[114:117], v[78:81]
	s_setprio 0
	s_barrier
	ds_read_b128 v[8:11], v75
	ds_read_b128 v[12:15], v75 offset:1024
	ds_read_b128 v[82:85], v75 offset:2048
	ds_read_b128 v[86:89], v75 offset:3072
	s_add_u32 s2, s38, 0x10180
	s_addc_u32 s3, s39, 0
	s_mov_b32 m0, s57
	v_lshl_add_u64 v[126:127], s[2:3], 0, v[64:65]
	ds_read_b128 v[90:93], v76
	ds_read_b128 v[98:101], v76 offset:1024
	ds_read_b128 v[102:105], v76 offset:2048
	ds_read_b128 v[106:109], v76 offset:3072
	ds_read_b128 v[110:113], v76 offset:4096
	ds_read_b128 v[114:117], v76 offset:5120
	ds_read_b128 v[118:121], v76 offset:6144
	ds_read_b128 v[122:125], v76 offset:7168
	global_load_lds_dwordx4 v[126:127], off
	v_lshl_add_u64 v[126:127], s[2:3], 0, v[68:69]
	s_mov_b32 m0, s59
	s_nop 0
	global_load_lds_dwordx4 v[126:127], off
	s_waitcnt vmcnt(8)
	s_waitcnt lgkmcnt(0)
	s_barrier
	s_setprio 1
	s_waitcnt lgkmcnt(0)
	v_mfma_f32_16x16x32_bf16 v[48:51], v[8:11], v[90:93], v[48:51]
	v_mfma_f32_16x16x32_bf16 v[16:19], v[82:85], v[90:93], v[16:19]
	v_mfma_f32_16x16x32_bf16 v[20:23], v[8:11], v[102:105], v[20:23]
	v_mfma_f32_16x16x32_bf16 v[24:27], v[82:85], v[102:105], v[24:27]
	v_mfma_f32_16x16x32_bf16 v[28:31], v[8:11], v[110:113], v[28:31]
	v_mfma_f32_16x16x32_bf16 v[32:35], v[82:85], v[110:113], v[32:35]
	v_mfma_f32_16x16x32_bf16 v[36:39], v[8:11], v[118:121], v[36:39]
	v_mfma_f32_16x16x32_bf16 v[48:51], v[12:15], v[98:101], v[48:51]
	v_mfma_f32_16x16x32_bf16 v[16:19], v[86:89], v[98:101], v[16:19]
	v_mfma_f32_16x16x32_bf16 v[20:23], v[12:15], v[106:109], v[20:23]
	v_mfma_f32_16x16x32_bf16 v[24:27], v[86:89], v[106:109], v[24:27]
	v_mfma_f32_16x16x32_bf16 v[28:31], v[12:15], v[114:117], v[28:31]
	v_mfma_f32_16x16x32_bf16 v[32:35], v[86:89], v[114:117], v[32:35]
	v_mfma_f32_16x16x32_bf16 v[36:39], v[12:15], v[122:125], v[36:39]
	v_mfma_f32_16x16x32_bf16 v[40:43], v[82:85], v[118:121], v[40:43]
	v_mfma_f32_16x16x32_bf16 v[90:93], v[86:89], v[122:125], v[40:43]
	s_setprio 0
	s_barrier
	s_mov_b32 m0, s60
	v_lshl_add_u64 v[138:139], s[40:41], 0, v[66:67]
	s_add_u32 s2, s40, 0x10000
	ds_read_b128 v[40:43], v76 offset:16384
	ds_read_b128 v[98:101], v76 offset:17408
	ds_read_b128 v[102:105], v76 offset:18432
	ds_read_b128 v[106:109], v76 offset:19456
	ds_read_b128 v[110:113], v76 offset:20480
	ds_read_b128 v[114:117], v76 offset:21504
	ds_read_b128 v[118:121], v76 offset:22528
	ds_read_b128 v[122:125], v76 offset:23552
	global_load_lds_dwordx4 v[138:139], off
	v_lshl_add_u64 v[140:141], s[40:41], 0, v[70:71]
	s_mov_b32 m0, s61
	s_addc_u32 s3, s41, 0
	global_load_lds_dwordx4 v[140:141], off
	v_lshl_add_u64 v[126:127], s[2:3], 0, v[66:67]
	s_mov_b32 m0, s33
	v_lshl_add_u64 v[142:143], s[42:43], 0, v[64:65]
	global_load_lds_dwordx4 v[126:127], off
	v_lshl_add_u64 v[126:127], s[2:3], 0, v[70:71]
	s_mov_b32 m0, s46
	v_lshl_add_u64 v[144:145], s[42:43], 0, v[68:69]
	global_load_lds_dwordx4 v[126:127], off
	s_mov_b32 m0, s11
	s_nop 0
	global_load_lds_dwordx4 v[142:143], off
	s_mov_b32 m0, s47
	s_nop 0
	global_load_lds_dwordx4 v[144:145], off
	s_waitcnt vmcnt(8)
	s_waitcnt lgkmcnt(0)
	s_barrier
	s_setprio 1
	s_waitcnt lgkmcnt(0)
	v_mfma_f32_16x16x32_bf16 v[94:97], v[8:11], v[40:43], v[94:97]
	v_mfma_f32_16x16x32_bf16 v[40:43], v[82:85], v[40:43], v[44:47]
	v_mfma_f32_16x16x32_bf16 v[94:97], v[12:15], v[98:101], v[94:97]
	v_mfma_f32_16x16x32_bf16 v[98:101], v[86:89], v[98:101], v[40:43]
	v_mfma_f32_16x16x32_bf16 v[40:43], v[8:11], v[102:105], v[52:55]
	v_mfma_f32_16x16x32_bf16 v[126:129], v[12:15], v[106:109], v[40:43]
	v_mfma_f32_16x16x32_bf16 v[40:43], v[82:85], v[102:105], v[56:59]
	v_mfma_f32_16x16x32_bf16 v[102:105], v[86:89], v[106:109], v[40:43]
	v_mfma_f32_16x16x32_bf16 v[40:43], v[8:11], v[110:113], v[60:63]
	v_mfma_f32_16x16x32_bf16 v[0:3], v[8:11], v[118:121], v[0:3]
	v_mfma_f32_16x16x32_bf16 v[106:109], v[12:15], v[114:117], v[40:43]
	v_mfma_f32_16x16x32_bf16 v[40:43], v[82:85], v[110:113], v[78:81]
	v_mfma_f32_16x16x32_bf16 v[0:3], v[12:15], v[122:125], v[0:3]
	v_mfma_f32_16x16x32_bf16 v[4:7], v[82:85], v[118:121], v[4:7]
	v_mfma_f32_16x16x32_bf16 v[78:81], v[86:89], v[114:117], v[40:43]
	v_mfma_f32_16x16x32_bf16 v[82:85], v[86:89], v[122:125], v[4:7]
	s_setprio 0
	s_barrier
	s_nop 1
	ds_read_b128 v[4:7], v77
	ds_read_b128 v[86:89], v77 offset:1024
	ds_read_b128 v[110:113], v77 offset:2048
	ds_read_b128 v[114:117], v77 offset:3072
	s_add_u32 s2, s42, 0x10000
	s_addc_u32 s3, s43, 0
	s_mov_b32 m0, s48
	v_lshl_add_u64 v[52:53], s[2:3], 0, v[64:65]
	ds_read_b128 v[8:11], v76 offset:32768
	ds_read_b128 v[12:15], v76 offset:33792
	ds_read_b128 v[40:43], v76 offset:34816
	ds_read_b128 v[44:47], v76 offset:35840
	ds_read_b128 v[118:121], v76 offset:36864
	ds_read_b128 v[122:125], v76 offset:37888
	ds_read_b128 v[130:133], v76 offset:38912
	ds_read_b128 v[134:137], v76 offset:39936
	global_load_lds_dwordx4 v[52:53], off
	v_lshl_add_u64 v[52:53], s[2:3], 0, v[68:69]
	s_mov_b32 m0, s49
	s_nop 0
	global_load_lds_dwordx4 v[52:53], off
	s_waitcnt vmcnt(8)
	s_waitcnt lgkmcnt(0)
	s_barrier
	s_setprio 1
	s_waitcnt lgkmcnt(0)
	v_mfma_f32_16x16x32_bf16 v[48:51], v[4:7], v[8:11], v[48:51]
	v_mfma_f32_16x16x32_bf16 v[8:11], v[110:113], v[8:11], v[16:19]
	v_mfma_f32_16x16x32_bf16 v[56:59], v[114:117], v[12:15], v[8:11]
	v_mfma_f32_16x16x32_bf16 v[8:11], v[4:7], v[40:43], v[20:23]
	v_mfma_f32_16x16x32_bf16 v[52:55], v[86:89], v[44:47], v[8:11]
	v_mfma_f32_16x16x32_bf16 v[8:11], v[110:113], v[40:43], v[24:27]
	v_mfma_f32_16x16x32_bf16 v[60:63], v[86:89], v[12:15], v[48:51]
	v_mfma_f32_16x16x32_bf16 v[48:51], v[114:117], v[44:47], v[8:11]
	v_mfma_f32_16x16x32_bf16 v[8:11], v[4:7], v[118:121], v[28:31]
	v_mfma_f32_16x16x32_bf16 v[40:43], v[86:89], v[122:125], v[8:11]
	v_mfma_f32_16x16x32_bf16 v[8:11], v[110:113], v[118:121], v[32:35]
	v_mfma_f32_16x16x32_bf16 v[32:35], v[114:117], v[122:125], v[8:11]
	v_mfma_f32_16x16x32_bf16 v[8:11], v[4:7], v[130:133], v[36:39]
	v_mfma_f32_16x16x32_bf16 v[20:23], v[86:89], v[134:137], v[8:11]
	v_mfma_f32_16x16x32_bf16 v[8:11], v[110:113], v[130:133], v[90:93]
	v_mfma_f32_16x16x32_bf16 v[16:19], v[114:117], v[134:137], v[8:11]
	s_setprio 0
	s_barrier
	s_mov_b32 m0, s62
	v_lshl_add_u64 v[28:29], v[138:139], 0, s[6:7]
	s_add_u32 s2, s40, 0x10080
	ds_read_b128 v[8:11], v76 offset:49152
	ds_read_b128 v[12:15], v76 offset:50176
	ds_read_b128 v[24:27], v76 offset:51200
	ds_read_b128 v[90:93], v76 offset:52224
	ds_read_b128 v[118:121], v76 offset:53248
	ds_read_b128 v[122:125], v76 offset:54272
	ds_read_b128 v[130:133], v76 offset:55296
	ds_read_b128 v[134:137], v76 offset:56320
	global_load_lds_dwordx4 v[28:29], off
	v_lshl_add_u64 v[28:29], v[140:141], 0, s[6:7]
	s_mov_b32 m0, s63
	s_addc_u32 s3, s41, 0
	global_load_lds_dwordx4 v[28:29], off
	v_lshl_add_u64 v[28:29], s[2:3], 0, v[66:67]
	s_mov_b32 m0, s54
	s_nop 0
	global_load_lds_dwordx4 v[28:29], off
	v_lshl_add_u64 v[28:29], s[2:3], 0, v[70:71]
	s_mov_b32 m0, s55
	s_nop 0
	global_load_lds_dwordx4 v[28:29], off
	v_lshl_add_u64 v[28:29], v[142:143], 0, s[6:7]
	s_mov_b32 m0, s50
	s_nop 0
	global_load_lds_dwordx4 v[28:29], off
	v_lshl_add_u64 v[28:29], v[144:145], 0, s[6:7]
	s_mov_b32 m0, s51
	s_nop 0
	global_load_lds_dwordx4 v[28:29], off
	s_waitcnt vmcnt(8)
	s_waitcnt lgkmcnt(0)
	s_barrier
	s_setprio 1
	s_waitcnt lgkmcnt(0)
	v_mfma_f32_16x16x32_bf16 v[28:31], v[4:7], v[8:11], v[94:97]
	v_mfma_f32_16x16x32_bf16 v[8:11], v[110:113], v[8:11], v[98:101]
	v_mfma_f32_16x16x32_bf16 v[36:39], v[114:117], v[12:15], v[8:11]
	v_mfma_f32_16x16x32_bf16 v[8:11], v[4:7], v[24:27], v[126:129]
	v_mfma_f32_16x16x32_bf16 v[44:47], v[86:89], v[12:15], v[28:31]
	v_mfma_f32_16x16x32_bf16 v[28:31], v[86:89], v[90:93], v[8:11]
	v_mfma_f32_16x16x32_bf16 v[8:11], v[110:113], v[24:27], v[102:105]
	v_mfma_f32_16x16x32_bf16 v[24:27], v[114:117], v[90:93], v[8:11]
	v_mfma_f32_16x16x32_bf16 v[8:11], v[4:7], v[118:121], v[106:109]
	v_mfma_f32_16x16x32_bf16 v[0:3], v[4:7], v[130:133], v[0:3]
	v_mfma_f32_16x16x32_bf16 v[12:15], v[86:89], v[122:125], v[8:11]
	v_mfma_f32_16x16x32_bf16 v[8:11], v[110:113], v[118:121], v[78:81]
	v_mfma_f32_16x16x32_bf16 v[4:7], v[86:89], v[134:137], v[0:3]
	v_mfma_f32_16x16x32_bf16 v[0:3], v[110:113], v[130:133], v[82:85]
	v_mfma_f32_16x16x32_bf16 v[8:11], v[114:117], v[122:125], v[8:11]
	v_mfma_f32_16x16x32_bf16 v[0:3], v[114:117], v[134:137], v[0:3]
	s_setprio 0
	s_barrier
	s_andn2_b64 vcc, exec, s[18:19]
	s_cbranch_vccnz .LBB0_564
	s_barrier

.LBB0_842:
	ds_read_b128 v[144:147], v153
	ds_read_b128 v[156:159], v153 offset:1024
	ds_read_b128 v[160:163], v153 offset:2048
	ds_read_b128 v[164:167], v153 offset:3072
	ds_read_b128 v[168:171], v154
	ds_read_b128 v[172:175], v154 offset:1024
	ds_read_b128 v[176:179], v154 offset:2048
	ds_read_b128 v[184:187], v154 offset:3072
	s_add_u32 s2, s0, 0x100
	s_addc_u32 s3, s1, 0
	s_cmp_eq_u32 s47, 12
	s_cselect_b32 s25, s21, s3
	s_cselect_b32 s24, s20, s2
	s_cselect_b32 s7, s19, s46
	s_cselect_b32 s6, s44, s45
	v_lshl_add_u64 v[148:149], s[0:1], 0, v[136:137]
	s_add_i32 m0, s27, 0xc000
	ds_read_b128 v[188:191], v155
	ds_read_b128 v[192:195], v155 offset:1024
	ds_read_b128 v[196:199], v155 offset:2048
	ds_read_b128 v[200:203], v155 offset:3072
	ds_read_b128 v[204:207], v155 offset:4096
	ds_read_b128 v[208:211], v155 offset:5120
	ds_read_b128 v[212:215], v155 offset:6144
	ds_read_b128 v[216:219], v155 offset:7168
	global_load_lds_dwordx4 v[148:149], off
	v_lshl_add_u64 v[148:149], s[0:1], 0, v[138:139]
	s_add_i32 m0, s27, 0xe000
	s_nop 0
	global_load_lds_dwordx4 v[148:149], off
	s_waitcnt vmcnt(8)
	s_waitcnt lgkmcnt(0)
	s_barrier
	s_setprio 1
	s_waitcnt lgkmcnt(0)
	v_mfma_f32_16x16x32_bf16 v[124:127], v[144:147], v[188:191], v[124:127]
	v_mfma_f32_16x16x32_bf16 v[120:123], v[160:163], v[188:191], v[120:123]
	v_mfma_f32_16x16x32_bf16 v[108:111], v[144:147], v[196:199], v[108:111]
	v_mfma_f32_16x16x32_bf16 v[104:107], v[160:163], v[196:199], v[104:107]
	v_mfma_f32_16x16x32_bf16 v[92:95], v[144:147], v[204:207], v[92:95]
	v_mfma_f32_16x16x32_bf16 v[88:91], v[160:163], v[204:207], v[88:91]
	v_mfma_f32_16x16x32_bf16 v[76:79], v[144:147], v[212:215], v[76:79]
	v_mfma_f32_16x16x32_bf16 v[72:75], v[160:163], v[212:215], v[72:75]
	v_mfma_f32_16x16x32_bf16 v[124:127], v[156:159], v[192:195], v[124:127]
	v_mfma_f32_16x16x32_bf16 v[120:123], v[164:167], v[192:195], v[120:123]
	v_mfma_f32_16x16x32_bf16 v[108:111], v[156:159], v[200:203], v[108:111]
	v_mfma_f32_16x16x32_bf16 v[104:107], v[164:167], v[200:203], v[104:107]
	v_mfma_f32_16x16x32_bf16 v[92:95], v[156:159], v[208:211], v[92:95]
	v_mfma_f32_16x16x32_bf16 v[88:91], v[164:167], v[208:211], v[88:91]
	v_mfma_f32_16x16x32_bf16 v[76:79], v[156:159], v[216:219], v[76:79]
	v_mfma_f32_16x16x32_bf16 v[72:75], v[164:167], v[216:219], v[72:75]
	v_mfma_f32_16x16x32_bf16 v[116:119], v[168:171], v[188:191], v[116:119]
	v_mfma_f32_16x16x32_bf16 v[112:115], v[176:179], v[188:191], v[112:115]
	v_mfma_f32_16x16x32_bf16 v[100:103], v[168:171], v[196:199], v[100:103]
	v_mfma_f32_16x16x32_bf16 v[96:99], v[176:179], v[196:199], v[96:99]
	v_mfma_f32_16x16x32_bf16 v[84:87], v[168:171], v[204:207], v[84:87]
	v_mfma_f32_16x16x32_bf16 v[80:83], v[176:179], v[204:207], v[80:83]
	v_mfma_f32_16x16x32_bf16 v[68:71], v[168:171], v[212:215], v[68:71]
	v_mfma_f32_16x16x32_bf16 v[64:67], v[176:179], v[212:215], v[64:67]
	v_mfma_f32_16x16x32_bf16 v[116:119], v[172:175], v[192:195], v[116:119]
	v_mfma_f32_16x16x32_bf16 v[112:115], v[184:187], v[192:195], v[112:115]
	v_mfma_f32_16x16x32_bf16 v[100:103], v[172:175], v[200:203], v[100:103]
	v_mfma_f32_16x16x32_bf16 v[96:99], v[184:187], v[200:203], v[96:99]
	v_mfma_f32_16x16x32_bf16 v[84:87], v[172:175], v[208:211], v[84:87]
	v_mfma_f32_16x16x32_bf16 v[80:83], v[184:187], v[208:211], v[80:83]
	v_mfma_f32_16x16x32_bf16 v[68:71], v[172:175], v[216:219], v[68:71]
	v_mfma_f32_16x16x32_bf16 v[64:67], v[184:187], v[216:219], v[64:67]
	s_setprio 0
	s_barrier
	s_add_i32 s0, s36, s93
	v_lshl_add_u64 v[148:149], s[6:7], 0, v[130:131]
	s_mov_b32 m0, s0
	ds_read_b128 v[188:191], v155 offset:16384
	ds_read_b128 v[192:195], v155 offset:17408
	ds_read_b128 v[196:199], v155 offset:18432
	ds_read_b128 v[200:203], v155 offset:19456
	ds_read_b128 v[204:207], v155 offset:20480
	ds_read_b128 v[208:211], v155 offset:21504
	ds_read_b128 v[212:215], v155 offset:22528
	ds_read_b128 v[216:219], v155 offset:23552
	global_load_lds_dwordx4 v[148:149], off
	s_add_i32 m0, s0, 0x2000
	s_add_u32 s0, s6, 0x40000
	v_lshl_add_u64 v[180:181], s[6:7], 0, v[134:135]
	s_addc_u32 s1, s7, 0
	s_add_i32 s48, s37, s93
	global_load_lds_dwordx4 v[180:181], off
	v_lshl_add_u64 v[220:221], s[0:1], 0, v[130:131]
	s_mov_b32 m0, s48
	v_lshl_add_u64 v[222:223], s[24:25], 0, v[132:133]
	global_load_lds_dwordx4 v[220:221], off
	v_lshl_add_u64 v[220:221], s[0:1], 0, v[134:135]
	s_add_i32 m0, s48, 0x2000
	s_nop 0
	global_load_lds_dwordx4 v[220:221], off
	v_lshl_add_u64 v[220:221], s[24:25], 0, v[128:129]
	s_mov_b32 m0, s27
	s_nop 0
	global_load_lds_dwordx4 v[220:221], off
	s_mov_b32 m0, s28
	s_nop 0
	global_load_lds_dwordx4 v[222:223], off
	s_waitcnt vmcnt(8)
	s_waitcnt lgkmcnt(0)
	s_barrier
	s_setprio 1
	s_waitcnt lgkmcnt(0)
	v_mfma_f32_16x16x32_bf16 v[60:63], v[144:147], v[188:191], v[60:63]
	v_mfma_f32_16x16x32_bf16 v[56:59], v[160:163], v[188:191], v[56:59]
	v_mfma_f32_16x16x32_bf16 v[44:47], v[144:147], v[196:199], v[44:47]
	v_mfma_f32_16x16x32_bf16 v[40:43], v[160:163], v[196:199], v[40:43]
	v_mfma_f32_16x16x32_bf16 v[28:31], v[144:147], v[204:207], v[28:31]
	v_mfma_f32_16x16x32_bf16 v[24:27], v[160:163], v[204:207], v[24:27]
	v_mfma_f32_16x16x32_bf16 v[12:15], v[144:147], v[212:215], v[12:15]
	v_mfma_f32_16x16x32_bf16 v[8:11], v[160:163], v[212:215], v[8:11]
	v_mfma_f32_16x16x32_bf16 v[60:63], v[156:159], v[192:195], v[60:63]
	v_mfma_f32_16x16x32_bf16 v[56:59], v[164:167], v[192:195], v[56:59]
	v_mfma_f32_16x16x32_bf16 v[44:47], v[156:159], v[200:203], v[44:47]
	v_mfma_f32_16x16x32_bf16 v[40:43], v[164:167], v[200:203], v[40:43]
	v_mfma_f32_16x16x32_bf16 v[28:31], v[156:159], v[208:211], v[28:31]
	v_mfma_f32_16x16x32_bf16 v[24:27], v[164:167], v[208:211], v[24:27]
	v_mfma_f32_16x16x32_bf16 v[12:15], v[156:159], v[216:219], v[12:15]
	v_mfma_f32_16x16x32_bf16 v[8:11], v[164:167], v[216:219], v[8:11]
	v_mfma_f32_16x16x32_bf16 v[52:55], v[168:171], v[188:191], v[52:55]
	v_mfma_f32_16x16x32_bf16 v[48:51], v[176:179], v[188:191], v[48:51]
	v_mfma_f32_16x16x32_bf16 v[36:39], v[168:171], v[196:199], v[36:39]
	v_mfma_f32_16x16x32_bf16 v[32:35], v[176:179], v[196:199], v[32:35]
	v_mfma_f32_16x16x32_bf16 v[20:23], v[168:171], v[204:207], v[20:23]
	v_mfma_f32_16x16x32_bf16 v[16:19], v[176:179], v[204:207], v[16:19]
	v_mfma_f32_16x16x32_bf16 v[4:7], v[168:171], v[212:215], v[4:7]
	v_mfma_f32_16x16x32_bf16 v[0:3], v[176:179], v[212:215], v[0:3]
	v_mfma_f32_16x16x32_bf16 v[52:55], v[172:175], v[192:195], v[52:55]
	v_mfma_f32_16x16x32_bf16 v[48:51], v[184:187], v[192:195], v[48:51]
	v_mfma_f32_16x16x32_bf16 v[36:39], v[172:175], v[200:203], v[36:39]
	v_mfma_f32_16x16x32_bf16 v[32:35], v[184:187], v[200:203], v[32:35]
	v_mfma_f32_16x16x32_bf16 v[20:23], v[172:175], v[208:211], v[20:23]
	v_mfma_f32_16x16x32_bf16 v[16:19], v[184:187], v[208:211], v[16:19]
	v_mfma_f32_16x16x32_bf16 v[4:7], v[172:175], v[216:219], v[4:7]
	v_mfma_f32_16x16x32_bf16 v[0:3], v[184:187], v[216:219], v[0:3]
	s_setprio 0
	s_barrier
	s_add_i32 s48, 0, 0x18000
	s_add_i32 s49, 0, 0x1c000
	v_add_u32_e32 v164, s48, v151
	v_add_u32_e32 v183, s49, v151
	ds_read_b128 v[144:147], v164
	ds_read_b128 v[156:159], v164 offset:1024
	ds_read_b128 v[160:163], v164 offset:2048
	ds_read_b128 v[164:167], v164 offset:3072
	ds_read_b128 v[168:171], v183
	ds_read_b128 v[172:175], v183 offset:1024
	ds_read_b128 v[176:179], v183 offset:2048
	ds_read_b128 v[184:187], v183 offset:3072
	s_add_u32 s0, s24, 0x270000
	s_addc_u32 s1, s25, 0
	s_mov_b32 m0, s29
	v_lshl_add_u64 v[224:225], s[0:1], 0, v[128:129]
	ds_read_b128 v[188:191], v155 offset:32768
	ds_read_b128 v[192:195], v155 offset:33792
	ds_read_b128 v[196:199], v155 offset:34816
	ds_read_b128 v[200:203], v155 offset:35840
	ds_read_b128 v[204:207], v155 offset:36864
	ds_read_b128 v[208:211], v155 offset:37888
	ds_read_b128 v[212:215], v155 offset:38912
	ds_read_b128 v[216:219], v155 offset:39936
	global_load_lds_dwordx4 v[224:225], off
	v_lshl_add_u64 v[224:225], s[0:1], 0, v[132:133]
	s_mov_b32 m0, s30
	s_nop 0
	global_load_lds_dwordx4 v[224:225], off
	s_waitcnt vmcnt(8)
	s_waitcnt lgkmcnt(0)
	s_barrier
	s_setprio 1
	s_waitcnt lgkmcnt(0)
	v_mfma_f32_16x16x32_bf16 v[124:127], v[144:147], v[188:191], v[124:127]
	v_mfma_f32_16x16x32_bf16 v[120:123], v[160:163], v[188:191], v[120:123]
	v_mfma_f32_16x16x32_bf16 v[108:111], v[144:147], v[196:199], v[108:111]
	v_mfma_f32_16x16x32_bf16 v[104:107], v[160:163], v[196:199], v[104:107]
	v_mfma_f32_16x16x32_bf16 v[92:95], v[144:147], v[204:207], v[92:95]
	v_mfma_f32_16x16x32_bf16 v[88:91], v[160:163], v[204:207], v[88:91]
	v_mfma_f32_16x16x32_bf16 v[76:79], v[144:147], v[212:215], v[76:79]
	v_mfma_f32_16x16x32_bf16 v[72:75], v[160:163], v[212:215], v[72:75]
	v_mfma_f32_16x16x32_bf16 v[124:127], v[156:159], v[192:195], v[124:127]
	v_mfma_f32_16x16x32_bf16 v[120:123], v[164:167], v[192:195], v[120:123]
	v_mfma_f32_16x16x32_bf16 v[108:111], v[156:159], v[200:203], v[108:111]
	v_mfma_f32_16x16x32_bf16 v[104:107], v[164:167], v[200:203], v[104:107]
	v_mfma_f32_16x16x32_bf16 v[92:95], v[156:159], v[208:211], v[92:95]
	v_mfma_f32_16x16x32_bf16 v[88:91], v[164:167], v[208:211], v[88:91]
	v_mfma_f32_16x16x32_bf16 v[76:79], v[156:159], v[216:219], v[76:79]
	v_mfma_f32_16x16x32_bf16 v[72:75], v[164:167], v[216:219], v[72:75]
	v_mfma_f32_16x16x32_bf16 v[116:119], v[168:171], v[188:191], v[116:119]
	v_mfma_f32_16x16x32_bf16 v[112:115], v[176:179], v[188:191], v[112:115]
	v_mfma_f32_16x16x32_bf16 v[100:103], v[168:171], v[196:199], v[100:103]
	v_mfma_f32_16x16x32_bf16 v[96:99], v[176:179], v[196:199], v[96:99]
	v_mfma_f32_16x16x32_bf16 v[84:87], v[168:171], v[204:207], v[84:87]
	v_mfma_f32_16x16x32_bf16 v[80:83], v[176:179], v[204:207], v[80:83]
	v_mfma_f32_16x16x32_bf16 v[68:71], v[168:171], v[212:215], v[68:71]
	v_mfma_f32_16x16x32_bf16 v[64:67], v[176:179], v[212:215], v[64:67]
	v_mfma_f32_16x16x32_bf16 v[116:119], v[172:175], v[192:195], v[116:119]
	v_mfma_f32_16x16x32_bf16 v[112:115], v[184:187], v[192:195], v[112:115]
	v_mfma_f32_16x16x32_bf16 v[100:103], v[172:175], v[200:203], v[100:103]
	v_mfma_f32_16x16x32_bf16 v[96:99], v[184:187], v[200:203], v[96:99]
	v_mfma_f32_16x16x32_bf16 v[84:87], v[172:175], v[208:211], v[84:87]
	v_mfma_f32_16x16x32_bf16 v[80:83], v[184:187], v[208:211], v[80:83]
	v_mfma_f32_16x16x32_bf16 v[68:71], v[172:175], v[216:219], v[68:71]
	v_mfma_f32_16x16x32_bf16 v[64:67], v[184:187], v[216:219], v[64:67]
	s_setprio 0
	s_barrier
	s_add_i32 s0, s48, s93
	v_lshl_add_u64 v[148:149], v[148:149], 0, s[14:15]
	s_mov_b32 m0, s0
	ds_read_b128 v[188:191], v155 offset:49152
	ds_read_b128 v[192:195], v155 offset:50176
	ds_read_b128 v[196:199], v155 offset:51200
	ds_read_b128 v[200:203], v155 offset:52224
	ds_read_b128 v[204:207], v155 offset:53248
	ds_read_b128 v[208:211], v155 offset:54272
	ds_read_b128 v[212:215], v155 offset:55296
	ds_read_b128 v[216:219], v155 offset:56320
	global_load_lds_dwordx4 v[148:149], off
	s_add_i32 m0, s0, 0x2000
	s_add_u32 s0, s6, 0x40080
	v_lshl_add_u64 v[148:149], v[180:181], 0, s[14:15]
	s_addc_u32 s1, s7, 0
	s_add_i32 s6, s49, s93
	global_load_lds_dwordx4 v[148:149], off
	v_lshl_add_u64 v[148:149], s[0:1], 0, v[130:131]
	s_mov_b32 m0, s6
	s_nop 0
	global_load_lds_dwordx4 v[148:149], off
	v_lshl_add_u64 v[148:149], s[0:1], 0, v[134:135]
	s_add_i32 m0, s6, 0x2000
	s_nop 0
	global_load_lds_dwordx4 v[148:149], off
	v_lshl_add_u64 v[148:149], v[220:221], 0, s[14:15]
	s_mov_b32 m0, s33
	s_nop 0
	global_load_lds_dwordx4 v[148:149], off
	v_lshl_add_u64 v[148:149], v[222:223], 0, s[14:15]
	s_mov_b32 m0, s34
	s_nop 0
	global_load_lds_dwordx4 v[148:149], off
	s_waitcnt vmcnt(8)
	s_waitcnt lgkmcnt(0)
	s_barrier
	s_setprio 1
	s_waitcnt lgkmcnt(0)
	v_mfma_f32_16x16x32_bf16 v[60:63], v[144:147], v[188:191], v[60:63]
	v_mfma_f32_16x16x32_bf16 v[56:59], v[160:163], v[188:191], v[56:59]
	v_mfma_f32_16x16x32_bf16 v[44:47], v[144:147], v[196:199], v[44:47]
	v_mfma_f32_16x16x32_bf16 v[40:43], v[160:163], v[196:199], v[40:43]
	v_mfma_f32_16x16x32_bf16 v[28:31], v[144:147], v[204:207], v[28:31]
	v_mfma_f32_16x16x32_bf16 v[24:27], v[160:163], v[204:207], v[24:27]
	v_mfma_f32_16x16x32_bf16 v[12:15], v[144:147], v[212:215], v[12:15]
	v_mfma_f32_16x16x32_bf16 v[8:11], v[160:163], v[212:215], v[8:11]
	v_mfma_f32_16x16x32_bf16 v[60:63], v[156:159], v[192:195], v[60:63]
	v_mfma_f32_16x16x32_bf16 v[56:59], v[164:167], v[192:195], v[56:59]
	v_mfma_f32_16x16x32_bf16 v[44:47], v[156:159], v[200:203], v[44:47]
	v_mfma_f32_16x16x32_bf16 v[40:43], v[164:167], v[200:203], v[40:43]
	v_mfma_f32_16x16x32_bf16 v[28:31], v[156:159], v[208:211], v[28:31]
	v_mfma_f32_16x16x32_bf16 v[24:27], v[164:167], v[208:211], v[24:27]
	v_mfma_f32_16x16x32_bf16 v[12:15], v[156:159], v[216:219], v[12:15]
	v_mfma_f32_16x16x32_bf16 v[8:11], v[164:167], v[216:219], v[8:11]
	v_mfma_f32_16x16x32_bf16 v[52:55], v[168:171], v[188:191], v[52:55]
	v_mfma_f32_16x16x32_bf16 v[48:51], v[176:179], v[188:191], v[48:51]
	v_mfma_f32_16x16x32_bf16 v[36:39], v[168:171], v[196:199], v[36:39]
	v_mfma_f32_16x16x32_bf16 v[32:35], v[176:179], v[196:199], v[32:35]
	v_mfma_f32_16x16x32_bf16 v[20:23], v[168:171], v[204:207], v[20:23]
	v_mfma_f32_16x16x32_bf16 v[16:19], v[176:179], v[204:207], v[16:19]
	v_mfma_f32_16x16x32_bf16 v[4:7], v[168:171], v[212:215], v[4:7]
	v_mfma_f32_16x16x32_bf16 v[0:3], v[176:179], v[212:215], v[0:3]
	v_mfma_f32_16x16x32_bf16 v[52:55], v[172:175], v[192:195], v[52:55]
	v_mfma_f32_16x16x32_bf16 v[48:51], v[184:187], v[192:195], v[48:51]
	v_mfma_f32_16x16x32_bf16 v[36:39], v[172:175], v[200:203], v[36:39]
	v_mfma_f32_16x16x32_bf16 v[32:35], v[184:187], v[200:203], v[32:35]
	v_mfma_f32_16x16x32_bf16 v[20:23], v[172:175], v[208:211], v[20:23]
	v_mfma_f32_16x16x32_bf16 v[16:19], v[184:187], v[208:211], v[16:19]
	v_mfma_f32_16x16x32_bf16 v[4:7], v[172:175], v[216:219], v[4:7]
	v_mfma_f32_16x16x32_bf16 v[0:3], v[184:187], v[216:219], v[0:3]
	s_setprio 0
	s_barrier
	s_add_i32 s47, s47, 2
	s_add_u32 s45, s45, 0x100
	s_addc_u32 s46, s46, 0
	s_cmp_gt_u32 s47, 13
	s_mov_b64 s[0:1], s[2:3]
	s_cbranch_scc0 .LBB0_842
	s_and_b64 vcc, exec, s[16:17]
	s_cbranch_vccz .LBB0_845
	s_barrier

.LBB0_868:
	ds_read_b128 v[128:131], v159
	ds_read_b128 v[148:151], v159 offset:1024
	ds_read_b128 v[152:155], v159 offset:2048
	ds_read_b128 v[162:165], v159 offset:3072
	ds_read_b128 v[166:169], v160
	ds_read_b128 v[170:173], v160 offset:1024
	ds_read_b128 v[174:177], v160 offset:2048
	ds_read_b128 v[178:181], v160 offset:3072
	s_add_u32 s2, s0, 0x100
	s_addc_u32 s3, s1, 0
	s_cmp_eq_u32 s49, 12
	s_cselect_b32 s25, s21, s3
	s_cselect_b32 s24, s20, s2
	s_cselect_b32 s9, s19, s48
	s_cselect_b32 s8, s46, s47
	v_lshl_add_u64 v[216:217], s[0:1], 0, v[140:141]
	s_add_i32 m0, s29, 0xc000
	ds_read_b128 v[184:187], v161
	ds_read_b128 v[188:191], v161 offset:1024
	ds_read_b128 v[192:195], v161 offset:2048
	ds_read_b128 v[196:199], v161 offset:3072
	ds_read_b128 v[200:203], v161 offset:4096
	ds_read_b128 v[204:207], v161 offset:5120
	ds_read_b128 v[208:211], v161 offset:6144
	ds_read_b128 v[212:215], v161 offset:7168
	global_load_lds_dwordx4 v[216:217], off
	v_lshl_add_u64 v[216:217], s[0:1], 0, v[142:143]
	s_add_i32 m0, s29, 0xe000
	s_nop 0
	global_load_lds_dwordx4 v[216:217], off
	s_waitcnt vmcnt(8)
	s_waitcnt lgkmcnt(0)
	s_barrier
	s_setprio 1
	s_waitcnt lgkmcnt(0)
	v_mfma_f32_16x16x32_bf16 v[124:127], v[128:131], v[184:187], v[124:127]
	v_mfma_f32_16x16x32_bf16 v[120:123], v[152:155], v[184:187], v[120:123]
	v_mfma_f32_16x16x32_bf16 v[108:111], v[128:131], v[192:195], v[108:111]
	v_mfma_f32_16x16x32_bf16 v[104:107], v[152:155], v[192:195], v[104:107]
	v_mfma_f32_16x16x32_bf16 v[92:95], v[128:131], v[200:203], v[92:95]
	v_mfma_f32_16x16x32_bf16 v[88:91], v[152:155], v[200:203], v[88:91]
	v_mfma_f32_16x16x32_bf16 v[76:79], v[128:131], v[208:211], v[76:79]
	v_mfma_f32_16x16x32_bf16 v[72:75], v[152:155], v[208:211], v[72:75]
	v_mfma_f32_16x16x32_bf16 v[124:127], v[148:151], v[188:191], v[124:127]
	v_mfma_f32_16x16x32_bf16 v[120:123], v[162:165], v[188:191], v[120:123]
	v_mfma_f32_16x16x32_bf16 v[108:111], v[148:151], v[196:199], v[108:111]
	v_mfma_f32_16x16x32_bf16 v[104:107], v[162:165], v[196:199], v[104:107]
	v_mfma_f32_16x16x32_bf16 v[92:95], v[148:151], v[204:207], v[92:95]
	v_mfma_f32_16x16x32_bf16 v[88:91], v[162:165], v[204:207], v[88:91]
	v_mfma_f32_16x16x32_bf16 v[76:79], v[148:151], v[212:215], v[76:79]
	v_mfma_f32_16x16x32_bf16 v[72:75], v[162:165], v[212:215], v[72:75]
	v_mfma_f32_16x16x32_bf16 v[116:119], v[166:169], v[184:187], v[116:119]
	v_mfma_f32_16x16x32_bf16 v[112:115], v[174:177], v[184:187], v[112:115]
	v_mfma_f32_16x16x32_bf16 v[100:103], v[166:169], v[192:195], v[100:103]
	v_mfma_f32_16x16x32_bf16 v[96:99], v[174:177], v[192:195], v[96:99]
	v_mfma_f32_16x16x32_bf16 v[84:87], v[166:169], v[200:203], v[84:87]
	v_mfma_f32_16x16x32_bf16 v[80:83], v[174:177], v[200:203], v[80:83]
	v_mfma_f32_16x16x32_bf16 v[68:71], v[166:169], v[208:211], v[68:71]
	v_mfma_f32_16x16x32_bf16 v[64:67], v[174:177], v[208:211], v[64:67]
	v_mfma_f32_16x16x32_bf16 v[116:119], v[170:173], v[188:191], v[116:119]
	v_mfma_f32_16x16x32_bf16 v[112:115], v[178:181], v[188:191], v[112:115]
	v_mfma_f32_16x16x32_bf16 v[100:103], v[170:173], v[196:199], v[100:103]
	v_mfma_f32_16x16x32_bf16 v[96:99], v[178:181], v[196:199], v[96:99]
	v_mfma_f32_16x16x32_bf16 v[84:87], v[170:173], v[204:207], v[84:87]
	v_mfma_f32_16x16x32_bf16 v[80:83], v[178:181], v[204:207], v[80:83]
	v_mfma_f32_16x16x32_bf16 v[68:71], v[170:173], v[212:215], v[68:71]
	v_mfma_f32_16x16x32_bf16 v[64:67], v[178:181], v[212:215], v[64:67]
	s_setprio 0
	s_barrier
	s_add_i32 s0, s38, s93
	v_lshl_add_u64 v[216:217], s[8:9], 0, v[134:135]
	s_mov_b32 m0, s0
	ds_read_b128 v[184:187], v161 offset:16384
	ds_read_b128 v[188:191], v161 offset:17408
	ds_read_b128 v[192:195], v161 offset:18432
	ds_read_b128 v[196:199], v161 offset:19456
	ds_read_b128 v[200:203], v161 offset:20480
	ds_read_b128 v[204:207], v161 offset:21504
	ds_read_b128 v[208:211], v161 offset:22528
	ds_read_b128 v[212:215], v161 offset:23552
	global_load_lds_dwordx4 v[216:217], off
	s_add_i32 m0, s0, 0x2000
	s_add_u32 s0, s8, 0x40000
	v_lshl_add_u64 v[218:219], s[8:9], 0, v[138:139]
	s_addc_u32 s1, s9, 0
	s_add_i32 s50, s39, s93
	global_load_lds_dwordx4 v[218:219], off
	v_lshl_add_u64 v[220:221], s[0:1], 0, v[134:135]
	s_mov_b32 m0, s50
	v_lshl_add_u64 v[222:223], s[24:25], 0, v[136:137]
	global_load_lds_dwordx4 v[220:221], off
	v_lshl_add_u64 v[220:221], s[0:1], 0, v[138:139]
	s_add_i32 m0, s50, 0x2000
	s_nop 0
	global_load_lds_dwordx4 v[220:221], off
	v_lshl_add_u64 v[220:221], s[24:25], 0, v[132:133]
	s_mov_b32 m0, s29
	s_nop 0
	global_load_lds_dwordx4 v[220:221], off
	s_mov_b32 m0, s30
	s_nop 0
	global_load_lds_dwordx4 v[222:223], off
	s_waitcnt vmcnt(8)
	s_waitcnt lgkmcnt(0)
	s_barrier
	s_setprio 1
	s_waitcnt lgkmcnt(0)
	v_mfma_f32_16x16x32_bf16 v[60:63], v[128:131], v[184:187], v[60:63]
	v_mfma_f32_16x16x32_bf16 v[56:59], v[152:155], v[184:187], v[56:59]
	v_mfma_f32_16x16x32_bf16 v[44:47], v[128:131], v[192:195], v[44:47]
	v_mfma_f32_16x16x32_bf16 v[40:43], v[152:155], v[192:195], v[40:43]
	v_mfma_f32_16x16x32_bf16 v[28:31], v[128:131], v[200:203], v[28:31]
	v_mfma_f32_16x16x32_bf16 v[24:27], v[152:155], v[200:203], v[24:27]
	v_mfma_f32_16x16x32_bf16 v[12:15], v[128:131], v[208:211], v[12:15]
	v_mfma_f32_16x16x32_bf16 v[8:11], v[152:155], v[208:211], v[8:11]
	v_mfma_f32_16x16x32_bf16 v[60:63], v[148:151], v[188:191], v[60:63]
	v_mfma_f32_16x16x32_bf16 v[56:59], v[162:165], v[188:191], v[56:59]
	v_mfma_f32_16x16x32_bf16 v[44:47], v[148:151], v[196:199], v[44:47]
	v_mfma_f32_16x16x32_bf16 v[40:43], v[162:165], v[196:199], v[40:43]
	v_mfma_f32_16x16x32_bf16 v[28:31], v[148:151], v[204:207], v[28:31]
	v_mfma_f32_16x16x32_bf16 v[24:27], v[162:165], v[204:207], v[24:27]
	v_mfma_f32_16x16x32_bf16 v[12:15], v[148:151], v[212:215], v[12:15]
	v_mfma_f32_16x16x32_bf16 v[8:11], v[162:165], v[212:215], v[8:11]
	v_mfma_f32_16x16x32_bf16 v[52:55], v[166:169], v[184:187], v[52:55]
	v_mfma_f32_16x16x32_bf16 v[48:51], v[174:177], v[184:187], v[48:51]
	v_mfma_f32_16x16x32_bf16 v[36:39], v[166:169], v[192:195], v[36:39]
	v_mfma_f32_16x16x32_bf16 v[32:35], v[174:177], v[192:195], v[32:35]
	v_mfma_f32_16x16x32_bf16 v[20:23], v[166:169], v[200:203], v[20:23]
	v_mfma_f32_16x16x32_bf16 v[16:19], v[174:177], v[200:203], v[16:19]
	v_mfma_f32_16x16x32_bf16 v[4:7], v[166:169], v[208:211], v[4:7]
	v_mfma_f32_16x16x32_bf16 v[0:3], v[174:177], v[208:211], v[0:3]
	v_mfma_f32_16x16x32_bf16 v[52:55], v[170:173], v[188:191], v[52:55]
	v_mfma_f32_16x16x32_bf16 v[48:51], v[178:181], v[188:191], v[48:51]
	v_mfma_f32_16x16x32_bf16 v[36:39], v[170:173], v[196:199], v[36:39]
	v_mfma_f32_16x16x32_bf16 v[32:35], v[178:181], v[196:199], v[32:35]
	v_mfma_f32_16x16x32_bf16 v[20:23], v[170:173], v[204:207], v[20:23]
	v_mfma_f32_16x16x32_bf16 v[16:19], v[178:181], v[204:207], v[16:19]
	v_mfma_f32_16x16x32_bf16 v[4:7], v[170:173], v[212:215], v[4:7]
	v_mfma_f32_16x16x32_bf16 v[0:3], v[178:181], v[212:215], v[0:3]
	s_setprio 0
	s_barrier
	s_add_i32 s50, 0, 0x18000
	s_add_i32 s51, 0, 0x1c000
	v_add_u32_e32 v162, s50, v157
	v_add_u32_e32 v178, s51, v157
	ds_read_b128 v[128:131], v162
	ds_read_b128 v[148:151], v162 offset:1024
	ds_read_b128 v[152:155], v162 offset:2048
	ds_read_b128 v[162:165], v162 offset:3072
	ds_read_b128 v[166:169], v178
	ds_read_b128 v[170:173], v178 offset:1024
	ds_read_b128 v[174:177], v178 offset:2048
	ds_read_b128 v[178:181], v178 offset:3072
	s_add_u32 s0, s24, 0x270000
	s_addc_u32 s1, s25, 0
	s_mov_b32 m0, s31
	v_lshl_add_u64 v[224:225], s[0:1], 0, v[132:133]
	ds_read_b128 v[184:187], v161 offset:32768
	ds_read_b128 v[188:191], v161 offset:33792
	ds_read_b128 v[192:195], v161 offset:34816
	ds_read_b128 v[196:199], v161 offset:35840
	ds_read_b128 v[200:203], v161 offset:36864
	ds_read_b128 v[204:207], v161 offset:37888
	ds_read_b128 v[208:211], v161 offset:38912
	ds_read_b128 v[212:215], v161 offset:39936
	global_load_lds_dwordx4 v[224:225], off
	v_lshl_add_u64 v[224:225], s[0:1], 0, v[136:137]
	s_mov_b32 m0, s33
	s_nop 0
	global_load_lds_dwordx4 v[224:225], off
	s_waitcnt vmcnt(8)
	s_waitcnt lgkmcnt(0)
	s_barrier
	s_setprio 1
	s_waitcnt lgkmcnt(0)
	v_mfma_f32_16x16x32_bf16 v[124:127], v[128:131], v[184:187], v[124:127]
	v_mfma_f32_16x16x32_bf16 v[120:123], v[152:155], v[184:187], v[120:123]
	v_mfma_f32_16x16x32_bf16 v[108:111], v[128:131], v[192:195], v[108:111]
	v_mfma_f32_16x16x32_bf16 v[104:107], v[152:155], v[192:195], v[104:107]
	v_mfma_f32_16x16x32_bf16 v[92:95], v[128:131], v[200:203], v[92:95]
	v_mfma_f32_16x16x32_bf16 v[88:91], v[152:155], v[200:203], v[88:91]
	v_mfma_f32_16x16x32_bf16 v[76:79], v[128:131], v[208:211], v[76:79]
	v_mfma_f32_16x16x32_bf16 v[72:75], v[152:155], v[208:211], v[72:75]
	v_mfma_f32_16x16x32_bf16 v[124:127], v[148:151], v[188:191], v[124:127]
	v_mfma_f32_16x16x32_bf16 v[120:123], v[162:165], v[188:191], v[120:123]
	v_mfma_f32_16x16x32_bf16 v[108:111], v[148:151], v[196:199], v[108:111]
	v_mfma_f32_16x16x32_bf16 v[104:107], v[162:165], v[196:199], v[104:107]
	v_mfma_f32_16x16x32_bf16 v[92:95], v[148:151], v[204:207], v[92:95]
	v_mfma_f32_16x16x32_bf16 v[88:91], v[162:165], v[204:207], v[88:91]
	v_mfma_f32_16x16x32_bf16 v[76:79], v[148:151], v[212:215], v[76:79]
	v_mfma_f32_16x16x32_bf16 v[72:75], v[162:165], v[212:215], v[72:75]
	v_mfma_f32_16x16x32_bf16 v[116:119], v[166:169], v[184:187], v[116:119]
	v_mfma_f32_16x16x32_bf16 v[112:115], v[174:177], v[184:187], v[112:115]
	v_mfma_f32_16x16x32_bf16 v[100:103], v[166:169], v[192:195], v[100:103]
	v_mfma_f32_16x16x32_bf16 v[96:99], v[174:177], v[192:195], v[96:99]
	v_mfma_f32_16x16x32_bf16 v[84:87], v[166:169], v[200:203], v[84:87]
	v_mfma_f32_16x16x32_bf16 v[80:83], v[174:177], v[200:203], v[80:83]
	v_mfma_f32_16x16x32_bf16 v[68:71], v[166:169], v[208:211], v[68:71]
	v_mfma_f32_16x16x32_bf16 v[64:67], v[174:177], v[208:211], v[64:67]
	v_mfma_f32_16x16x32_bf16 v[116:119], v[170:173], v[188:191], v[116:119]
	v_mfma_f32_16x16x32_bf16 v[112:115], v[178:181], v[188:191], v[112:115]
	v_mfma_f32_16x16x32_bf16 v[100:103], v[170:173], v[196:199], v[100:103]
	v_mfma_f32_16x16x32_bf16 v[96:99], v[178:181], v[196:199], v[96:99]
	v_mfma_f32_16x16x32_bf16 v[84:87], v[170:173], v[204:207], v[84:87]
	v_mfma_f32_16x16x32_bf16 v[80:83], v[178:181], v[204:207], v[80:83]
	v_mfma_f32_16x16x32_bf16 v[68:71], v[170:173], v[212:215], v[68:71]
	v_mfma_f32_16x16x32_bf16 v[64:67], v[178:181], v[212:215], v[64:67]
	s_setprio 0
	s_barrier
	s_add_i32 s0, s50, s93
	v_lshl_add_u64 v[216:217], v[216:217], 0, s[14:15]
	s_mov_b32 m0, s0
	ds_read_b128 v[184:187], v161 offset:49152
	ds_read_b128 v[188:191], v161 offset:50176
	ds_read_b128 v[192:195], v161 offset:51200
	ds_read_b128 v[196:199], v161 offset:52224
	ds_read_b128 v[200:203], v161 offset:53248
	ds_read_b128 v[204:207], v161 offset:54272
	ds_read_b128 v[208:211], v161 offset:55296
	ds_read_b128 v[212:215], v161 offset:56320
	global_load_lds_dwordx4 v[216:217], off
	s_add_i32 m0, s0, 0x2000
	s_add_u32 s0, s8, 0x40080
	v_lshl_add_u64 v[216:217], v[218:219], 0, s[14:15]
	s_addc_u32 s1, s9, 0
	s_add_i32 s8, s51, s93
	global_load_lds_dwordx4 v[216:217], off
	v_lshl_add_u64 v[216:217], s[0:1], 0, v[134:135]
	s_mov_b32 m0, s8
	s_nop 0
	global_load_lds_dwordx4 v[216:217], off
	v_lshl_add_u64 v[216:217], s[0:1], 0, v[138:139]
	s_add_i32 m0, s8, 0x2000
	s_nop 0
	global_load_lds_dwordx4 v[216:217], off
	v_lshl_add_u64 v[216:217], v[220:221], 0, s[14:15]
	s_mov_b32 m0, s35
	s_nop 0
	global_load_lds_dwordx4 v[216:217], off
	v_lshl_add_u64 v[216:217], v[222:223], 0, s[14:15]
	s_mov_b32 m0, s36
	s_nop 0
	global_load_lds_dwordx4 v[216:217], off
	s_waitcnt vmcnt(8)
	s_waitcnt lgkmcnt(0)
	s_barrier
	s_setprio 1
	s_waitcnt lgkmcnt(0)
	v_mfma_f32_16x16x32_bf16 v[60:63], v[128:131], v[184:187], v[60:63]
	v_mfma_f32_16x16x32_bf16 v[56:59], v[152:155], v[184:187], v[56:59]
	v_mfma_f32_16x16x32_bf16 v[44:47], v[128:131], v[192:195], v[44:47]
	v_mfma_f32_16x16x32_bf16 v[40:43], v[152:155], v[192:195], v[40:43]
	v_mfma_f32_16x16x32_bf16 v[28:31], v[128:131], v[200:203], v[28:31]
	v_mfma_f32_16x16x32_bf16 v[24:27], v[152:155], v[200:203], v[24:27]
	v_mfma_f32_16x16x32_bf16 v[12:15], v[128:131], v[208:211], v[12:15]
	v_mfma_f32_16x16x32_bf16 v[8:11], v[152:155], v[208:211], v[8:11]
	v_mfma_f32_16x16x32_bf16 v[60:63], v[148:151], v[188:191], v[60:63]
	v_mfma_f32_16x16x32_bf16 v[56:59], v[162:165], v[188:191], v[56:59]
	v_mfma_f32_16x16x32_bf16 v[44:47], v[148:151], v[196:199], v[44:47]
	v_mfma_f32_16x16x32_bf16 v[40:43], v[162:165], v[196:199], v[40:43]
	v_mfma_f32_16x16x32_bf16 v[28:31], v[148:151], v[204:207], v[28:31]
	v_mfma_f32_16x16x32_bf16 v[24:27], v[162:165], v[204:207], v[24:27]
	v_mfma_f32_16x16x32_bf16 v[12:15], v[148:151], v[212:215], v[12:15]
	v_mfma_f32_16x16x32_bf16 v[8:11], v[162:165], v[212:215], v[8:11]
	v_mfma_f32_16x16x32_bf16 v[52:55], v[166:169], v[184:187], v[52:55]
	v_mfma_f32_16x16x32_bf16 v[48:51], v[174:177], v[184:187], v[48:51]
	v_mfma_f32_16x16x32_bf16 v[36:39], v[166:169], v[192:195], v[36:39]
	v_mfma_f32_16x16x32_bf16 v[32:35], v[174:177], v[192:195], v[32:35]
	v_mfma_f32_16x16x32_bf16 v[20:23], v[166:169], v[200:203], v[20:23]
	v_mfma_f32_16x16x32_bf16 v[16:19], v[174:177], v[200:203], v[16:19]
	v_mfma_f32_16x16x32_bf16 v[4:7], v[166:169], v[208:211], v[4:7]
	v_mfma_f32_16x16x32_bf16 v[0:3], v[174:177], v[208:211], v[0:3]
	v_mfma_f32_16x16x32_bf16 v[52:55], v[170:173], v[188:191], v[52:55]
	v_mfma_f32_16x16x32_bf16 v[48:51], v[178:181], v[188:191], v[48:51]
	v_mfma_f32_16x16x32_bf16 v[36:39], v[170:173], v[196:199], v[36:39]
	v_mfma_f32_16x16x32_bf16 v[32:35], v[178:181], v[196:199], v[32:35]
	v_mfma_f32_16x16x32_bf16 v[20:23], v[170:173], v[204:207], v[20:23]
	v_mfma_f32_16x16x32_bf16 v[16:19], v[178:181], v[204:207], v[16:19]
	v_mfma_f32_16x16x32_bf16 v[4:7], v[170:173], v[212:215], v[4:7]
	v_mfma_f32_16x16x32_bf16 v[0:3], v[178:181], v[212:215], v[0:3]
	s_setprio 0
	s_barrier
	s_add_i32 s49, s49, 2
	s_add_u32 s47, s47, 0x100
	s_addc_u32 s48, s48, 0
	s_cmp_gt_u32 s49, 13
	s_mov_b64 s[0:1], s[2:3]
	s_cbranch_scc0 .LBB0_868
	s_and_b64 vcc, exec, s[16:17]
	s_cbranch_vccz .LBB0_871
	s_barrier

.LBB0_902:
	ds_read_b128 v[128:131], v168
	ds_read_b128 v[144:147], v168 offset:1024
	ds_read_b128 v[148:151], v168 offset:2048
	ds_read_b128 v[152:155], v168 offset:3072
	ds_read_b128 v[156:159], v169
	ds_read_b128 v[174:177], v169 offset:1024
	ds_read_b128 v[178:181], v169 offset:2048
	ds_read_b128 v[184:187], v169 offset:3072
	s_add_u32 s16, s2, 0xfff80080
	s_addc_u32 s17, s3, -1
	s_cmp_eq_u32 s56, 28
	s_cselect_b32 s37, s1, s17
	s_cselect_b32 s36, s15, s16
	s_cselect_b32 s17, s27, s55
	s_cselect_b32 s16, s29, s54
	v_lshl_add_u64 v[160:161], s[2:3], 0, v[136:137]
	s_add_i32 m0, s33, 0xc000
	ds_read_b128 v[188:191], v170
	ds_read_b128 v[192:195], v170 offset:1024
	ds_read_b128 v[196:199], v170 offset:2048
	ds_read_b128 v[200:203], v170 offset:3072
	ds_read_b128 v[204:207], v170 offset:4096
	ds_read_b128 v[208:211], v170 offset:5120
	ds_read_b128 v[212:215], v170 offset:6144
	ds_read_b128 v[216:219], v170 offset:7168
	global_load_lds_dwordx4 v[160:161], off
	v_lshl_add_u64 v[160:161], s[2:3], 0, v[138:139]
	s_add_i32 m0, s33, 0xe000
	s_nop 0
	global_load_lds_dwordx4 v[160:161], off
	s_waitcnt vmcnt(8)
	s_waitcnt lgkmcnt(0)
	s_barrier
	s_setprio 1
	s_waitcnt lgkmcnt(0)
	v_mfma_f32_16x16x32_bf16 v[124:127], v[128:131], v[188:191], v[124:127]
	v_mfma_f32_16x16x32_bf16 v[120:123], v[148:151], v[188:191], v[120:123]
	v_mfma_f32_16x16x32_bf16 v[112:115], v[128:131], v[196:199], v[112:115]
	v_mfma_f32_16x16x32_bf16 v[108:111], v[148:151], v[196:199], v[108:111]
	v_mfma_f32_16x16x32_bf16 v[96:99], v[128:131], v[204:207], v[96:99]
	v_mfma_f32_16x16x32_bf16 v[92:95], v[148:151], v[204:207], v[92:95]
	v_mfma_f32_16x16x32_bf16 v[80:83], v[128:131], v[212:215], v[80:83]
	v_mfma_f32_16x16x32_bf16 v[76:79], v[148:151], v[212:215], v[76:79]
	v_mfma_f32_16x16x32_bf16 v[124:127], v[144:147], v[192:195], v[124:127]
	v_mfma_f32_16x16x32_bf16 v[120:123], v[152:155], v[192:195], v[120:123]
	v_mfma_f32_16x16x32_bf16 v[112:115], v[144:147], v[200:203], v[112:115]
	v_mfma_f32_16x16x32_bf16 v[108:111], v[152:155], v[200:203], v[108:111]
	v_mfma_f32_16x16x32_bf16 v[96:99], v[144:147], v[208:211], v[96:99]
	v_mfma_f32_16x16x32_bf16 v[92:95], v[152:155], v[208:211], v[92:95]
	v_mfma_f32_16x16x32_bf16 v[80:83], v[144:147], v[216:219], v[80:83]
	v_mfma_f32_16x16x32_bf16 v[76:79], v[152:155], v[216:219], v[76:79]
	v_mfma_f32_16x16x32_bf16 v[116:119], v[156:159], v[188:191], v[116:119]
	v_mfma_f32_16x16x32_bf16 v[104:107], v[178:181], v[188:191], v[104:107]
	v_mfma_f32_16x16x32_bf16 v[100:103], v[156:159], v[196:199], v[100:103]
	v_mfma_f32_16x16x32_bf16 v[88:91], v[178:181], v[196:199], v[88:91]
	v_mfma_f32_16x16x32_bf16 v[84:87], v[156:159], v[204:207], v[84:87]
	v_mfma_f32_16x16x32_bf16 v[72:75], v[178:181], v[204:207], v[72:75]
	v_mfma_f32_16x16x32_bf16 v[68:71], v[156:159], v[212:215], v[68:71]
	v_mfma_f32_16x16x32_bf16 v[64:67], v[178:181], v[212:215], v[64:67]
	v_mfma_f32_16x16x32_bf16 v[116:119], v[174:177], v[192:195], v[116:119]
	v_mfma_f32_16x16x32_bf16 v[104:107], v[184:187], v[192:195], v[104:107]
	v_mfma_f32_16x16x32_bf16 v[100:103], v[174:177], v[200:203], v[100:103]
	v_mfma_f32_16x16x32_bf16 v[88:91], v[184:187], v[200:203], v[88:91]
	v_mfma_f32_16x16x32_bf16 v[84:87], v[174:177], v[208:211], v[84:87]
	v_mfma_f32_16x16x32_bf16 v[72:75], v[184:187], v[208:211], v[72:75]
	v_mfma_f32_16x16x32_bf16 v[68:71], v[174:177], v[216:219], v[68:71]
	v_mfma_f32_16x16x32_bf16 v[64:67], v[184:187], v[216:219], v[64:67]
	s_setprio 0
	s_barrier
	s_add_i32 s57, s50, s93
	v_lshl_add_u64 v[160:161], s[16:17], 0, v[132:133]
	s_mov_b32 m0, s57
	ds_read_b128 v[188:191], v170 offset:16384
	ds_read_b128 v[192:195], v170 offset:17408
	ds_read_b128 v[196:199], v170 offset:18432
	ds_read_b128 v[200:203], v170 offset:19456
	ds_read_b128 v[204:207], v170 offset:20480
	ds_read_b128 v[208:211], v170 offset:21504
	ds_read_b128 v[212:215], v170 offset:22528
	ds_read_b128 v[216:219], v170 offset:23552
	global_load_lds_dwordx4 v[160:161], off
	s_add_i32 m0, s57, 0x2000
	s_add_u32 s58, s16, 0x80000
	v_lshl_add_u64 v[220:221], s[16:17], 0, v[134:135]
	s_addc_u32 s59, s17, 0
	s_add_i32 s57, s51, s93
	global_load_lds_dwordx4 v[220:221], off
	v_lshl_add_u64 v[222:223], s[58:59], 0, v[132:133]
	s_mov_b32 m0, s57
	v_lshl_add_u64 v[224:225], s[36:37], 0, v[134:135]
	global_load_lds_dwordx4 v[222:223], off
	v_lshl_add_u64 v[222:223], s[58:59], 0, v[134:135]
	s_add_i32 m0, s57, 0x2000
	s_nop 0
	global_load_lds_dwordx4 v[222:223], off
	v_lshl_add_u64 v[222:223], s[36:37], 0, v[132:133]
	s_mov_b32 m0, s33
	s_nop 0
	global_load_lds_dwordx4 v[222:223], off
	s_mov_b32 m0, s38
	s_nop 0
	global_load_lds_dwordx4 v[224:225], off
	s_waitcnt vmcnt(8)
	s_waitcnt lgkmcnt(0)
	s_barrier
	s_setprio 1
	s_waitcnt lgkmcnt(0)
	v_mfma_f32_16x16x32_bf16 v[60:63], v[128:131], v[188:191], v[60:63]
	v_mfma_f32_16x16x32_bf16 v[56:59], v[148:151], v[188:191], v[56:59]
	v_mfma_f32_16x16x32_bf16 v[48:51], v[128:131], v[196:199], v[48:51]
	v_mfma_f32_16x16x32_bf16 v[44:47], v[148:151], v[196:199], v[44:47]
	v_mfma_f32_16x16x32_bf16 v[32:35], v[128:131], v[204:207], v[32:35]
	v_mfma_f32_16x16x32_bf16 v[28:31], v[148:151], v[204:207], v[28:31]
	v_mfma_f32_16x16x32_bf16 v[16:19], v[128:131], v[212:215], v[16:19]
	v_mfma_f32_16x16x32_bf16 v[12:15], v[148:151], v[212:215], v[12:15]
	v_mfma_f32_16x16x32_bf16 v[60:63], v[144:147], v[192:195], v[60:63]
	v_mfma_f32_16x16x32_bf16 v[56:59], v[152:155], v[192:195], v[56:59]
	v_mfma_f32_16x16x32_bf16 v[48:51], v[144:147], v[200:203], v[48:51]
	v_mfma_f32_16x16x32_bf16 v[44:47], v[152:155], v[200:203], v[44:47]
	v_mfma_f32_16x16x32_bf16 v[32:35], v[144:147], v[208:211], v[32:35]
	v_mfma_f32_16x16x32_bf16 v[28:31], v[152:155], v[208:211], v[28:31]
	v_mfma_f32_16x16x32_bf16 v[16:19], v[144:147], v[216:219], v[16:19]
	v_mfma_f32_16x16x32_bf16 v[12:15], v[152:155], v[216:219], v[12:15]
	v_mfma_f32_16x16x32_bf16 v[52:55], v[156:159], v[188:191], v[52:55]
	v_mfma_f32_16x16x32_bf16 v[40:43], v[178:181], v[188:191], v[40:43]
	v_mfma_f32_16x16x32_bf16 v[36:39], v[156:159], v[196:199], v[36:39]
	v_mfma_f32_16x16x32_bf16 v[24:27], v[178:181], v[196:199], v[24:27]
	v_mfma_f32_16x16x32_bf16 v[20:23], v[156:159], v[204:207], v[20:23]
	v_mfma_f32_16x16x32_bf16 v[8:11], v[178:181], v[204:207], v[8:11]
	v_mfma_f32_16x16x32_bf16 v[4:7], v[156:159], v[212:215], v[4:7]
	v_mfma_f32_16x16x32_bf16 v[0:3], v[178:181], v[212:215], v[0:3]
	v_mfma_f32_16x16x32_bf16 v[52:55], v[174:177], v[192:195], v[52:55]
	v_mfma_f32_16x16x32_bf16 v[40:43], v[184:187], v[192:195], v[40:43]
	v_mfma_f32_16x16x32_bf16 v[36:39], v[174:177], v[200:203], v[36:39]
	v_mfma_f32_16x16x32_bf16 v[24:27], v[184:187], v[200:203], v[24:27]
	v_mfma_f32_16x16x32_bf16 v[20:23], v[174:177], v[208:211], v[20:23]
	v_mfma_f32_16x16x32_bf16 v[8:11], v[184:187], v[208:211], v[8:11]
	v_mfma_f32_16x16x32_bf16 v[4:7], v[174:177], v[216:219], v[4:7]
	v_mfma_f32_16x16x32_bf16 v[0:3], v[184:187], v[216:219], v[0:3]
	s_setprio 0
	s_barrier
	s_add_i32 s57, 0, 0x18000
	s_add_i32 s58, 0, 0x1c000
	v_add_u32_e32 v152, s57, v163
	v_add_u32_e32 v183, s58, v163
	ds_read_b128 v[128:131], v152
	ds_read_b128 v[144:147], v152 offset:1024
	ds_read_b128 v[148:151], v152 offset:2048
	ds_read_b128 v[152:155], v152 offset:3072
	ds_read_b128 v[156:159], v183
	ds_read_b128 v[174:177], v183 offset:1024
	ds_read_b128 v[178:181], v183 offset:2048
	ds_read_b128 v[184:187], v183 offset:3072
	s_add_u32 s36, s36, 0x80000
	s_addc_u32 s37, s37, 0
	s_mov_b32 m0, s39
	v_lshl_add_u64 v[226:227], s[36:37], 0, v[132:133]
	ds_read_b128 v[188:191], v170 offset:32768
	ds_read_b128 v[192:195], v170 offset:33792
	ds_read_b128 v[196:199], v170 offset:34816
	ds_read_b128 v[200:203], v170 offset:35840
	ds_read_b128 v[204:207], v170 offset:36864
	ds_read_b128 v[208:211], v170 offset:37888
	ds_read_b128 v[212:215], v170 offset:38912
	ds_read_b128 v[216:219], v170 offset:39936
	global_load_lds_dwordx4 v[226:227], off
	v_lshl_add_u64 v[226:227], s[36:37], 0, v[134:135]
	s_mov_b32 m0, s40
	s_nop 0
	global_load_lds_dwordx4 v[226:227], off
	s_waitcnt vmcnt(8)
	s_waitcnt lgkmcnt(0)
	s_barrier
	s_setprio 1
	s_waitcnt lgkmcnt(0)
	v_mfma_f32_16x16x32_bf16 v[124:127], v[128:131], v[188:191], v[124:127]
	v_mfma_f32_16x16x32_bf16 v[120:123], v[148:151], v[188:191], v[120:123]
	v_mfma_f32_16x16x32_bf16 v[112:115], v[128:131], v[196:199], v[112:115]
	v_mfma_f32_16x16x32_bf16 v[108:111], v[148:151], v[196:199], v[108:111]
	v_mfma_f32_16x16x32_bf16 v[96:99], v[128:131], v[204:207], v[96:99]
	v_mfma_f32_16x16x32_bf16 v[92:95], v[148:151], v[204:207], v[92:95]
	v_mfma_f32_16x16x32_bf16 v[80:83], v[128:131], v[212:215], v[80:83]
	v_mfma_f32_16x16x32_bf16 v[76:79], v[148:151], v[212:215], v[76:79]
	v_mfma_f32_16x16x32_bf16 v[124:127], v[144:147], v[192:195], v[124:127]
	v_mfma_f32_16x16x32_bf16 v[120:123], v[152:155], v[192:195], v[120:123]
	v_mfma_f32_16x16x32_bf16 v[112:115], v[144:147], v[200:203], v[112:115]
	v_mfma_f32_16x16x32_bf16 v[108:111], v[152:155], v[200:203], v[108:111]
	v_mfma_f32_16x16x32_bf16 v[96:99], v[144:147], v[208:211], v[96:99]
	v_mfma_f32_16x16x32_bf16 v[92:95], v[152:155], v[208:211], v[92:95]
	v_mfma_f32_16x16x32_bf16 v[80:83], v[144:147], v[216:219], v[80:83]
	v_mfma_f32_16x16x32_bf16 v[76:79], v[152:155], v[216:219], v[76:79]
	v_mfma_f32_16x16x32_bf16 v[116:119], v[156:159], v[188:191], v[116:119]
	v_mfma_f32_16x16x32_bf16 v[104:107], v[178:181], v[188:191], v[104:107]
	v_mfma_f32_16x16x32_bf16 v[100:103], v[156:159], v[196:199], v[100:103]
	v_mfma_f32_16x16x32_bf16 v[88:91], v[178:181], v[196:199], v[88:91]
	v_mfma_f32_16x16x32_bf16 v[84:87], v[156:159], v[204:207], v[84:87]
	v_mfma_f32_16x16x32_bf16 v[72:75], v[178:181], v[204:207], v[72:75]
	v_mfma_f32_16x16x32_bf16 v[68:71], v[156:159], v[212:215], v[68:71]
	v_mfma_f32_16x16x32_bf16 v[64:67], v[178:181], v[212:215], v[64:67]
	v_mfma_f32_16x16x32_bf16 v[116:119], v[174:177], v[192:195], v[116:119]
	v_mfma_f32_16x16x32_bf16 v[104:107], v[184:187], v[192:195], v[104:107]
	v_mfma_f32_16x16x32_bf16 v[100:103], v[174:177], v[200:203], v[100:103]
	v_mfma_f32_16x16x32_bf16 v[88:91], v[184:187], v[200:203], v[88:91]
	v_mfma_f32_16x16x32_bf16 v[84:87], v[174:177], v[208:211], v[84:87]
	v_mfma_f32_16x16x32_bf16 v[72:75], v[184:187], v[208:211], v[72:75]
	v_mfma_f32_16x16x32_bf16 v[68:71], v[174:177], v[216:219], v[68:71]
	v_mfma_f32_16x16x32_bf16 v[64:67], v[184:187], v[216:219], v[64:67]
	s_setprio 0
	s_barrier
	s_add_i32 s36, s57, s93
	v_lshl_add_u64 v[160:161], v[160:161], 0, s[22:23]
	s_mov_b32 m0, s36
	ds_read_b128 v[188:191], v170 offset:49152
	ds_read_b128 v[192:195], v170 offset:50176
	ds_read_b128 v[196:199], v170 offset:51200
	ds_read_b128 v[200:203], v170 offset:52224
	ds_read_b128 v[204:207], v170 offset:53248
	ds_read_b128 v[208:211], v170 offset:54272
	ds_read_b128 v[212:215], v170 offset:55296
	ds_read_b128 v[216:219], v170 offset:56320
	global_load_lds_dwordx4 v[160:161], off
	s_add_i32 m0, s36, 0x2000
	s_add_u32 s16, s16, 0x80080
	v_lshl_add_u64 v[160:161], v[220:221], 0, s[22:23]
	s_addc_u32 s17, s17, 0
	s_add_i32 s36, s58, s93
	global_load_lds_dwordx4 v[160:161], off
	v_lshl_add_u64 v[160:161], s[16:17], 0, v[132:133]
	s_mov_b32 m0, s36
	s_nop 0
	global_load_lds_dwordx4 v[160:161], off
	v_lshl_add_u64 v[160:161], s[16:17], 0, v[134:135]
	s_add_i32 m0, s36, 0x2000
	s_nop 0
	global_load_lds_dwordx4 v[160:161], off
	v_lshl_add_u64 v[160:161], v[222:223], 0, s[22:23]
	s_mov_b32 m0, s46
	s_nop 0
	global_load_lds_dwordx4 v[160:161], off
	v_lshl_add_u64 v[160:161], v[224:225], 0, s[22:23]
	s_mov_b32 m0, s47
	s_nop 0
	global_load_lds_dwordx4 v[160:161], off
	s_waitcnt vmcnt(8)
	s_waitcnt lgkmcnt(0)
	s_barrier
	s_setprio 1
	s_waitcnt lgkmcnt(0)
	v_mfma_f32_16x16x32_bf16 v[60:63], v[128:131], v[188:191], v[60:63]
	v_mfma_f32_16x16x32_bf16 v[56:59], v[148:151], v[188:191], v[56:59]
	v_mfma_f32_16x16x32_bf16 v[48:51], v[128:131], v[196:199], v[48:51]
	v_mfma_f32_16x16x32_bf16 v[44:47], v[148:151], v[196:199], v[44:47]
	v_mfma_f32_16x16x32_bf16 v[32:35], v[128:131], v[204:207], v[32:35]
	v_mfma_f32_16x16x32_bf16 v[28:31], v[148:151], v[204:207], v[28:31]
	v_mfma_f32_16x16x32_bf16 v[16:19], v[128:131], v[212:215], v[16:19]
	v_mfma_f32_16x16x32_bf16 v[12:15], v[148:151], v[212:215], v[12:15]
	v_mfma_f32_16x16x32_bf16 v[60:63], v[144:147], v[192:195], v[60:63]
	v_mfma_f32_16x16x32_bf16 v[56:59], v[152:155], v[192:195], v[56:59]
	v_mfma_f32_16x16x32_bf16 v[48:51], v[144:147], v[200:203], v[48:51]
	v_mfma_f32_16x16x32_bf16 v[44:47], v[152:155], v[200:203], v[44:47]
	v_mfma_f32_16x16x32_bf16 v[32:35], v[144:147], v[208:211], v[32:35]
	v_mfma_f32_16x16x32_bf16 v[28:31], v[152:155], v[208:211], v[28:31]
	v_mfma_f32_16x16x32_bf16 v[16:19], v[144:147], v[216:219], v[16:19]
	v_mfma_f32_16x16x32_bf16 v[12:15], v[152:155], v[216:219], v[12:15]
	v_mfma_f32_16x16x32_bf16 v[52:55], v[156:159], v[188:191], v[52:55]
	v_mfma_f32_16x16x32_bf16 v[40:43], v[178:181], v[188:191], v[40:43]
	v_mfma_f32_16x16x32_bf16 v[36:39], v[156:159], v[196:199], v[36:39]
	v_mfma_f32_16x16x32_bf16 v[24:27], v[178:181], v[196:199], v[24:27]
	v_mfma_f32_16x16x32_bf16 v[20:23], v[156:159], v[204:207], v[20:23]
	v_mfma_f32_16x16x32_bf16 v[8:11], v[178:181], v[204:207], v[8:11]
	v_mfma_f32_16x16x32_bf16 v[4:7], v[156:159], v[212:215], v[4:7]
	v_mfma_f32_16x16x32_bf16 v[0:3], v[178:181], v[212:215], v[0:3]
	v_mfma_f32_16x16x32_bf16 v[52:55], v[174:177], v[192:195], v[52:55]
	v_mfma_f32_16x16x32_bf16 v[40:43], v[184:187], v[192:195], v[40:43]
	v_mfma_f32_16x16x32_bf16 v[36:39], v[174:177], v[200:203], v[36:39]
	v_mfma_f32_16x16x32_bf16 v[24:27], v[184:187], v[200:203], v[24:27]
	v_mfma_f32_16x16x32_bf16 v[20:23], v[174:177], v[208:211], v[20:23]
	v_mfma_f32_16x16x32_bf16 v[8:11], v[184:187], v[208:211], v[8:11]
	v_mfma_f32_16x16x32_bf16 v[4:7], v[174:177], v[216:219], v[4:7]
	v_mfma_f32_16x16x32_bf16 v[0:3], v[184:187], v[216:219], v[0:3]
	s_setprio 0
	s_barrier
	s_add_i32 s56, s56, 2
	s_add_u32 s2, s2, 0x100
	s_addc_u32 s3, s3, 0
	s_add_u32 s54, s54, 0x100
	s_addc_u32 s55, s55, 0
	s_cmp_gt_u32 s56, 29
	s_cbranch_scc0 .LBB0_902
	s_and_b64 vcc, exec, s[24:25]
	s_cbranch_vccz .LBB0_905
	s_barrier

.LBB0_975:
	ds_read_b128 v[116:119], v185
	ds_read_b128 v[120:123], v185 offset:1024
	ds_read_b128 v[124:127], v185 offset:2048
	ds_read_b128 v[132:135], v185 offset:3072
	ds_read_b128 v[166:169], v186
	ds_read_b128 v[170:173], v186 offset:1024
	ds_read_b128 v[174:177], v186 offset:2048
	ds_read_b128 v[178:181], v186 offset:3072
	s_add_u32 s40, s38, 0xfff80080
	s_addc_u32 s41, s39, -1
	s_cmp_eq_u32 s59, 28
	s_cselect_b32 s43, s1, s41
	s_cselect_b32 s42, s3, s40
	s_cselect_b32 s41, s29, s58
	s_cselect_b32 s40, s31, s57
	v_lshl_add_u64 v[224:225], s[38:39], 0, v[156:157]
	s_add_i32 m0, s33, 0xc000
	ds_read_b128 v[192:195], v187
	ds_read_b128 v[196:199], v187 offset:1024
	ds_read_b128 v[200:203], v187 offset:2048
	ds_read_b128 v[204:207], v187 offset:3072
	ds_read_b128 v[208:211], v187 offset:4096
	ds_read_b128 v[212:215], v187 offset:5120
	ds_read_b128 v[216:219], v187 offset:6144
	ds_read_b128 v[220:223], v187 offset:7168
	global_load_lds_dwordx4 v[224:225], off
	v_lshl_add_u64 v[224:225], s[38:39], 0, v[158:159]
	s_add_i32 m0, s33, 0xe000
	s_nop 0
	global_load_lds_dwordx4 v[224:225], off
	s_waitcnt vmcnt(8)
	s_waitcnt lgkmcnt(0)
	s_barrier
	s_setprio 1
	s_waitcnt lgkmcnt(0)
	v_mfma_f32_16x16x32_bf16 v[136:139], v[116:119], v[192:195], v[136:139]
	v_mfma_f32_16x16x32_bf16 v[56:59], v[124:127], v[192:195], v[56:59]
	v_mfma_f32_16x16x32_bf16 v[112:115], v[116:119], v[200:203], v[112:115]
	v_mfma_f32_16x16x32_bf16 v[48:51], v[124:127], v[200:203], v[48:51]
	v_mfma_f32_16x16x32_bf16 v[104:107], v[116:119], v[208:211], v[104:107]
	v_mfma_f32_16x16x32_bf16 v[40:43], v[124:127], v[208:211], v[40:43]
	v_mfma_f32_16x16x32_bf16 v[100:103], v[116:119], v[216:219], v[100:103]
	v_mfma_f32_16x16x32_bf16 v[36:39], v[124:127], v[216:219], v[36:39]
	v_mfma_f32_16x16x32_bf16 v[136:139], v[120:123], v[196:199], v[136:139]
	v_mfma_f32_16x16x32_bf16 v[56:59], v[132:135], v[196:199], v[56:59]
	v_mfma_f32_16x16x32_bf16 v[112:115], v[120:123], v[204:207], v[112:115]
	v_mfma_f32_16x16x32_bf16 v[48:51], v[132:135], v[204:207], v[48:51]
	v_mfma_f32_16x16x32_bf16 v[104:107], v[120:123], v[212:215], v[104:107]
	v_mfma_f32_16x16x32_bf16 v[40:43], v[132:135], v[212:215], v[40:43]
	v_mfma_f32_16x16x32_bf16 v[100:103], v[120:123], v[220:223], v[100:103]
	v_mfma_f32_16x16x32_bf16 v[36:39], v[132:135], v[220:223], v[36:39]
	v_mfma_f32_16x16x32_bf16 v[140:143], v[166:169], v[192:195], v[140:143]
	v_mfma_f32_16x16x32_bf16 v[60:63], v[174:177], v[192:195], v[60:63]
	v_mfma_f32_16x16x32_bf16 v[128:131], v[166:169], v[200:203], v[128:131]
	v_mfma_f32_16x16x32_bf16 v[52:55], v[174:177], v[200:203], v[52:55]
	v_mfma_f32_16x16x32_bf16 v[108:111], v[166:169], v[208:211], v[108:111]
	v_mfma_f32_16x16x32_bf16 v[44:47], v[174:177], v[208:211], v[44:47]
	v_mfma_f32_16x16x32_bf16 v[96:99], v[166:169], v[216:219], v[96:99]
	v_mfma_f32_16x16x32_bf16 v[32:35], v[174:177], v[216:219], v[32:35]
	v_mfma_f32_16x16x32_bf16 v[140:143], v[170:173], v[196:199], v[140:143]
	v_mfma_f32_16x16x32_bf16 v[60:63], v[178:181], v[196:199], v[60:63]
	v_mfma_f32_16x16x32_bf16 v[128:131], v[170:173], v[204:207], v[128:131]
	v_mfma_f32_16x16x32_bf16 v[52:55], v[178:181], v[204:207], v[52:55]
	v_mfma_f32_16x16x32_bf16 v[108:111], v[170:173], v[212:215], v[108:111]
	v_mfma_f32_16x16x32_bf16 v[44:47], v[178:181], v[212:215], v[44:47]
	v_mfma_f32_16x16x32_bf16 v[96:99], v[170:173], v[220:223], v[96:99]
	v_mfma_f32_16x16x32_bf16 v[32:35], v[178:181], v[220:223], v[32:35]
	s_setprio 0
	s_barrier
	s_add_i32 s60, s53, s93
	v_lshl_add_u64 v[224:225], s[40:41], 0, v[146:147]
	s_mov_b32 m0, s60
	ds_read_b128 v[192:195], v187 offset:16384
	ds_read_b128 v[196:199], v187 offset:17408
	ds_read_b128 v[200:203], v187 offset:18432
	ds_read_b128 v[204:207], v187 offset:19456
	ds_read_b128 v[208:211], v187 offset:20480
	ds_read_b128 v[212:215], v187 offset:21504
	ds_read_b128 v[216:219], v187 offset:22528
	ds_read_b128 v[220:223], v187 offset:23552
	global_load_lds_dwordx4 v[224:225], off
	s_add_i32 m0, s60, 0x2000
	s_add_u32 s60, s40, 0x80000
	v_lshl_add_u64 v[226:227], s[40:41], 0, v[150:151]
	s_addc_u32 s61, s41, 0
	s_add_i32 s62, s54, s93
	global_load_lds_dwordx4 v[226:227], off
	v_lshl_add_u64 v[228:229], s[60:61], 0, v[146:147]
	s_mov_b32 m0, s62
	v_lshl_add_u64 v[230:231], s[42:43], 0, v[148:149]
	global_load_lds_dwordx4 v[228:229], off
	v_lshl_add_u64 v[228:229], s[60:61], 0, v[150:151]
	s_add_i32 m0, s62, 0x2000
	s_nop 0
	global_load_lds_dwordx4 v[228:229], off
	v_lshl_add_u64 v[228:229], s[42:43], 0, v[144:145]
	s_mov_b32 m0, s33
	s_nop 0
	global_load_lds_dwordx4 v[228:229], off
	s_mov_b32 m0, s44
	s_nop 0
	global_load_lds_dwordx4 v[230:231], off
	s_waitcnt vmcnt(8)
	s_waitcnt lgkmcnt(0)
	s_barrier
	s_setprio 1
	s_waitcnt lgkmcnt(0)
	v_mfma_f32_16x16x32_bf16 v[88:91], v[116:119], v[192:195], v[88:91]
	v_mfma_f32_16x16x32_bf16 v[24:27], v[124:127], v[192:195], v[24:27]
	v_mfma_f32_16x16x32_bf16 v[80:83], v[116:119], v[200:203], v[80:83]
	v_mfma_f32_16x16x32_bf16 v[16:19], v[124:127], v[200:203], v[16:19]
	v_mfma_f32_16x16x32_bf16 v[72:75], v[116:119], v[208:211], v[72:75]
	v_mfma_f32_16x16x32_bf16 v[8:11], v[124:127], v[208:211], v[8:11]
	v_mfma_f32_16x16x32_bf16 v[68:71], v[116:119], v[216:219], v[68:71]
	v_mfma_f32_16x16x32_bf16 v[4:7], v[124:127], v[216:219], v[4:7]
	v_mfma_f32_16x16x32_bf16 v[88:91], v[120:123], v[196:199], v[88:91]
	v_mfma_f32_16x16x32_bf16 v[24:27], v[132:135], v[196:199], v[24:27]
	v_mfma_f32_16x16x32_bf16 v[80:83], v[120:123], v[204:207], v[80:83]
	v_mfma_f32_16x16x32_bf16 v[16:19], v[132:135], v[204:207], v[16:19]
	v_mfma_f32_16x16x32_bf16 v[72:75], v[120:123], v[212:215], v[72:75]
	v_mfma_f32_16x16x32_bf16 v[8:11], v[132:135], v[212:215], v[8:11]
	v_mfma_f32_16x16x32_bf16 v[68:71], v[120:123], v[220:223], v[68:71]
	v_mfma_f32_16x16x32_bf16 v[4:7], v[132:135], v[220:223], v[4:7]
	v_mfma_f32_16x16x32_bf16 v[92:95], v[166:169], v[192:195], v[92:95]
	v_mfma_f32_16x16x32_bf16 v[28:31], v[174:177], v[192:195], v[28:31]
	v_mfma_f32_16x16x32_bf16 v[84:87], v[166:169], v[200:203], v[84:87]
	v_mfma_f32_16x16x32_bf16 v[20:23], v[174:177], v[200:203], v[20:23]
	v_mfma_f32_16x16x32_bf16 v[76:79], v[166:169], v[208:211], v[76:79]
	v_mfma_f32_16x16x32_bf16 v[12:15], v[174:177], v[208:211], v[12:15]
	v_mfma_f32_16x16x32_bf16 v[64:67], v[166:169], v[216:219], v[64:67]
	v_mfma_f32_16x16x32_bf16 v[0:3], v[174:177], v[216:219], v[0:3]
	v_mfma_f32_16x16x32_bf16 v[92:95], v[170:173], v[196:199], v[92:95]
	v_mfma_f32_16x16x32_bf16 v[28:31], v[178:181], v[196:199], v[28:31]
	v_mfma_f32_16x16x32_bf16 v[84:87], v[170:173], v[204:207], v[84:87]
	v_mfma_f32_16x16x32_bf16 v[20:23], v[178:181], v[204:207], v[20:23]
	v_mfma_f32_16x16x32_bf16 v[76:79], v[170:173], v[212:215], v[76:79]
	v_mfma_f32_16x16x32_bf16 v[12:15], v[178:181], v[212:215], v[12:15]
	v_mfma_f32_16x16x32_bf16 v[64:67], v[170:173], v[220:223], v[64:67]
	v_mfma_f32_16x16x32_bf16 v[0:3], v[178:181], v[220:223], v[0:3]
	s_setprio 0
	s_barrier
	s_add_i32 s60, 0, 0x18000
	s_add_i32 s61, 0, 0x1c000
	v_add_u32_e32 v132, s60, v183
	v_add_u32_e32 v178, s61, v183
	ds_read_b128 v[116:119], v132
	ds_read_b128 v[120:123], v132 offset:1024
	ds_read_b128 v[124:127], v132 offset:2048
	ds_read_b128 v[132:135], v132 offset:3072
	ds_read_b128 v[166:169], v178
	ds_read_b128 v[170:173], v178 offset:1024
	ds_read_b128 v[174:177], v178 offset:2048
	ds_read_b128 v[178:181], v178 offset:3072
	s_add_u32 s42, s42, 0x80000
	s_addc_u32 s43, s43, 0
	s_mov_b32 m0, s45
	v_lshl_add_u64 v[232:233], s[42:43], 0, v[144:145]
	ds_read_b128 v[192:195], v187 offset:32768
	ds_read_b128 v[196:199], v187 offset:33792
	ds_read_b128 v[200:203], v187 offset:34816
	ds_read_b128 v[204:207], v187 offset:35840
	ds_read_b128 v[208:211], v187 offset:36864
	ds_read_b128 v[212:215], v187 offset:37888
	ds_read_b128 v[216:219], v187 offset:38912
	ds_read_b128 v[220:223], v187 offset:39936
	global_load_lds_dwordx4 v[232:233], off
	v_lshl_add_u64 v[232:233], s[42:43], 0, v[148:149]
	s_mov_b32 m0, s46
	s_nop 0
	global_load_lds_dwordx4 v[232:233], off
	s_waitcnt vmcnt(8)
	s_waitcnt lgkmcnt(0)
	s_barrier
	s_setprio 1
	s_waitcnt lgkmcnt(0)
	v_mfma_f32_16x16x32_bf16 v[136:139], v[116:119], v[192:195], v[136:139]
	v_mfma_f32_16x16x32_bf16 v[56:59], v[124:127], v[192:195], v[56:59]
	v_mfma_f32_16x16x32_bf16 v[112:115], v[116:119], v[200:203], v[112:115]
	v_mfma_f32_16x16x32_bf16 v[48:51], v[124:127], v[200:203], v[48:51]
	v_mfma_f32_16x16x32_bf16 v[104:107], v[116:119], v[208:211], v[104:107]
	v_mfma_f32_16x16x32_bf16 v[40:43], v[124:127], v[208:211], v[40:43]
	v_mfma_f32_16x16x32_bf16 v[100:103], v[116:119], v[216:219], v[100:103]
	v_mfma_f32_16x16x32_bf16 v[36:39], v[124:127], v[216:219], v[36:39]
	v_mfma_f32_16x16x32_bf16 v[136:139], v[120:123], v[196:199], v[136:139]
	v_mfma_f32_16x16x32_bf16 v[56:59], v[132:135], v[196:199], v[56:59]
	v_mfma_f32_16x16x32_bf16 v[112:115], v[120:123], v[204:207], v[112:115]
	v_mfma_f32_16x16x32_bf16 v[48:51], v[132:135], v[204:207], v[48:51]
	v_mfma_f32_16x16x32_bf16 v[104:107], v[120:123], v[212:215], v[104:107]
	v_mfma_f32_16x16x32_bf16 v[40:43], v[132:135], v[212:215], v[40:43]
	v_mfma_f32_16x16x32_bf16 v[100:103], v[120:123], v[220:223], v[100:103]
	v_mfma_f32_16x16x32_bf16 v[36:39], v[132:135], v[220:223], v[36:39]
	v_mfma_f32_16x16x32_bf16 v[140:143], v[166:169], v[192:195], v[140:143]
	v_mfma_f32_16x16x32_bf16 v[60:63], v[174:177], v[192:195], v[60:63]
	v_mfma_f32_16x16x32_bf16 v[128:131], v[166:169], v[200:203], v[128:131]
	v_mfma_f32_16x16x32_bf16 v[52:55], v[174:177], v[200:203], v[52:55]
	v_mfma_f32_16x16x32_bf16 v[108:111], v[166:169], v[208:211], v[108:111]
	v_mfma_f32_16x16x32_bf16 v[44:47], v[174:177], v[208:211], v[44:47]
	v_mfma_f32_16x16x32_bf16 v[96:99], v[166:169], v[216:219], v[96:99]
	v_mfma_f32_16x16x32_bf16 v[32:35], v[174:177], v[216:219], v[32:35]
	v_mfma_f32_16x16x32_bf16 v[140:143], v[170:173], v[196:199], v[140:143]
	v_mfma_f32_16x16x32_bf16 v[60:63], v[178:181], v[196:199], v[60:63]
	v_mfma_f32_16x16x32_bf16 v[128:131], v[170:173], v[204:207], v[128:131]
	v_mfma_f32_16x16x32_bf16 v[52:55], v[178:181], v[204:207], v[52:55]
	v_mfma_f32_16x16x32_bf16 v[108:111], v[170:173], v[212:215], v[108:111]
	v_mfma_f32_16x16x32_bf16 v[44:47], v[178:181], v[212:215], v[44:47]
	v_mfma_f32_16x16x32_bf16 v[96:99], v[170:173], v[220:223], v[96:99]
	v_mfma_f32_16x16x32_bf16 v[32:35], v[178:181], v[220:223], v[32:35]
	s_setprio 0
	s_barrier
	s_add_i32 s42, s60, s93
	v_lshl_add_u64 v[224:225], v[224:225], 0, s[20:21]
	s_mov_b32 m0, s42
	ds_read_b128 v[192:195], v187 offset:49152
	ds_read_b128 v[196:199], v187 offset:50176
	ds_read_b128 v[200:203], v187 offset:51200
	ds_read_b128 v[204:207], v187 offset:52224
	ds_read_b128 v[208:211], v187 offset:53248
	ds_read_b128 v[212:215], v187 offset:54272
	ds_read_b128 v[216:219], v187 offset:55296
	ds_read_b128 v[220:223], v187 offset:56320
	global_load_lds_dwordx4 v[224:225], off
	s_add_i32 m0, s42, 0x2000
	s_add_u32 s40, s40, 0x80080
	v_lshl_add_u64 v[224:225], v[226:227], 0, s[20:21]
	s_addc_u32 s41, s41, 0
	s_add_i32 s42, s61, s93
	global_load_lds_dwordx4 v[224:225], off
	v_lshl_add_u64 v[224:225], s[40:41], 0, v[146:147]
	s_mov_b32 m0, s42
	s_nop 0
	global_load_lds_dwordx4 v[224:225], off
	v_lshl_add_u64 v[224:225], s[40:41], 0, v[150:151]
	s_add_i32 m0, s42, 0x2000
	s_nop 0
	global_load_lds_dwordx4 v[224:225], off
	v_lshl_add_u64 v[224:225], v[228:229], 0, s[20:21]
	s_mov_b32 m0, s48
	s_nop 0
	global_load_lds_dwordx4 v[224:225], off
	v_lshl_add_u64 v[224:225], v[230:231], 0, s[20:21]
	s_mov_b32 m0, s49
	s_nop 0
	global_load_lds_dwordx4 v[224:225], off
	s_waitcnt vmcnt(8)
	s_waitcnt lgkmcnt(0)
	s_barrier
	s_setprio 1
	s_waitcnt lgkmcnt(0)
	v_mfma_f32_16x16x32_bf16 v[88:91], v[116:119], v[192:195], v[88:91]
	v_mfma_f32_16x16x32_bf16 v[24:27], v[124:127], v[192:195], v[24:27]
	v_mfma_f32_16x16x32_bf16 v[80:83], v[116:119], v[200:203], v[80:83]
	v_mfma_f32_16x16x32_bf16 v[16:19], v[124:127], v[200:203], v[16:19]
	v_mfma_f32_16x16x32_bf16 v[72:75], v[116:119], v[208:211], v[72:75]
	v_mfma_f32_16x16x32_bf16 v[8:11], v[124:127], v[208:211], v[8:11]
	v_mfma_f32_16x16x32_bf16 v[68:71], v[116:119], v[216:219], v[68:71]
	v_mfma_f32_16x16x32_bf16 v[4:7], v[124:127], v[216:219], v[4:7]
	v_mfma_f32_16x16x32_bf16 v[88:91], v[120:123], v[196:199], v[88:91]
	v_mfma_f32_16x16x32_bf16 v[24:27], v[132:135], v[196:199], v[24:27]
	v_mfma_f32_16x16x32_bf16 v[80:83], v[120:123], v[204:207], v[80:83]
	v_mfma_f32_16x16x32_bf16 v[16:19], v[132:135], v[204:207], v[16:19]
	v_mfma_f32_16x16x32_bf16 v[72:75], v[120:123], v[212:215], v[72:75]
	v_mfma_f32_16x16x32_bf16 v[8:11], v[132:135], v[212:215], v[8:11]
	v_mfma_f32_16x16x32_bf16 v[68:71], v[120:123], v[220:223], v[68:71]
	v_mfma_f32_16x16x32_bf16 v[4:7], v[132:135], v[220:223], v[4:7]
	v_mfma_f32_16x16x32_bf16 v[92:95], v[166:169], v[192:195], v[92:95]
	v_mfma_f32_16x16x32_bf16 v[28:31], v[174:177], v[192:195], v[28:31]
	v_mfma_f32_16x16x32_bf16 v[84:87], v[166:169], v[200:203], v[84:87]
	v_mfma_f32_16x16x32_bf16 v[20:23], v[174:177], v[200:203], v[20:23]
	v_mfma_f32_16x16x32_bf16 v[76:79], v[166:169], v[208:211], v[76:79]
	v_mfma_f32_16x16x32_bf16 v[12:15], v[174:177], v[208:211], v[12:15]
	v_mfma_f32_16x16x32_bf16 v[64:67], v[166:169], v[216:219], v[64:67]
	v_mfma_f32_16x16x32_bf16 v[0:3], v[174:177], v[216:219], v[0:3]
	v_mfma_f32_16x16x32_bf16 v[92:95], v[170:173], v[196:199], v[92:95]
	v_mfma_f32_16x16x32_bf16 v[28:31], v[178:181], v[196:199], v[28:31]
	v_mfma_f32_16x16x32_bf16 v[84:87], v[170:173], v[204:207], v[84:87]
	v_mfma_f32_16x16x32_bf16 v[20:23], v[178:181], v[204:207], v[20:23]
	v_mfma_f32_16x16x32_bf16 v[76:79], v[170:173], v[212:215], v[76:79]
	v_mfma_f32_16x16x32_bf16 v[12:15], v[178:181], v[212:215], v[12:15]
	v_mfma_f32_16x16x32_bf16 v[64:67], v[170:173], v[220:223], v[64:67]
	v_mfma_f32_16x16x32_bf16 v[0:3], v[178:181], v[220:223], v[0:3]
	s_setprio 0
	s_barrier
	s_add_i32 s59, s59, 2
	s_add_u32 s38, s38, 0x100
	s_addc_u32 s39, s39, 0
	s_add_u32 s57, s57, 0x100
	s_addc_u32 s58, s58, 0
	s_cmp_gt_u32 s59, 29
	s_cbranch_scc0 .LBB0_975
	s_and_b64 vcc, exec, s[22:23]
	s_cbranch_vccz .LBB0_978
	s_barrier

.LBB0_1051:
	ds_read_b128 v[140:143], v167
	ds_read_b128 v[144:147], v167 offset:1024
	ds_read_b128 v[148:151], v167 offset:2048
	ds_read_b128 v[152:155], v167 offset:3072
	ds_read_b128 v[156:159], v168
	ds_read_b128 v[174:177], v168 offset:1024
	ds_read_b128 v[178:181], v168 offset:2048
	ds_read_b128 v[184:187], v168 offset:3072
	s_add_u32 s12, s2, 0x100
	s_addc_u32 s13, s3, 0
	s_cmpk_eq_i32 s62, 0x54
	s_cselect_b32 s39, s35, s13
	s_cselect_b32 s38, s34, s12
	s_cselect_b32 s15, s37, s61
	s_cselect_b32 s14, s36, s1
	v_lshl_add_u64 v[220:221], s[2:3], 0, v[132:133]
	s_add_i32 m0, s33, 0xc000
	ds_read_b128 v[188:191], v169
	ds_read_b128 v[192:195], v169 offset:1024
	ds_read_b128 v[196:199], v169 offset:2048
	ds_read_b128 v[200:203], v169 offset:3072
	ds_read_b128 v[204:207], v169 offset:4096
	ds_read_b128 v[208:211], v169 offset:5120
	ds_read_b128 v[212:215], v169 offset:6144
	ds_read_b128 v[216:219], v169 offset:7168
	global_load_lds_dwordx4 v[220:221], off
	v_lshl_add_u64 v[220:221], s[2:3], 0, v[134:135]
	s_add_i32 m0, s33, 0xe000
	s_nop 0
	global_load_lds_dwordx4 v[220:221], off
	s_waitcnt vmcnt(8)
	s_waitcnt lgkmcnt(0)
	s_barrier
	s_setprio 1
	s_waitcnt lgkmcnt(0)
	v_mfma_f32_16x16x32_bf16 v[124:127], v[140:143], v[188:191], v[124:127]
	v_mfma_f32_16x16x32_bf16 v[120:123], v[148:151], v[188:191], v[120:123]
	v_mfma_f32_16x16x32_bf16 v[116:119], v[140:143], v[196:199], v[116:119]
	v_mfma_f32_16x16x32_bf16 v[104:107], v[148:151], v[196:199], v[104:107]
	v_mfma_f32_16x16x32_bf16 v[112:115], v[140:143], v[204:207], v[112:115]
	v_mfma_f32_16x16x32_bf16 v[100:103], v[148:151], v[204:207], v[100:103]
	v_mfma_f32_16x16x32_bf16 v[96:99], v[140:143], v[212:215], v[96:99]
	v_mfma_f32_16x16x32_bf16 v[76:79], v[148:151], v[212:215], v[76:79]
	v_mfma_f32_16x16x32_bf16 v[124:127], v[144:147], v[192:195], v[124:127]
	v_mfma_f32_16x16x32_bf16 v[120:123], v[152:155], v[192:195], v[120:123]
	v_mfma_f32_16x16x32_bf16 v[116:119], v[144:147], v[200:203], v[116:119]
	v_mfma_f32_16x16x32_bf16 v[104:107], v[152:155], v[200:203], v[104:107]
	v_mfma_f32_16x16x32_bf16 v[112:115], v[144:147], v[208:211], v[112:115]
	v_mfma_f32_16x16x32_bf16 v[100:103], v[152:155], v[208:211], v[100:103]
	v_mfma_f32_16x16x32_bf16 v[96:99], v[144:147], v[216:219], v[96:99]
	v_mfma_f32_16x16x32_bf16 v[76:79], v[152:155], v[216:219], v[76:79]
	v_mfma_f32_16x16x32_bf16 v[108:111], v[156:159], v[188:191], v[108:111]
	v_mfma_f32_16x16x32_bf16 v[92:95], v[178:181], v[188:191], v[92:95]
	v_mfma_f32_16x16x32_bf16 v[88:91], v[156:159], v[196:199], v[88:91]
	v_mfma_f32_16x16x32_bf16 v[72:75], v[178:181], v[196:199], v[72:75]
	v_mfma_f32_16x16x32_bf16 v[80:83], v[156:159], v[204:207], v[80:83]
	v_mfma_f32_16x16x32_bf16 v[64:67], v[178:181], v[204:207], v[64:67]
	v_mfma_f32_16x16x32_bf16 v[60:63], v[156:159], v[212:215], v[60:63]
	v_mfma_f32_16x16x32_bf16 v[56:59], v[178:181], v[212:215], v[56:59]
	v_mfma_f32_16x16x32_bf16 v[108:111], v[174:177], v[192:195], v[108:111]
	v_mfma_f32_16x16x32_bf16 v[92:95], v[184:187], v[192:195], v[92:95]
	v_mfma_f32_16x16x32_bf16 v[88:91], v[174:177], v[200:203], v[88:91]
	v_mfma_f32_16x16x32_bf16 v[72:75], v[184:187], v[200:203], v[72:75]
	v_mfma_f32_16x16x32_bf16 v[80:83], v[174:177], v[208:211], v[80:83]
	v_mfma_f32_16x16x32_bf16 v[64:67], v[184:187], v[208:211], v[64:67]
	v_mfma_f32_16x16x32_bf16 v[60:63], v[174:177], v[216:219], v[60:63]
	v_mfma_f32_16x16x32_bf16 v[56:59], v[184:187], v[216:219], v[56:59]
	s_setprio 0
	s_barrier
	s_add_i32 s2, s50, s93
	v_lshl_add_u64 v[220:221], s[14:15], 0, v[128:129]
	s_mov_b32 m0, s2
	ds_read_b128 v[188:191], v169 offset:16384
	ds_read_b128 v[192:195], v169 offset:17408
	ds_read_b128 v[196:199], v169 offset:18432
	ds_read_b128 v[200:203], v169 offset:19456
	ds_read_b128 v[204:207], v169 offset:20480
	ds_read_b128 v[208:211], v169 offset:21504
	ds_read_b128 v[212:215], v169 offset:22528
	ds_read_b128 v[216:219], v169 offset:23552
	global_load_lds_dwordx4 v[220:221], off
	s_add_i32 m0, s2, 0x2000
	s_add_u32 s2, s14, 0x160000
	v_lshl_add_u64 v[222:223], s[14:15], 0, v[130:131]
	s_addc_u32 s3, s15, 0
	s_add_i32 s63, s51, s93
	global_load_lds_dwordx4 v[222:223], off
	v_lshl_add_u64 v[224:225], s[2:3], 0, v[128:129]
	s_mov_b32 m0, s63
	v_lshl_add_u64 v[226:227], s[38:39], 0, v[130:131]
	global_load_lds_dwordx4 v[224:225], off
	v_lshl_add_u64 v[224:225], s[2:3], 0, v[130:131]
	s_add_i32 m0, s63, 0x2000
	s_nop 0
	global_load_lds_dwordx4 v[224:225], off
	v_lshl_add_u64 v[224:225], s[38:39], 0, v[128:129]
	s_mov_b32 m0, s33
	s_nop 0
	global_load_lds_dwordx4 v[224:225], off
	s_mov_b32 m0, s40
	s_nop 0
	global_load_lds_dwordx4 v[226:227], off
	s_waitcnt vmcnt(8)
	s_waitcnt lgkmcnt(0)
	s_barrier
	s_setprio 1
	s_waitcnt lgkmcnt(0)
	v_mfma_f32_16x16x32_bf16 v[84:87], v[140:143], v[188:191], v[84:87]
	v_mfma_f32_16x16x32_bf16 v[68:71], v[148:151], v[188:191], v[68:71]
	v_mfma_f32_16x16x32_bf16 v[44:47], v[140:143], v[196:199], v[44:47]
	v_mfma_f32_16x16x32_bf16 v[40:43], v[148:151], v[196:199], v[40:43]
	v_mfma_f32_16x16x32_bf16 v[28:31], v[140:143], v[204:207], v[28:31]
	v_mfma_f32_16x16x32_bf16 v[24:27], v[148:151], v[204:207], v[24:27]
	v_mfma_f32_16x16x32_bf16 v[12:15], v[140:143], v[212:215], v[12:15]
	v_mfma_f32_16x16x32_bf16 v[8:11], v[148:151], v[212:215], v[8:11]
	v_mfma_f32_16x16x32_bf16 v[84:87], v[144:147], v[192:195], v[84:87]
	v_mfma_f32_16x16x32_bf16 v[68:71], v[152:155], v[192:195], v[68:71]
	v_mfma_f32_16x16x32_bf16 v[44:47], v[144:147], v[200:203], v[44:47]
	v_mfma_f32_16x16x32_bf16 v[40:43], v[152:155], v[200:203], v[40:43]
	v_mfma_f32_16x16x32_bf16 v[28:31], v[144:147], v[208:211], v[28:31]
	v_mfma_f32_16x16x32_bf16 v[24:27], v[152:155], v[208:211], v[24:27]
	v_mfma_f32_16x16x32_bf16 v[12:15], v[144:147], v[216:219], v[12:15]
	v_mfma_f32_16x16x32_bf16 v[8:11], v[152:155], v[216:219], v[8:11]
	v_mfma_f32_16x16x32_bf16 v[52:55], v[156:159], v[188:191], v[52:55]
	v_mfma_f32_16x16x32_bf16 v[48:51], v[178:181], v[188:191], v[48:51]
	v_mfma_f32_16x16x32_bf16 v[36:39], v[156:159], v[196:199], v[36:39]
	v_mfma_f32_16x16x32_bf16 v[32:35], v[178:181], v[196:199], v[32:35]
	v_mfma_f32_16x16x32_bf16 v[20:23], v[156:159], v[204:207], v[20:23]
	v_mfma_f32_16x16x32_bf16 v[16:19], v[178:181], v[204:207], v[16:19]
	v_mfma_f32_16x16x32_bf16 v[4:7], v[156:159], v[212:215], v[4:7]
	v_mfma_f32_16x16x32_bf16 v[0:3], v[178:181], v[212:215], v[0:3]
	v_mfma_f32_16x16x32_bf16 v[52:55], v[174:177], v[192:195], v[52:55]
	v_mfma_f32_16x16x32_bf16 v[48:51], v[184:187], v[192:195], v[48:51]
	v_mfma_f32_16x16x32_bf16 v[36:39], v[174:177], v[200:203], v[36:39]
	v_mfma_f32_16x16x32_bf16 v[32:35], v[184:187], v[200:203], v[32:35]
	v_mfma_f32_16x16x32_bf16 v[20:23], v[174:177], v[208:211], v[20:23]
	v_mfma_f32_16x16x32_bf16 v[16:19], v[184:187], v[208:211], v[16:19]
	v_mfma_f32_16x16x32_bf16 v[4:7], v[174:177], v[216:219], v[4:7]
	v_mfma_f32_16x16x32_bf16 v[0:3], v[184:187], v[216:219], v[0:3]
	s_setprio 0
	s_barrier
	s_add_i32 s63, 0, 0x18000
	s_add_i32 s64, 0, 0x1c000
	v_add_u32_e32 v152, s63, v162
	v_add_u32_e32 v160, s64, v162
	ds_read_b128 v[140:143], v152
	ds_read_b128 v[144:147], v152 offset:1024
	ds_read_b128 v[148:151], v152 offset:2048
	ds_read_b128 v[152:155], v152 offset:3072
	ds_read_b128 v[156:159], v160
	ds_read_b128 v[174:177], v160 offset:1024
	ds_read_b128 v[178:181], v160 offset:2048
	ds_read_b128 v[184:187], v160 offset:3072
	s_add_u32 s2, s38, 0x160000
	s_addc_u32 s3, s39, 0
	s_mov_b32 m0, s41
	v_lshl_add_u64 v[228:229], s[2:3], 0, v[128:129]
	ds_read_b128 v[188:191], v169 offset:32768
	ds_read_b128 v[192:195], v169 offset:33792
	ds_read_b128 v[196:199], v169 offset:34816
	ds_read_b128 v[200:203], v169 offset:35840
	ds_read_b128 v[204:207], v169 offset:36864
	ds_read_b128 v[208:211], v169 offset:37888
	ds_read_b128 v[212:215], v169 offset:38912
	ds_read_b128 v[216:219], v169 offset:39936
	global_load_lds_dwordx4 v[228:229], off
	v_lshl_add_u64 v[228:229], s[2:3], 0, v[130:131]
	s_mov_b32 m0, s42
	s_nop 0
	global_load_lds_dwordx4 v[228:229], off
	s_waitcnt vmcnt(8)
	s_waitcnt lgkmcnt(0)
	s_barrier
	s_setprio 1
	s_waitcnt lgkmcnt(0)
	v_mfma_f32_16x16x32_bf16 v[124:127], v[140:143], v[188:191], v[124:127]
	v_mfma_f32_16x16x32_bf16 v[120:123], v[148:151], v[188:191], v[120:123]
	v_mfma_f32_16x16x32_bf16 v[116:119], v[140:143], v[196:199], v[116:119]
	v_mfma_f32_16x16x32_bf16 v[104:107], v[148:151], v[196:199], v[104:107]
	v_mfma_f32_16x16x32_bf16 v[112:115], v[140:143], v[204:207], v[112:115]
	v_mfma_f32_16x16x32_bf16 v[100:103], v[148:151], v[204:207], v[100:103]
	v_mfma_f32_16x16x32_bf16 v[96:99], v[140:143], v[212:215], v[96:99]
	v_mfma_f32_16x16x32_bf16 v[76:79], v[148:151], v[212:215], v[76:79]
	v_mfma_f32_16x16x32_bf16 v[124:127], v[144:147], v[192:195], v[124:127]
	v_mfma_f32_16x16x32_bf16 v[120:123], v[152:155], v[192:195], v[120:123]
	v_mfma_f32_16x16x32_bf16 v[116:119], v[144:147], v[200:203], v[116:119]
	v_mfma_f32_16x16x32_bf16 v[104:107], v[152:155], v[200:203], v[104:107]
	v_mfma_f32_16x16x32_bf16 v[112:115], v[144:147], v[208:211], v[112:115]
	v_mfma_f32_16x16x32_bf16 v[100:103], v[152:155], v[208:211], v[100:103]
	v_mfma_f32_16x16x32_bf16 v[96:99], v[144:147], v[216:219], v[96:99]
	v_mfma_f32_16x16x32_bf16 v[76:79], v[152:155], v[216:219], v[76:79]
	v_mfma_f32_16x16x32_bf16 v[108:111], v[156:159], v[188:191], v[108:111]
	v_mfma_f32_16x16x32_bf16 v[92:95], v[178:181], v[188:191], v[92:95]
	v_mfma_f32_16x16x32_bf16 v[88:91], v[156:159], v[196:199], v[88:91]
	v_mfma_f32_16x16x32_bf16 v[72:75], v[178:181], v[196:199], v[72:75]
	v_mfma_f32_16x16x32_bf16 v[80:83], v[156:159], v[204:207], v[80:83]
	v_mfma_f32_16x16x32_bf16 v[64:67], v[178:181], v[204:207], v[64:67]
	v_mfma_f32_16x16x32_bf16 v[60:63], v[156:159], v[212:215], v[60:63]
	v_mfma_f32_16x16x32_bf16 v[56:59], v[178:181], v[212:215], v[56:59]
	v_mfma_f32_16x16x32_bf16 v[108:111], v[174:177], v[192:195], v[108:111]
	v_mfma_f32_16x16x32_bf16 v[92:95], v[184:187], v[192:195], v[92:95]
	v_mfma_f32_16x16x32_bf16 v[88:91], v[174:177], v[200:203], v[88:91]
	v_mfma_f32_16x16x32_bf16 v[72:75], v[184:187], v[200:203], v[72:75]
	v_mfma_f32_16x16x32_bf16 v[80:83], v[174:177], v[208:211], v[80:83]
	v_mfma_f32_16x16x32_bf16 v[64:67], v[184:187], v[208:211], v[64:67]
	v_mfma_f32_16x16x32_bf16 v[60:63], v[174:177], v[216:219], v[60:63]
	v_mfma_f32_16x16x32_bf16 v[56:59], v[184:187], v[216:219], v[56:59]
	s_setprio 0
	s_barrier
	s_add_i32 s2, s63, s93
	v_lshl_add_u64 v[220:221], v[220:221], 0, s[22:23]
	s_mov_b32 m0, s2
	ds_read_b128 v[188:191], v169 offset:49152
	ds_read_b128 v[192:195], v169 offset:50176
	ds_read_b128 v[196:199], v169 offset:51200
	ds_read_b128 v[200:203], v169 offset:52224
	ds_read_b128 v[204:207], v169 offset:53248
	ds_read_b128 v[208:211], v169 offset:54272
	ds_read_b128 v[212:215], v169 offset:55296
	ds_read_b128 v[216:219], v169 offset:56320
	global_load_lds_dwordx4 v[220:221], off
	s_add_i32 m0, s2, 0x2000
	s_add_u32 s2, s14, 0x160080
	v_lshl_add_u64 v[220:221], v[222:223], 0, s[22:23]
	s_addc_u32 s3, s15, 0
	s_add_i32 s14, s64, s93
	global_load_lds_dwordx4 v[220:221], off
	v_lshl_add_u64 v[220:221], s[2:3], 0, v[128:129]
	s_mov_b32 m0, s14
	s_nop 0
	global_load_lds_dwordx4 v[220:221], off
	v_lshl_add_u64 v[220:221], s[2:3], 0, v[130:131]
	s_add_i32 m0, s14, 0x2000
	s_nop 0
	global_load_lds_dwordx4 v[220:221], off
	v_lshl_add_u64 v[220:221], v[224:225], 0, s[22:23]
	s_mov_b32 m0, s46
	s_nop 0
	global_load_lds_dwordx4 v[220:221], off
	v_lshl_add_u64 v[220:221], v[226:227], 0, s[22:23]
	s_mov_b32 m0, s47
	s_nop 0
	global_load_lds_dwordx4 v[220:221], off
	s_waitcnt vmcnt(8)
	s_waitcnt lgkmcnt(0)
	s_barrier
	s_setprio 1
	s_waitcnt lgkmcnt(0)
	v_mfma_f32_16x16x32_bf16 v[84:87], v[140:143], v[188:191], v[84:87]
	v_mfma_f32_16x16x32_bf16 v[68:71], v[148:151], v[188:191], v[68:71]
	v_mfma_f32_16x16x32_bf16 v[44:47], v[140:143], v[196:199], v[44:47]
	v_mfma_f32_16x16x32_bf16 v[40:43], v[148:151], v[196:199], v[40:43]
	v_mfma_f32_16x16x32_bf16 v[28:31], v[140:143], v[204:207], v[28:31]
	v_mfma_f32_16x16x32_bf16 v[24:27], v[148:151], v[204:207], v[24:27]
	v_mfma_f32_16x16x32_bf16 v[12:15], v[140:143], v[212:215], v[12:15]
	v_mfma_f32_16x16x32_bf16 v[8:11], v[148:151], v[212:215], v[8:11]
	v_mfma_f32_16x16x32_bf16 v[84:87], v[144:147], v[192:195], v[84:87]
	v_mfma_f32_16x16x32_bf16 v[68:71], v[152:155], v[192:195], v[68:71]
	v_mfma_f32_16x16x32_bf16 v[44:47], v[144:147], v[200:203], v[44:47]
	v_mfma_f32_16x16x32_bf16 v[40:43], v[152:155], v[200:203], v[40:43]
	v_mfma_f32_16x16x32_bf16 v[28:31], v[144:147], v[208:211], v[28:31]
	v_mfma_f32_16x16x32_bf16 v[24:27], v[152:155], v[208:211], v[24:27]
	v_mfma_f32_16x16x32_bf16 v[12:15], v[144:147], v[216:219], v[12:15]
	v_mfma_f32_16x16x32_bf16 v[8:11], v[152:155], v[216:219], v[8:11]
	v_mfma_f32_16x16x32_bf16 v[52:55], v[156:159], v[188:191], v[52:55]
	v_mfma_f32_16x16x32_bf16 v[48:51], v[178:181], v[188:191], v[48:51]
	v_mfma_f32_16x16x32_bf16 v[36:39], v[156:159], v[196:199], v[36:39]
	v_mfma_f32_16x16x32_bf16 v[32:35], v[178:181], v[196:199], v[32:35]
	v_mfma_f32_16x16x32_bf16 v[20:23], v[156:159], v[204:207], v[20:23]
	v_mfma_f32_16x16x32_bf16 v[16:19], v[178:181], v[204:207], v[16:19]
	v_mfma_f32_16x16x32_bf16 v[4:7], v[156:159], v[212:215], v[4:7]
	v_mfma_f32_16x16x32_bf16 v[0:3], v[178:181], v[212:215], v[0:3]
	v_mfma_f32_16x16x32_bf16 v[52:55], v[174:177], v[192:195], v[52:55]
	v_mfma_f32_16x16x32_bf16 v[48:51], v[184:187], v[192:195], v[48:51]
	v_mfma_f32_16x16x32_bf16 v[36:39], v[174:177], v[200:203], v[36:39]
	v_mfma_f32_16x16x32_bf16 v[32:35], v[184:187], v[200:203], v[32:35]
	v_mfma_f32_16x16x32_bf16 v[20:23], v[174:177], v[208:211], v[20:23]
	v_mfma_f32_16x16x32_bf16 v[16:19], v[184:187], v[208:211], v[16:19]
	v_mfma_f32_16x16x32_bf16 v[4:7], v[174:177], v[216:219], v[4:7]
	v_mfma_f32_16x16x32_bf16 v[0:3], v[184:187], v[216:219], v[0:3]
	s_setprio 0
	s_barrier
	s_add_i32 s62, s62, 2
	s_add_u32 s1, s1, 0x100
	s_addc_u32 s61, s61, 0
	s_cmpk_gt_u32 s62, 0x55
	s_mov_b64 s[2:3], s[12:13]
	s_cbranch_scc0 .LBB0_1051
	s_and_b64 vcc, exec, s[24:25]
	s_cbranch_vccz .LBB0_1054
	s_barrier
